# v27 plus non-temporal hint on the read-once f32 residual loads in the residual-add GEMM epilogues
# baseline (speedup 1.0000x reference)
; DEVI unsigned pk_bf16(float lo, float hi) { unsigned r; asm("v_cvt_pk_bf16_f32 %0, %1, %2" : "=v"(r) : "v"(lo), "v"(hi)); return r; }
;     DEVI void operator()(const f32x4 (&acc)[2][2][4][2], const Unit& u, int wr, int wc, int fr, int fq, const LAS float*) const {
;     ...
;         const int row0 = u.pm * BM + wr * 64 + fr, col0 = u.pn * BM + wc * 32 + 4 * fq;
;         f32x4 cur[2][2], nxt[2][2];
;         { const size_t ro = (size_t)row0 * ldc + col0;
; #pragma unroll
;           for (int bj = 0; bj < 2; ++bj)
; #pragma unroll
;               for (int n = 0; n < 2; ++n) cur[bj][n] = *(const f32x4*)(R + ro + bj * HALF + n * 16); }
; #pragma unroll
;         for (int idx = 0; idx < 8; ++idx) {
;             const int ai = idx >> 2, m = idx & 3;
;             const size_t ro = (size_t)(row0 + ai * HALF + m * 16) * ldc + col0;
;             if (idx + 1 < 8) { const int ai2 = (idx + 1) >> 2, m2 = (idx + 1) & 3; const size_t ro2 = (size_t)(row0 + ai2 * HALF + m2 * 16) * ldc + col0;
; #pragma unroll
;                 for (int bj = 0; bj < 2; ++bj)
; #pragma unroll
;                     for (int n = 0; n < 2; ++n) nxt[bj][n] = *(const f32x4*)(R + ro2 + bj * HALF + n * 16); }
;             float ss = 0.f;
; #pragma unroll
;             for (int bj = 0; bj < 2; ++bj)
; #pragma unroll
;                 for (int n = 0; n < 2; ++n) {
;                     const f32x4 hn = cur[bj][n] + acc[ai][bj][m][n] * scale;
;                     *(f32x4*)(C + ro + bj * HALF + n * 16) = hn;
;                     if (HB) { u32x2 w; w.x = pk_bf16(hn[0], hn[1]); w.y = pk_bf16(hn[2], hn[3]); *(u32x2*)(HB + ro + bj * HALF + n * 16) = w;
;                         ss += hn[0] * hn[0] + hn[1] * hn[1] + hn[2] * hn[2] + hn[3] * hn[3]; } }
;             if (HB) { ss += __shfl_xor(ss, 16); ss += __shfl_xor(ss, 32); if (fq == 0) RS[(size_t)(row0 + ai * HALF + m * 16) * 32 + u.pn * 4 + wc] = ss; }
; #pragma unroll
;             for (int bj = 0; bj < 2; ++bj)
; #pragma unroll
;                 for (int n = 0; n < 2; ++n) cur[bj][n] = nxt[bj][n];
;         }
.LBB0_389:
	v_lshl_add_u32 v188, s35, 8, v198
	v_lshl_or_b32 v182, s31, 8, v200
	v_mad_i64_i32 v[128:129], s[14:15], v188, s46, 0
	v_ashrrev_i32_e32 v183, 31, v182
	v_lshl_add_u64 v[128:129], v[128:129], 2, s[94:95]
	v_lshlrev_b64 v[130:131], 2, v[182:183]
	v_or_b32_e32 v190, 16, v188
	v_mov_b32_e32 v180, v204
	v_lshl_add_u64 v[128:129], v[128:129], 0, v[130:131]
	v_lshl_add_u64 v[186:187], s[94:95], 0, v[130:131]
	v_mad_i64_i32 v[192:193], s[16:17], v190, s46, 0
	global_load_dwordx4 v[160:163], v[128:129], off nt
	global_load_dwordx4 v[152:155], v[128:129], off offset:64 nt
	global_load_dwordx4 v[148:151], v[128:129], off offset:512 nt
	global_load_dwordx4 v[140:143], v[128:129], off offset:576 nt
	v_lshl_add_u64 v[128:129], v[192:193], 2, v[186:187]
	global_load_dwordx4 v[144:147], v[128:129], off nt
	global_load_dwordx4 v[136:139], v[128:129], off offset:64 nt
	global_load_dwordx4 v[132:135], v[128:129], off offset:512 nt
	s_nop 0
	global_load_dwordx4 v[128:131], v[128:129], off offset:576 nt
	s_lshl_b32 s14, s31, 2
	s_ashr_i32 s15, s14, 31
	s_lshl_b64 s[14:15], s[14:15], 2
	v_mov_b32_e32 v184, v180
	v_mov_b32_e32 v185, v180
	s_add_u32 s14, s4, s14
	v_mad_i64_i32 v[158:159], s[16:17], v188, s46, v[182:183]
	v_ashrrev_i32_e32 v189, 31, v188
	s_addc_u32 s15, s5, s15
	v_lshl_add_u64 v[194:195], v[158:159], 2, s[92:93]
	s_andn2_b64 vcc, exec, s[8:9]
	s_waitcnt vmcnt(0)
	v_pk_fma_f32 v[164:165], v[126:127], v[180:181], v[162:163] op_sel_hi:[1,0,1]
	v_pk_fma_f32 v[162:163], v[124:125], v[180:181], v[160:161] op_sel_hi:[1,0,1]
	v_cndmask_b32_e64 v124, 0, 1, s[8:9]
	v_cmp_ne_u32_e64 s[40:41], 1, v124
	v_pk_fma_f32 v[160:161], v[120:121], v[184:185], v[152:153]
	v_pk_fma_f32 v[156:157], v[116:117], v[184:185], v[148:149]
	v_pk_fma_f32 v[124:125], v[112:113], v[184:185], v[140:141]
	global_store_dwordx4 v[194:195], v[162:165], off nt
	s_cbranch_vccnz .LBB0_428
	v_readlane_b32 s72, v240, 54
	v_readlane_b32 s74, v240, 56
	v_readlane_b32 s75, v240, 57
	v_cvt_pk_bf16_f32 v116, v162, v163
	v_mul_f32_e32 v120, v163, v163
	v_mov_b32_e32 v181, v180
	v_lshl_add_u64 v[112:113], v[158:159], 1, s[74:75]
	v_cvt_pk_bf16_f32 v117, v164, v165
	global_store_dwordx2 v[112:113], v[116:117], off
	v_fmac_f32_e32 v120, v162, v162
	v_pk_fma_f32 v[162:163], v[122:123], v[180:181], v[154:155]
	v_cvt_pk_bf16_f32 v116, v160, v161
	global_store_dwordx4 v[194:195], v[160:163], off offset:64 nt
	v_cvt_pk_bf16_f32 v117, v162, v163
	global_store_dwordx2 v[112:113], v[116:117], off offset:32
	v_mul_f32_e32 v116, v161, v161
	v_fmac_f32_e32 v116, v160, v160
	v_fmac_f32_e32 v120, v164, v164
	v_fmac_f32_e32 v116, v162, v162
	v_fmac_f32_e32 v120, v165, v165
	v_fmac_f32_e32 v116, v163, v163
	v_add_f32_e32 v120, v120, v116
	v_pk_fma_f32 v[158:159], v[118:119], v[180:181], v[150:151]
	v_cvt_pk_bf16_f32 v116, v156, v157
	global_store_dwordx4 v[194:195], v[156:159], off offset:512 nt
	v_cvt_pk_bf16_f32 v117, v158, v159
	global_store_dwordx2 v[112:113], v[116:117], off offset:256
	v_mul_f32_e32 v116, v157, v157
	v_fmac_f32_e32 v116, v156, v156
	v_fmac_f32_e32 v116, v158, v158
	v_fmac_f32_e32 v116, v159, v159
	v_add_f32_e32 v120, v116, v120
	v_pk_fma_f32 v[126:127], v[114:115], v[180:181], v[142:143]
	v_cvt_pk_bf16_f32 v116, v124, v125
	global_store_dwordx4 v[194:195], v[124:127], off offset:576 nt
	v_cvt_pk_bf16_f32 v117, v126, v127
	global_store_dwordx2 v[112:113], v[116:117], off offset:288
	v_mul_f32_e32 v112, v125, v125
	v_and_b32_e32 v116, 64, v205
	v_fmac_f32_e32 v112, v124, v124
	v_xor_b32_e32 v113, 16, v205
	v_add_u32_e32 v116, 64, v116
	v_fmac_f32_e32 v112, v126, v126
	v_cmp_lt_i32_e32 vcc, v113, v116
	v_fmac_f32_e32 v112, v127, v127
	v_add_f32_e32 v112, v112, v120
	v_cndmask_b32_e32 v113, v205, v113, vcc
	v_lshlrev_b32_e32 v113, 2, v113
	ds_bpermute_b32 v113, v113, v112
	v_readlane_b32 s73, v240, 55
	s_waitcnt lgkmcnt(0)
	v_add_f32_e32 v112, v112, v113
	v_xor_b32_e32 v113, 32, v205
	v_cmp_lt_i32_e32 vcc, v113, v116
	s_nop 1
	v_cndmask_b32_e32 v113, v205, v113, vcc
	v_lshlrev_b32_e32 v113, 2, v113
	ds_bpermute_b32 v113, v113, v112
	s_and_saveexec_b64 s[16:17], s[36:37]
	s_cbranch_execz .LBB0_392
	s_waitcnt lgkmcnt(0)
	v_add_f32_e32 v116, v112, v113
	v_lshlrev_b64 v[112:113], 7, v[188:189]
	v_lshl_add_u64 v[112:113], s[14:15], 0, v[112:113]
	global_store_dword v[112:113], v116, off

; DEVI unsigned pk_bf16(float lo, float hi) { unsigned r; asm("v_cvt_pk_bf16_f32 %0, %1, %2" : "=v"(r) : "v"(lo), "v"(hi)); return r; }
;     DEVI void operator()(const f32x4 (&acc)[2][2][4][2], const Unit& u, int wr, int wc, int fr, int fq, const LAS float*) const {
;     ...
;         for (int idx = 0; idx < 8; ++idx) {
;             const int ai = idx >> 2, m = idx & 3;
;             const size_t ro = (size_t)(row0 + ai * HALF + m * 16) * ldc + col0;
;             if (idx + 1 < 8) { const int ai2 = (idx + 1) >> 2, m2 = (idx + 1) & 3; const size_t ro2 = (size_t)(row0 + ai2 * HALF + m2 * 16) * ldc + col0;
; #pragma unroll
;                 for (int bj = 0; bj < 2; ++bj)
; #pragma unroll
;                     for (int n = 0; n < 2; ++n) nxt[bj][n] = *(const f32x4*)(R + ro2 + bj * HALF + n * 16); }
;             float ss = 0.f;
; #pragma unroll
;             for (int bj = 0; bj < 2; ++bj)
; #pragma unroll
;                 for (int n = 0; n < 2; ++n) {
;                     const f32x4 hn = cur[bj][n] + acc[ai][bj][m][n] * scale;
;                     *(f32x4*)(C + ro + bj * HALF + n * 16) = hn;
;                     if (HB) { u32x2 w; w.x = pk_bf16(hn[0], hn[1]); w.y = pk_bf16(hn[2], hn[3]); *(u32x2*)(HB + ro + bj * HALF + n * 16) = w;
;                         ss += hn[0] * hn[0] + hn[1] * hn[1] + hn[2] * hn[2] + hn[3] * hn[3]; } }
;             if (HB) { ss += __shfl_xor(ss, 16); ss += __shfl_xor(ss, 32); if (fq == 0) RS[(size_t)(row0 + ai * HALF + m * 16) * 32 + u.pn * 4 + wc] = ss; }
; #pragma unroll
;             for (int bj = 0; bj < 2; ++bj)
; #pragma unroll
;                 for (int n = 0; n < 2; ++n) cur[bj][n] = nxt[bj][n];
;         }
.LBB0_394:
	v_or_b32_e32 v150, 32, v188
	v_mad_i64_i32 v[152:153], s[16:17], v150, s46, 0
	s_waitcnt lgkmcnt(0)
	v_lshl_add_u64 v[112:113], v[152:153], 2, v[186:187]
	global_load_dwordx4 v[124:127], v[112:113], off nt
	global_load_dwordx4 v[120:123], v[112:113], off offset:64 nt
	global_load_dwordx4 v[116:119], v[112:113], off offset:512 nt
	s_nop 0
	global_load_dwordx4 v[112:115], v[112:113], off offset:576 nt
	v_lshl_add_u64 v[142:143], v[192:193], 0, v[182:183]
	v_mov_b32_e32 v181, v180
	v_lshl_add_u64 v[154:155], v[142:143], 2, s[92:93]
	v_pk_fma_f32 v[148:149], v[110:111], v[180:181], v[146:147]
	v_pk_fma_f32 v[146:147], v[108:109], v[184:185], v[144:145]
	s_and_b64 vcc, exec, s[40:41]
	v_pk_fma_f32 v[144:145], v[104:105], v[184:185], v[136:137]
	v_pk_fma_f32 v[140:141], v[100:101], v[184:185], v[132:133]
	v_pk_fma_f32 v[108:109], v[96:97], v[184:185], v[128:129]
	global_store_dwordx4 v[154:155], v[146:149], off nt
	s_cbranch_vccnz .LBB0_429
	v_readlane_b32 s72, v240, 54
	v_readlane_b32 s74, v240, 56
	v_readlane_b32 s75, v240, 57
	v_cvt_pk_bf16_f32 v100, v146, v147
	v_mul_f32_e32 v104, v147, v147
	v_cvt_pk_bf16_f32 v101, v148, v149
	v_fmac_f32_e32 v104, v146, v146
	v_lshl_add_u64 v[96:97], v[142:143], 1, s[74:75]
	global_store_dwordx2 v[96:97], v[100:101], off
	v_pk_fma_f32 v[146:147], v[106:107], v[180:181], v[138:139]
	v_cvt_pk_bf16_f32 v100, v144, v145
	global_store_dwordx4 v[154:155], v[144:147], off offset:64 nt
	v_cvt_pk_bf16_f32 v101, v146, v147
	global_store_dwordx2 v[96:97], v[100:101], off offset:32
	v_mul_f32_e32 v100, v145, v145
	v_fmac_f32_e32 v100, v144, v144
	v_fmac_f32_e32 v104, v148, v148
	v_fmac_f32_e32 v100, v146, v146
	v_fmac_f32_e32 v104, v149, v149
	v_fmac_f32_e32 v100, v147, v147
	v_add_f32_e32 v104, v104, v100
	v_pk_fma_f32 v[142:143], v[102:103], v[180:181], v[134:135]
	v_cvt_pk_bf16_f32 v100, v140, v141
	global_store_dwordx4 v[154:155], v[140:143], off offset:512 nt
	v_cvt_pk_bf16_f32 v101, v142, v143
	global_store_dwordx2 v[96:97], v[100:101], off offset:256
	v_mul_f32_e32 v100, v141, v141
	v_fmac_f32_e32 v100, v140, v140
	v_fmac_f32_e32 v100, v142, v142
	v_fmac_f32_e32 v100, v143, v143
	v_add_f32_e32 v104, v104, v100
	v_pk_fma_f32 v[110:111], v[98:99], v[180:181], v[130:131]
	v_cvt_pk_bf16_f32 v100, v108, v109
	global_store_dwordx4 v[154:155], v[108:111], off offset:576 nt
	v_cvt_pk_bf16_f32 v101, v110, v111
	global_store_dwordx2 v[96:97], v[100:101], off offset:288
	v_mul_f32_e32 v96, v109, v109
	v_and_b32_e32 v100, 64, v205
	v_fmac_f32_e32 v96, v108, v108
	v_xor_b32_e32 v97, 16, v205
	v_add_u32_e32 v100, 64, v100
	v_fmac_f32_e32 v96, v110, v110
	v_cmp_lt_i32_e32 vcc, v97, v100
	v_fmac_f32_e32 v96, v111, v111
	v_add_f32_e32 v96, v104, v96
	v_cndmask_b32_e32 v97, v205, v97, vcc
	v_lshlrev_b32_e32 v97, 2, v97
	ds_bpermute_b32 v97, v97, v96
	v_readlane_b32 s73, v240, 55
	s_waitcnt lgkmcnt(0)
	v_add_f32_e32 v96, v96, v97
	v_xor_b32_e32 v97, 32, v205
	v_cmp_lt_i32_e32 vcc, v97, v100
	s_nop 1
	v_cndmask_b32_e32 v97, v205, v97, vcc
	v_lshlrev_b32_e32 v97, 2, v97
	ds_bpermute_b32 v97, v97, v96
	s_and_saveexec_b64 s[16:17], s[36:37]
	s_cbranch_execz .LBB0_397
	v_ashrrev_i32_e32 v191, 31, v190
	s_waitcnt lgkmcnt(0)
	v_add_f32_e32 v100, v96, v97
	v_lshlrev_b64 v[96:97], 7, v[190:191]
	v_lshl_add_u64 v[96:97], s[14:15], 0, v[96:97]
	global_store_dword v[96:97], v100, off

; DEVI unsigned pk_bf16(float lo, float hi) { unsigned r; asm("v_cvt_pk_bf16_f32 %0, %1, %2" : "=v"(r) : "v"(lo), "v"(hi)); return r; }
;     DEVI void operator()(const f32x4 (&acc)[2][2][4][2], const Unit& u, int wr, int wc, int fr, int fq, const LAS float*) const {
;     ...
;         for (int idx = 0; idx < 8; ++idx) {
;             const int ai = idx >> 2, m = idx & 3;
;             const size_t ro = (size_t)(row0 + ai * HALF + m * 16) * ldc + col0;
;             if (idx + 1 < 8) { const int ai2 = (idx + 1) >> 2, m2 = (idx + 1) & 3; const size_t ro2 = (size_t)(row0 + ai2 * HALF + m2 * 16) * ldc + col0;
; #pragma unroll
;                 for (int bj = 0; bj < 2; ++bj)
; #pragma unroll
;                     for (int n = 0; n < 2; ++n) nxt[bj][n] = *(const f32x4*)(R + ro2 + bj * HALF + n * 16); }
;             float ss = 0.f;
; #pragma unroll
;             for (int bj = 0; bj < 2; ++bj)
; #pragma unroll
;                 for (int n = 0; n < 2; ++n) {
;                     const f32x4 hn = cur[bj][n] + acc[ai][bj][m][n] * scale;
;                     *(f32x4*)(C + ro + bj * HALF + n * 16) = hn;
;                     if (HB) { u32x2 w; w.x = pk_bf16(hn[0], hn[1]); w.y = pk_bf16(hn[2], hn[3]); *(u32x2*)(HB + ro + bj * HALF + n * 16) = w;
;                         ss += hn[0] * hn[0] + hn[1] * hn[1] + hn[2] * hn[2] + hn[3] * hn[3]; } }
;             if (HB) { ss += __shfl_xor(ss, 16); ss += __shfl_xor(ss, 32); if (fq == 0) RS[(size_t)(row0 + ai * HALF + m * 16) * 32 + u.pn * 4 + wc] = ss; }
; #pragma unroll
;             for (int bj = 0; bj < 2; ++bj)
; #pragma unroll
;                 for (int n = 0; n < 2; ++n) cur[bj][n] = nxt[bj][n];
;         }
.LBB0_399:
	v_or_b32_e32 v134, 48, v188
	v_mad_i64_i32 v[136:137], s[16:17], v134, s46, 0
	s_waitcnt lgkmcnt(0)
	v_lshl_add_u64 v[96:97], v[136:137], 2, v[186:187]
	global_load_dwordx4 v[108:111], v[96:97], off nt
	global_load_dwordx4 v[104:107], v[96:97], off offset:64 nt
	global_load_dwordx4 v[100:103], v[96:97], off offset:512 nt
	s_nop 0
	global_load_dwordx4 v[96:99], v[96:97], off offset:576 nt
	v_lshl_add_u64 v[140:141], v[152:153], 0, v[182:183]
	v_mov_b32_e32 v181, v180
	v_lshl_add_u64 v[138:139], v[140:141], 2, s[92:93]
	s_waitcnt vmcnt(8)
	v_pk_fma_f32 v[132:133], v[94:95], v[180:181], v[126:127]
	v_pk_fma_f32 v[130:131], v[92:93], v[184:185], v[124:125]
	s_and_b64 vcc, exec, s[40:41]
	s_waitcnt vmcnt(7)
	v_pk_fma_f32 v[128:129], v[88:89], v[184:185], v[120:121]
	s_waitcnt vmcnt(6)
	v_pk_fma_f32 v[124:125], v[84:85], v[184:185], v[116:117]
	s_waitcnt vmcnt(5)
	v_pk_fma_f32 v[92:93], v[80:81], v[184:185], v[112:113]
	global_store_dwordx4 v[138:139], v[130:133], off nt
	s_cbranch_vccnz .LBB0_430
	v_readlane_b32 s72, v240, 54
	v_readlane_b32 s74, v240, 56
	v_readlane_b32 s75, v240, 57
	v_cvt_pk_bf16_f32 v84, v130, v131
	v_mul_f32_e32 v88, v131, v131
	v_cvt_pk_bf16_f32 v85, v132, v133
	v_fmac_f32_e32 v88, v130, v130
	v_lshl_add_u64 v[80:81], v[140:141], 1, s[74:75]
	global_store_dwordx2 v[80:81], v[84:85], off
	v_pk_fma_f32 v[130:131], v[90:91], v[180:181], v[122:123]
	v_cvt_pk_bf16_f32 v84, v128, v129
	global_store_dwordx4 v[138:139], v[128:131], off offset:64 nt
	v_cvt_pk_bf16_f32 v85, v130, v131
	global_store_dwordx2 v[80:81], v[84:85], off offset:32
	v_mul_f32_e32 v84, v129, v129
	v_fmac_f32_e32 v84, v128, v128
	v_fmac_f32_e32 v88, v132, v132
	v_fmac_f32_e32 v84, v130, v130
	v_fmac_f32_e32 v88, v133, v133
	v_fmac_f32_e32 v84, v131, v131
	v_add_f32_e32 v88, v88, v84
	v_pk_fma_f32 v[126:127], v[86:87], v[180:181], v[118:119]
	v_cvt_pk_bf16_f32 v84, v124, v125
	global_store_dwordx4 v[138:139], v[124:127], off offset:512 nt
	v_cvt_pk_bf16_f32 v85, v126, v127
	global_store_dwordx2 v[80:81], v[84:85], off offset:256
	v_mul_f32_e32 v84, v125, v125
	v_fmac_f32_e32 v84, v124, v124
	v_fmac_f32_e32 v84, v126, v126
	v_fmac_f32_e32 v84, v127, v127
	v_add_f32_e32 v88, v88, v84
	v_pk_fma_f32 v[94:95], v[82:83], v[180:181], v[114:115]
	v_cvt_pk_bf16_f32 v84, v92, v93
	global_store_dwordx4 v[138:139], v[92:95], off offset:576 nt
	v_cvt_pk_bf16_f32 v85, v94, v95
	global_store_dwordx2 v[80:81], v[84:85], off offset:288
	v_mul_f32_e32 v80, v93, v93
	v_and_b32_e32 v84, 64, v205
	v_fmac_f32_e32 v80, v92, v92
	v_xor_b32_e32 v81, 16, v205
	v_add_u32_e32 v84, 64, v84
	v_fmac_f32_e32 v80, v94, v94
	v_cmp_lt_i32_e32 vcc, v81, v84
	v_fmac_f32_e32 v80, v95, v95
	v_add_f32_e32 v80, v88, v80
	v_cndmask_b32_e32 v81, v205, v81, vcc
	v_lshlrev_b32_e32 v81, 2, v81
	ds_bpermute_b32 v81, v81, v80
	v_readlane_b32 s73, v240, 55
	s_waitcnt lgkmcnt(0)
	v_add_f32_e32 v80, v80, v81
	v_xor_b32_e32 v81, 32, v205
	v_cmp_lt_i32_e32 vcc, v81, v84
	s_nop 1
	v_cndmask_b32_e32 v81, v205, v81, vcc
	v_lshlrev_b32_e32 v81, 2, v81
	ds_bpermute_b32 v81, v81, v80
	s_and_saveexec_b64 s[16:17], s[36:37]
	s_cbranch_execz .LBB0_402
	v_ashrrev_i32_e32 v151, 31, v150
	s_waitcnt lgkmcnt(0)
	v_add_f32_e32 v84, v80, v81
	v_lshlrev_b64 v[80:81], 7, v[150:151]
	v_lshl_add_u64 v[80:81], s[14:15], 0, v[80:81]
	global_store_dword v[80:81], v84, off

; DEVI unsigned pk_bf16(float lo, float hi) { unsigned r; asm("v_cvt_pk_bf16_f32 %0, %1, %2" : "=v"(r) : "v"(lo), "v"(hi)); return r; }
;     DEVI void operator()(const f32x4 (&acc)[2][2][4][2], const Unit& u, int wr, int wc, int fr, int fq, const LAS float*) const {
;     ...
;         for (int idx = 0; idx < 8; ++idx) {
;             const int ai = idx >> 2, m = idx & 3;
;             const size_t ro = (size_t)(row0 + ai * HALF + m * 16) * ldc + col0;
;             if (idx + 1 < 8) { const int ai2 = (idx + 1) >> 2, m2 = (idx + 1) & 3; const size_t ro2 = (size_t)(row0 + ai2 * HALF + m2 * 16) * ldc + col0;
; #pragma unroll
;                 for (int bj = 0; bj < 2; ++bj)
; #pragma unroll
;                     for (int n = 0; n < 2; ++n) nxt[bj][n] = *(const f32x4*)(R + ro2 + bj * HALF + n * 16); }
;             float ss = 0.f;
; #pragma unroll
;             for (int bj = 0; bj < 2; ++bj)
; #pragma unroll
;                 for (int n = 0; n < 2; ++n) {
;                     const f32x4 hn = cur[bj][n] + acc[ai][bj][m][n] * scale;
;                     *(f32x4*)(C + ro + bj * HALF + n * 16) = hn;
;                     if (HB) { u32x2 w; w.x = pk_bf16(hn[0], hn[1]); w.y = pk_bf16(hn[2], hn[3]); *(u32x2*)(HB + ro + bj * HALF + n * 16) = w;
;                         ss += hn[0] * hn[0] + hn[1] * hn[1] + hn[2] * hn[2] + hn[3] * hn[3]; } }
;             if (HB) { ss += __shfl_xor(ss, 16); ss += __shfl_xor(ss, 32); if (fq == 0) RS[(size_t)(row0 + ai * HALF + m * 16) * 32 + u.pn * 4 + wc] = ss; }
; #pragma unroll
;             for (int bj = 0; bj < 2; ++bj)
; #pragma unroll
;                 for (int n = 0; n < 2; ++n) cur[bj][n] = nxt[bj][n];
;         }
.LBB0_404:
	v_add_u32_e32 v118, 0x80, v188
	v_mad_i64_i32 v[120:121], s[16:17], v118, s46, 0
	s_waitcnt lgkmcnt(0)
	v_lshl_add_u64 v[80:81], v[120:121], 2, v[186:187]
	global_load_dwordx4 v[92:95], v[80:81], off nt
	global_load_dwordx4 v[88:91], v[80:81], off offset:64 nt
	global_load_dwordx4 v[84:87], v[80:81], off offset:512 nt
	s_nop 0
	global_load_dwordx4 v[80:83], v[80:81], off offset:576 nt
	v_lshl_add_u64 v[124:125], v[136:137], 0, v[182:183]
	v_mov_b32_e32 v181, v180
	v_lshl_add_u64 v[122:123], v[124:125], 2, s[92:93]
	s_waitcnt vmcnt(8)
	v_pk_fma_f32 v[116:117], v[78:79], v[180:181], v[110:111]
	v_pk_fma_f32 v[114:115], v[76:77], v[184:185], v[108:109]
	s_and_b64 vcc, exec, s[40:41]
	s_waitcnt vmcnt(7)
	v_pk_fma_f32 v[112:113], v[72:73], v[184:185], v[104:105]
	s_waitcnt vmcnt(6)
	v_pk_fma_f32 v[108:109], v[68:69], v[184:185], v[100:101]
	s_waitcnt vmcnt(5)
	v_pk_fma_f32 v[76:77], v[64:65], v[184:185], v[96:97]
	global_store_dwordx4 v[122:123], v[114:117], off nt
	s_cbranch_vccnz .LBB0_431
	v_readlane_b32 s72, v240, 54
	v_readlane_b32 s74, v240, 56
	v_readlane_b32 s75, v240, 57
	v_cvt_pk_bf16_f32 v68, v114, v115
	v_mul_f32_e32 v72, v115, v115
	v_cvt_pk_bf16_f32 v69, v116, v117
	v_fmac_f32_e32 v72, v114, v114
	v_lshl_add_u64 v[64:65], v[124:125], 1, s[74:75]
	global_store_dwordx2 v[64:65], v[68:69], off
	v_pk_fma_f32 v[114:115], v[74:75], v[180:181], v[106:107]
	v_cvt_pk_bf16_f32 v68, v112, v113
	global_store_dwordx4 v[122:123], v[112:115], off offset:64 nt
	v_cvt_pk_bf16_f32 v69, v114, v115
	global_store_dwordx2 v[64:65], v[68:69], off offset:32
	v_mul_f32_e32 v68, v113, v113
	v_fmac_f32_e32 v68, v112, v112
	v_fmac_f32_e32 v72, v116, v116
	v_fmac_f32_e32 v68, v114, v114
	v_fmac_f32_e32 v72, v117, v117
	v_fmac_f32_e32 v68, v115, v115
	v_add_f32_e32 v72, v72, v68
	v_pk_fma_f32 v[110:111], v[70:71], v[180:181], v[102:103]
	v_cvt_pk_bf16_f32 v68, v108, v109
	global_store_dwordx4 v[122:123], v[108:111], off offset:512 nt
	v_cvt_pk_bf16_f32 v69, v110, v111
	global_store_dwordx2 v[64:65], v[68:69], off offset:256
	v_mul_f32_e32 v68, v109, v109
	v_fmac_f32_e32 v68, v108, v108
	v_fmac_f32_e32 v68, v110, v110
	v_fmac_f32_e32 v68, v111, v111
	v_add_f32_e32 v72, v72, v68
	v_pk_fma_f32 v[78:79], v[66:67], v[180:181], v[98:99]
	v_cvt_pk_bf16_f32 v68, v76, v77
	global_store_dwordx4 v[122:123], v[76:79], off offset:576 nt
	v_cvt_pk_bf16_f32 v69, v78, v79
	global_store_dwordx2 v[64:65], v[68:69], off offset:288
	v_mul_f32_e32 v64, v77, v77
	v_and_b32_e32 v68, 64, v205
	v_fmac_f32_e32 v64, v76, v76
	v_xor_b32_e32 v65, 16, v205
	v_add_u32_e32 v68, 64, v68
	v_fmac_f32_e32 v64, v78, v78
	v_cmp_lt_i32_e32 vcc, v65, v68
	v_fmac_f32_e32 v64, v79, v79
	v_add_f32_e32 v64, v72, v64
	v_cndmask_b32_e32 v65, v205, v65, vcc
	v_lshlrev_b32_e32 v65, 2, v65
	ds_bpermute_b32 v65, v65, v64
	v_readlane_b32 s73, v240, 55
	s_waitcnt lgkmcnt(0)
	v_add_f32_e32 v64, v64, v65
	v_xor_b32_e32 v65, 32, v205
	v_cmp_lt_i32_e32 vcc, v65, v68
	s_nop 1
	v_cndmask_b32_e32 v65, v205, v65, vcc
	v_lshlrev_b32_e32 v65, 2, v65
	ds_bpermute_b32 v65, v65, v64
	s_and_saveexec_b64 s[16:17], s[36:37]
	s_cbranch_execz .LBB0_407
	v_ashrrev_i32_e32 v135, 31, v134
	s_waitcnt lgkmcnt(0)
	v_add_f32_e32 v68, v64, v65
	v_lshlrev_b64 v[64:65], 7, v[134:135]
	v_lshl_add_u64 v[64:65], s[14:15], 0, v[64:65]
	global_store_dword v[64:65], v68, off

; DEVI unsigned pk_bf16(float lo, float hi) { unsigned r; asm("v_cvt_pk_bf16_f32 %0, %1, %2" : "=v"(r) : "v"(lo), "v"(hi)); return r; }
;     DEVI void operator()(const f32x4 (&acc)[2][2][4][2], const Unit& u, int wr, int wc, int fr, int fq, const LAS float*) const {
;     ...
;             const int ai = idx >> 2, m = idx & 3;
;             const size_t ro = (size_t)(row0 + ai * HALF + m * 16) * ldc + col0;
;             if (idx + 1 < 8) { const int ai2 = (idx + 1) >> 2, m2 = (idx + 1) & 3; const size_t ro2 = (size_t)(row0 + ai2 * HALF + m2 * 16) * ldc + col0;
; #pragma unroll
;                 for (int bj = 0; bj < 2; ++bj)
; #pragma unroll
;                     for (int n = 0; n < 2; ++n) nxt[bj][n] = *(const f32x4*)(R + ro2 + bj * HALF + n * 16); }
;             float ss = 0.f;
; #pragma unroll
;             for (int bj = 0; bj < 2; ++bj)
; #pragma unroll
;                 for (int n = 0; n < 2; ++n) {
;                     const f32x4 hn = cur[bj][n] + acc[ai][bj][m][n] * scale;
;                     *(f32x4*)(C + ro + bj * HALF + n * 16) = hn;
;                     if (HB) { u32x2 w; w.x = pk_bf16(hn[0], hn[1]); w.y = pk_bf16(hn[2], hn[3]); *(u32x2*)(HB + ro + bj * HALF + n * 16) = w;
;                         ss += hn[0] * hn[0] + hn[1] * hn[1] + hn[2] * hn[2] + hn[3] * hn[3]; } }
;             if (HB) { ss += __shfl_xor(ss, 16); ss += __shfl_xor(ss, 32); if (fq == 0) RS[(size_t)(row0 + ai * HALF + m * 16) * 32 + u.pn * 4 + wc] = ss; }
.LBB0_409:
	v_or_b32_e32 v102, 16, v118
	v_mad_i64_i32 v[104:105], s[16:17], v102, s46, 0
	s_waitcnt lgkmcnt(0)
	v_lshl_add_u64 v[64:65], v[104:105], 2, v[186:187]
	global_load_dwordx4 v[76:79], v[64:65], off nt
	global_load_dwordx4 v[72:75], v[64:65], off offset:64 nt
	global_load_dwordx4 v[68:71], v[64:65], off offset:512 nt
	s_nop 0
	global_load_dwordx4 v[64:67], v[64:65], off offset:576 nt
	v_lshl_add_u64 v[108:109], v[120:121], 0, v[182:183]
	v_mov_b32_e32 v181, v180
	v_ashrrev_i32_e32 v119, 31, v118
	v_lshl_add_u64 v[106:107], v[108:109], 2, s[92:93]
	s_waitcnt vmcnt(8)
	v_pk_fma_f32 v[100:101], v[62:63], v[180:181], v[94:95]
	v_pk_fma_f32 v[98:99], v[60:61], v[184:185], v[92:93]
	s_and_b64 vcc, exec, s[40:41]
	s_waitcnt vmcnt(7)
	v_pk_fma_f32 v[96:97], v[56:57], v[184:185], v[88:89]
	s_waitcnt vmcnt(6)
	v_pk_fma_f32 v[92:93], v[52:53], v[184:185], v[84:85]
	s_waitcnt vmcnt(5)
	v_pk_fma_f32 v[60:61], v[48:49], v[184:185], v[80:81]
	global_store_dwordx4 v[106:107], v[98:101], off nt
	s_cbranch_vccnz .LBB0_432
	v_readlane_b32 s72, v240, 54
	v_readlane_b32 s74, v240, 56
	v_readlane_b32 s75, v240, 57
	v_cvt_pk_bf16_f32 v52, v98, v99
	v_mul_f32_e32 v56, v99, v99
	v_cvt_pk_bf16_f32 v53, v100, v101
	v_fmac_f32_e32 v56, v98, v98
	v_lshl_add_u64 v[48:49], v[108:109], 1, s[74:75]
	global_store_dwordx2 v[48:49], v[52:53], off
	v_pk_fma_f32 v[98:99], v[58:59], v[180:181], v[90:91]
	v_cvt_pk_bf16_f32 v52, v96, v97
	global_store_dwordx4 v[106:107], v[96:99], off offset:64 nt
	v_cvt_pk_bf16_f32 v53, v98, v99
	global_store_dwordx2 v[48:49], v[52:53], off offset:32
	v_mul_f32_e32 v52, v97, v97
	v_fmac_f32_e32 v52, v96, v96
	v_fmac_f32_e32 v56, v100, v100
	v_fmac_f32_e32 v52, v98, v98
	v_fmac_f32_e32 v56, v101, v101
	v_fmac_f32_e32 v52, v99, v99
	v_add_f32_e32 v56, v56, v52
	v_pk_fma_f32 v[94:95], v[54:55], v[180:181], v[86:87]
	v_cvt_pk_bf16_f32 v52, v92, v93
	global_store_dwordx4 v[106:107], v[92:95], off offset:512 nt
	v_cvt_pk_bf16_f32 v53, v94, v95
	global_store_dwordx2 v[48:49], v[52:53], off offset:256
	v_mul_f32_e32 v52, v93, v93
	v_fmac_f32_e32 v52, v92, v92
	v_fmac_f32_e32 v52, v94, v94
	v_fmac_f32_e32 v52, v95, v95
	v_add_f32_e32 v56, v56, v52
	v_pk_fma_f32 v[62:63], v[50:51], v[180:181], v[82:83]
	v_cvt_pk_bf16_f32 v52, v60, v61
	global_store_dwordx4 v[106:107], v[60:63], off offset:576 nt
	v_cvt_pk_bf16_f32 v53, v62, v63
	global_store_dwordx2 v[48:49], v[52:53], off offset:288
	v_mul_f32_e32 v48, v61, v61
	v_and_b32_e32 v52, 64, v205
	v_fmac_f32_e32 v48, v60, v60
	v_xor_b32_e32 v49, 16, v205
	v_add_u32_e32 v52, 64, v52
	v_fmac_f32_e32 v48, v62, v62
	v_cmp_lt_i32_e32 vcc, v49, v52
	v_fmac_f32_e32 v48, v63, v63
	v_add_f32_e32 v48, v56, v48
	v_cndmask_b32_e32 v49, v205, v49, vcc
	v_lshlrev_b32_e32 v49, 2, v49
	ds_bpermute_b32 v49, v49, v48
	v_readlane_b32 s73, v240, 55
	s_waitcnt lgkmcnt(0)
	v_add_f32_e32 v48, v48, v49
	v_xor_b32_e32 v49, 32, v205
	v_cmp_lt_i32_e32 vcc, v49, v52
	s_nop 1
	v_cndmask_b32_e32 v49, v205, v49, vcc
	v_lshlrev_b32_e32 v49, 2, v49
	ds_bpermute_b32 v49, v49, v48
	s_and_saveexec_b64 s[16:17], s[36:37]
	s_cbranch_execz .LBB0_412
	s_waitcnt lgkmcnt(0)
	v_add_f32_e32 v52, v48, v49
	v_lshlrev_b64 v[48:49], 7, v[118:119]
	v_lshl_add_u64 v[48:49], s[14:15], 0, v[48:49]
	global_store_dword v[48:49], v52, off

; DEVI unsigned pk_bf16(float lo, float hi) { unsigned r; asm("v_cvt_pk_bf16_f32 %0, %1, %2" : "=v"(r) : "v"(lo), "v"(hi)); return r; }
;     DEVI void operator()(const f32x4 (&acc)[2][2][4][2], const Unit& u, int wr, int wc, int fr, int fq, const LAS float*) const {
;     ...
;             const int ai = idx >> 2, m = idx & 3;
;             const size_t ro = (size_t)(row0 + ai * HALF + m * 16) * ldc + col0;
;             if (idx + 1 < 8) { const int ai2 = (idx + 1) >> 2, m2 = (idx + 1) & 3; const size_t ro2 = (size_t)(row0 + ai2 * HALF + m2 * 16) * ldc + col0;
; #pragma unroll
;                 for (int bj = 0; bj < 2; ++bj)
; #pragma unroll
;                     for (int n = 0; n < 2; ++n) nxt[bj][n] = *(const f32x4*)(R + ro2 + bj * HALF + n * 16); }
;             float ss = 0.f;
; #pragma unroll
;             for (int bj = 0; bj < 2; ++bj)
; #pragma unroll
;                 for (int n = 0; n < 2; ++n) {
;                     const f32x4 hn = cur[bj][n] + acc[ai][bj][m][n] * scale;
;                     *(f32x4*)(C + ro + bj * HALF + n * 16) = hn;
;                     if (HB) { u32x2 w; w.x = pk_bf16(hn[0], hn[1]); w.y = pk_bf16(hn[2], hn[3]); *(u32x2*)(HB + ro + bj * HALF + n * 16) = w;
;                         ss += hn[0] * hn[0] + hn[1] * hn[1] + hn[2] * hn[2] + hn[3] * hn[3]; } }
;             if (HB) { ss += __shfl_xor(ss, 16); ss += __shfl_xor(ss, 32); if (fq == 0) RS[(size_t)(row0 + ai * HALF + m * 16) * 32 + u.pn * 4 + wc] = ss; }
.LBB0_414:
	v_or_b32_e32 v86, 32, v118
	v_mad_i64_i32 v[88:89], s[16:17], v86, s46, 0
	s_waitcnt lgkmcnt(0)
	v_lshl_add_u64 v[48:49], v[88:89], 2, v[186:187]
	global_load_dwordx4 v[60:63], v[48:49], off nt
	global_load_dwordx4 v[56:59], v[48:49], off offset:64 nt
	global_load_dwordx4 v[52:55], v[48:49], off offset:512 nt
	s_nop 0
	global_load_dwordx4 v[48:51], v[48:49], off offset:576 nt
	v_lshl_add_u64 v[92:93], v[104:105], 0, v[182:183]
	v_mov_b32_e32 v181, v180
	v_lshl_add_u64 v[90:91], v[92:93], 2, s[92:93]
	s_waitcnt vmcnt(8)
	v_pk_fma_f32 v[84:85], v[46:47], v[180:181], v[78:79]
	v_pk_fma_f32 v[82:83], v[44:45], v[184:185], v[76:77]
	s_and_b64 vcc, exec, s[40:41]
	s_waitcnt vmcnt(7)
	v_pk_fma_f32 v[80:81], v[40:41], v[184:185], v[72:73]
	s_waitcnt vmcnt(6)
	v_pk_fma_f32 v[76:77], v[36:37], v[184:185], v[68:69]
	s_waitcnt vmcnt(5)
	v_pk_fma_f32 v[44:45], v[32:33], v[184:185], v[64:65]
	global_store_dwordx4 v[90:91], v[82:85], off nt
	s_cbranch_vccnz .LBB0_433
	v_readlane_b32 s72, v240, 54
	v_readlane_b32 s74, v240, 56
	v_readlane_b32 s75, v240, 57
	v_cvt_pk_bf16_f32 v36, v82, v83
	v_mul_f32_e32 v40, v83, v83
	v_cvt_pk_bf16_f32 v37, v84, v85
	v_fmac_f32_e32 v40, v82, v82
	v_lshl_add_u64 v[32:33], v[92:93], 1, s[74:75]
	global_store_dwordx2 v[32:33], v[36:37], off
	v_pk_fma_f32 v[82:83], v[42:43], v[180:181], v[74:75]
	v_cvt_pk_bf16_f32 v36, v80, v81
	global_store_dwordx4 v[90:91], v[80:83], off offset:64 nt
	v_cvt_pk_bf16_f32 v37, v82, v83
	global_store_dwordx2 v[32:33], v[36:37], off offset:32
	v_mul_f32_e32 v36, v81, v81
	v_fmac_f32_e32 v36, v80, v80
	v_fmac_f32_e32 v40, v84, v84
	v_fmac_f32_e32 v36, v82, v82
	v_fmac_f32_e32 v40, v85, v85
	v_fmac_f32_e32 v36, v83, v83
	v_add_f32_e32 v40, v40, v36
	v_pk_fma_f32 v[78:79], v[38:39], v[180:181], v[70:71]
	v_cvt_pk_bf16_f32 v36, v76, v77
	global_store_dwordx4 v[90:91], v[76:79], off offset:512 nt
	v_cvt_pk_bf16_f32 v37, v78, v79
	global_store_dwordx2 v[32:33], v[36:37], off offset:256
	v_mul_f32_e32 v36, v77, v77
	v_fmac_f32_e32 v36, v76, v76
	v_fmac_f32_e32 v36, v78, v78
	v_fmac_f32_e32 v36, v79, v79
	v_add_f32_e32 v40, v40, v36
	v_pk_fma_f32 v[46:47], v[34:35], v[180:181], v[66:67]
	v_cvt_pk_bf16_f32 v36, v44, v45
	global_store_dwordx4 v[90:91], v[44:47], off offset:576 nt
	v_cvt_pk_bf16_f32 v37, v46, v47
	global_store_dwordx2 v[32:33], v[36:37], off offset:288
	v_mul_f32_e32 v32, v45, v45
	v_and_b32_e32 v36, 64, v205
	v_fmac_f32_e32 v32, v44, v44
	v_xor_b32_e32 v33, 16, v205
	v_add_u32_e32 v36, 64, v36
	v_fmac_f32_e32 v32, v46, v46
	v_cmp_lt_i32_e32 vcc, v33, v36
	v_fmac_f32_e32 v32, v47, v47
	v_add_f32_e32 v32, v40, v32
	v_cndmask_b32_e32 v33, v205, v33, vcc
	v_lshlrev_b32_e32 v33, 2, v33
	ds_bpermute_b32 v33, v33, v32
	v_readlane_b32 s73, v240, 55
	s_waitcnt lgkmcnt(0)
	v_add_f32_e32 v32, v32, v33
	v_xor_b32_e32 v33, 32, v205
	v_cmp_lt_i32_e32 vcc, v33, v36
	s_nop 1
	v_cndmask_b32_e32 v33, v205, v33, vcc
	v_lshlrev_b32_e32 v33, 2, v33
	ds_bpermute_b32 v33, v33, v32
	s_and_saveexec_b64 s[16:17], s[36:37]
	s_cbranch_execz .LBB0_417
	v_ashrrev_i32_e32 v103, 31, v102
	s_waitcnt lgkmcnt(0)
	v_add_f32_e32 v36, v32, v33
	v_lshlrev_b64 v[32:33], 7, v[102:103]
	v_lshl_add_u64 v[32:33], s[14:15], 0, v[32:33]
	global_store_dword v[32:33], v36, off

; DEVI unsigned pk_bf16(float lo, float hi) { unsigned r; asm("v_cvt_pk_bf16_f32 %0, %1, %2" : "=v"(r) : "v"(lo), "v"(hi)); return r; }
;     DEVI void operator()(const f32x4 (&acc)[2][2][4][2], const Unit& u, int wr, int wc, int fr, int fq, const LAS float*) const {
;     ...
;             const int ai = idx >> 2, m = idx & 3;
;             const size_t ro = (size_t)(row0 + ai * HALF + m * 16) * ldc + col0;
;             if (idx + 1 < 8) { const int ai2 = (idx + 1) >> 2, m2 = (idx + 1) & 3; const size_t ro2 = (size_t)(row0 + ai2 * HALF + m2 * 16) * ldc + col0;
; #pragma unroll
;                 for (int bj = 0; bj < 2; ++bj)
; #pragma unroll
;                     for (int n = 0; n < 2; ++n) nxt[bj][n] = *(const f32x4*)(R + ro2 + bj * HALF + n * 16); }
;             float ss = 0.f;
; #pragma unroll
;             for (int bj = 0; bj < 2; ++bj)
; #pragma unroll
;                 for (int n = 0; n < 2; ++n) {
;                     const f32x4 hn = cur[bj][n] + acc[ai][bj][m][n] * scale;
;                     *(f32x4*)(C + ro + bj * HALF + n * 16) = hn;
;                     if (HB) { u32x2 w; w.x = pk_bf16(hn[0], hn[1]); w.y = pk_bf16(hn[2], hn[3]); *(u32x2*)(HB + ro + bj * HALF + n * 16) = w;
;                         ss += hn[0] * hn[0] + hn[1] * hn[1] + hn[2] * hn[2] + hn[3] * hn[3]; } }
;             if (HB) { ss += __shfl_xor(ss, 16); ss += __shfl_xor(ss, 32); if (fq == 0) RS[(size_t)(row0 + ai * HALF + m * 16) * 32 + u.pn * 4 + wc] = ss; }
.LBB0_419:
	v_or_b32_e32 v70, 48, v118
	v_mad_i64_i32 v[72:73], s[16:17], v70, s46, 0
	s_waitcnt lgkmcnt(0)
	v_lshl_add_u64 v[32:33], v[72:73], 2, v[186:187]
	global_load_dwordx4 v[44:47], v[32:33], off nt
	global_load_dwordx4 v[40:43], v[32:33], off offset:64 nt
	global_load_dwordx4 v[36:39], v[32:33], off offset:512 nt
	s_nop 0
	global_load_dwordx4 v[32:35], v[32:33], off offset:576 nt
	v_lshl_add_u64 v[76:77], v[88:89], 0, v[182:183]
	v_mov_b32_e32 v181, v180
	v_lshl_add_u64 v[74:75], v[76:77], 2, s[92:93]
	s_waitcnt vmcnt(8)
	v_pk_fma_f32 v[68:69], v[30:31], v[180:181], v[62:63]
	v_pk_fma_f32 v[66:67], v[28:29], v[184:185], v[60:61]
	s_and_b64 vcc, exec, s[40:41]
	s_waitcnt vmcnt(7)
	v_pk_fma_f32 v[64:65], v[24:25], v[184:185], v[56:57]
	s_waitcnt vmcnt(6)
	v_pk_fma_f32 v[60:61], v[20:21], v[184:185], v[52:53]
	s_waitcnt vmcnt(5)
	v_pk_fma_f32 v[28:29], v[16:17], v[184:185], v[48:49]
	global_store_dwordx4 v[74:75], v[66:69], off nt
	s_cbranch_vccnz .LBB0_434
	v_readlane_b32 s72, v240, 54
	v_readlane_b32 s74, v240, 56
	v_readlane_b32 s75, v240, 57
	v_cvt_pk_bf16_f32 v20, v66, v67
	v_mul_f32_e32 v24, v67, v67
	v_cvt_pk_bf16_f32 v21, v68, v69
	v_fmac_f32_e32 v24, v66, v66
	v_lshl_add_u64 v[16:17], v[76:77], 1, s[74:75]
	global_store_dwordx2 v[16:17], v[20:21], off
	v_pk_fma_f32 v[66:67], v[26:27], v[180:181], v[58:59]
	v_cvt_pk_bf16_f32 v20, v64, v65
	global_store_dwordx4 v[74:75], v[64:67], off offset:64 nt
	v_cvt_pk_bf16_f32 v21, v66, v67
	global_store_dwordx2 v[16:17], v[20:21], off offset:32
	v_mul_f32_e32 v20, v65, v65
	v_fmac_f32_e32 v20, v64, v64
	v_fmac_f32_e32 v24, v68, v68
	v_fmac_f32_e32 v20, v66, v66
	v_fmac_f32_e32 v24, v69, v69
	v_fmac_f32_e32 v20, v67, v67
	v_add_f32_e32 v24, v24, v20
	v_pk_fma_f32 v[62:63], v[22:23], v[180:181], v[54:55]
	v_cvt_pk_bf16_f32 v20, v60, v61
	global_store_dwordx4 v[74:75], v[60:63], off offset:512 nt
	v_cvt_pk_bf16_f32 v21, v62, v63
	global_store_dwordx2 v[16:17], v[20:21], off offset:256
	v_mul_f32_e32 v20, v61, v61
	v_fmac_f32_e32 v20, v60, v60
	v_fmac_f32_e32 v20, v62, v62
	v_fmac_f32_e32 v20, v63, v63
	v_add_f32_e32 v24, v24, v20
	v_pk_fma_f32 v[30:31], v[18:19], v[180:181], v[50:51]
	v_cvt_pk_bf16_f32 v20, v28, v29
	global_store_dwordx4 v[74:75], v[28:31], off offset:576 nt
	v_cvt_pk_bf16_f32 v21, v30, v31
	global_store_dwordx2 v[16:17], v[20:21], off offset:288
	v_mul_f32_e32 v16, v29, v29
	v_and_b32_e32 v20, 64, v205
	v_fmac_f32_e32 v16, v28, v28
	v_xor_b32_e32 v17, 16, v205
	v_add_u32_e32 v20, 64, v20
	v_fmac_f32_e32 v16, v30, v30
	v_cmp_lt_i32_e32 vcc, v17, v20
	v_fmac_f32_e32 v16, v31, v31
	v_add_f32_e32 v16, v24, v16
	v_cndmask_b32_e32 v17, v205, v17, vcc
	v_lshlrev_b32_e32 v17, 2, v17
	ds_bpermute_b32 v17, v17, v16
	v_readlane_b32 s73, v240, 55
	s_waitcnt lgkmcnt(0)
	v_add_f32_e32 v16, v16, v17
	v_xor_b32_e32 v17, 32, v205
	v_cmp_lt_i32_e32 vcc, v17, v20
	s_nop 1
	v_cndmask_b32_e32 v17, v205, v17, vcc
	v_lshlrev_b32_e32 v17, 2, v17
	ds_bpermute_b32 v17, v17, v16
	s_and_saveexec_b64 s[16:17], s[36:37]
	s_cbranch_execz .LBB0_422
	v_ashrrev_i32_e32 v87, 31, v86
	s_waitcnt lgkmcnt(0)
	v_add_f32_e32 v20, v16, v17
	v_lshlrev_b64 v[16:17], 7, v[86:87]
	v_lshl_add_u64 v[16:17], s[14:15], 0, v[16:17]
	global_store_dword v[16:17], v20, off

; DEVI unsigned pk_bf16(float lo, float hi) { unsigned r; asm("v_cvt_pk_bf16_f32 %0, %1, %2" : "=v"(r) : "v"(lo), "v"(hi)); return r; }
;     DEVI void operator()(const f32x4 (&acc)[2][2][4][2], const Unit& u, int wr, int wc, int fr, int fq, const LAS float*) const {
;     ...
;         const int row0 = u.pm * BM + wr * 64 + fr, col0 = u.pn * BM + wc * 32 + 4 * fq;
;         f32x4 cur[2][2], nxt[2][2];
;         { const size_t ro = (size_t)row0 * ldc + col0;
; #pragma unroll
;           for (int bj = 0; bj < 2; ++bj)
; #pragma unroll
;               for (int n = 0; n < 2; ++n) cur[bj][n] = *(const f32x4*)(R + ro + bj * HALF + n * 16); }
; #pragma unroll
;         for (int idx = 0; idx < 8; ++idx) {
;             const int ai = idx >> 2, m = idx & 3;
;             const size_t ro = (size_t)(row0 + ai * HALF + m * 16) * ldc + col0;
;             if (idx + 1 < 8) { const int ai2 = (idx + 1) >> 2, m2 = (idx + 1) & 3; const size_t ro2 = (size_t)(row0 + ai2 * HALF + m2 * 16) * ldc + col0;
; #pragma unroll
;                 for (int bj = 0; bj < 2; ++bj)
; #pragma unroll
;                     for (int n = 0; n < 2; ++n) nxt[bj][n] = *(const f32x4*)(R + ro2 + bj * HALF + n * 16); }
;             float ss = 0.f;
; #pragma unroll
;             for (int bj = 0; bj < 2; ++bj)
; #pragma unroll
;                 for (int n = 0; n < 2; ++n) {
;                     const f32x4 hn = cur[bj][n] + acc[ai][bj][m][n] * scale;
;                     *(f32x4*)(C + ro + bj * HALF + n * 16) = hn;
;                     if (HB) { u32x2 w; w.x = pk_bf16(hn[0], hn[1]); w.y = pk_bf16(hn[2], hn[3]); *(u32x2*)(HB + ro + bj * HALF + n * 16) = w;
;                         ss += hn[0] * hn[0] + hn[1] * hn[1] + hn[2] * hn[2] + hn[3] * hn[3]; } }
;             if (HB) { ss += __shfl_xor(ss, 16); ss += __shfl_xor(ss, 32); if (fq == 0) RS[(size_t)(row0 + ai * HALF + m * 16) * 32 + u.pn * 4 + wc] = ss; }
.LBB0_1302:
	v_readlane_b32 s72, v239, 34
	v_readlane_b32 s73, v239, 35
	v_readlane_b32 s74, v239, 36
	v_readlane_b32 s75, v239, 37
	v_lshl_add_u32 v188, s35, 8, v198
	v_lshl_or_b32 v182, s31, 8, v200
	s_mov_b32 s70, s74
	v_readlane_b32 s72, v240, 62
	v_mad_i64_i32 v[128:129], s[14:15], v188, s70, 0
	v_ashrrev_i32_e32 v183, 31, v182
	v_readlane_b32 s78, v238, 4
	v_readlane_b32 s79, v238, 5
	v_lshlrev_b64 v[130:131], 2, v[182:183]
	v_or_b32_e32 v190, 16, v188
	v_lshl_add_u64 v[128:129], v[128:129], 2, s[78:79]
	v_mov_b32_e32 v180, v204
	v_lshl_add_u64 v[128:129], v[128:129], 0, v[130:131]
	v_lshl_add_u64 v[186:187], s[78:79], 0, v[130:131]
	v_mad_i64_i32 v[192:193], s[16:17], v190, s70, 0
	global_load_dwordx4 v[160:163], v[128:129], off nt
	global_load_dwordx4 v[152:155], v[128:129], off offset:64 nt
	global_load_dwordx4 v[148:151], v[128:129], off offset:512 nt
	global_load_dwordx4 v[144:147], v[128:129], off offset:576 nt
	v_lshl_add_u64 v[128:129], v[192:193], 2, v[186:187]
	global_load_dwordx4 v[140:143], v[128:129], off nt
	global_load_dwordx4 v[136:139], v[128:129], off offset:64 nt
	global_load_dwordx4 v[132:135], v[128:129], off offset:512 nt
	s_nop 0
	global_load_dwordx4 v[128:131], v[128:129], off offset:576 nt
	s_lshl_b32 s14, s31, 2
	s_ashr_i32 s15, s14, 31
	s_lshl_b64 s[14:15], s[14:15], 2
	v_readlane_b32 s76, v238, 2
	v_readlane_b32 s77, v238, 3
	v_mov_b32_e32 v184, v180
	v_mov_b32_e32 v185, v180
	s_add_u32 s14, s4, s14
	v_mad_i64_i32 v[158:159], s[16:17], v188, s70, v[182:183]
	v_ashrrev_i32_e32 v189, 31, v188
	s_addc_u32 s15, s5, s15
	v_lshl_add_u64 v[194:195], v[158:159], 2, s[76:77]
	s_andn2_b64 vcc, exec, s[66:67]
	v_readlane_b32 s73, v240, 63
	v_readlane_b32 s74, v238, 0
	v_readlane_b32 s75, v238, 1
	s_waitcnt vmcnt(0)
	v_pk_fma_f32 v[164:165], v[126:127], v[180:181], v[162:163] op_sel_hi:[1,0,1]
	v_pk_fma_f32 v[162:163], v[124:125], v[180:181], v[160:161] op_sel_hi:[1,0,1]
	v_cndmask_b32_e64 v124, 0, 1, s[66:67]
	v_cmp_ne_u32_e64 s[40:41], 1, v124
	v_pk_fma_f32 v[160:161], v[120:121], v[184:185], v[152:153]
	v_pk_fma_f32 v[156:157], v[116:117], v[184:185], v[148:149]
	v_pk_fma_f32 v[124:125], v[112:113], v[184:185], v[144:145]
	global_store_dwordx4 v[194:195], v[162:165], off nt
	s_cbranch_vccnz .LBB0_1341
	v_readlane_b32 s72, v238, 6
	v_readlane_b32 s74, v238, 8
	v_readlane_b32 s75, v238, 9
	v_cvt_pk_bf16_f32 v116, v162, v163
	v_mul_f32_e32 v120, v163, v163
	v_mov_b32_e32 v181, v180
	v_lshl_add_u64 v[112:113], v[158:159], 1, s[74:75]
	v_cvt_pk_bf16_f32 v117, v164, v165
	global_store_dwordx2 v[112:113], v[116:117], off
	v_fmac_f32_e32 v120, v162, v162
	v_pk_fma_f32 v[162:163], v[122:123], v[180:181], v[154:155]
	v_cvt_pk_bf16_f32 v116, v160, v161
	global_store_dwordx4 v[194:195], v[160:163], off offset:64 nt
	v_cvt_pk_bf16_f32 v117, v162, v163
	global_store_dwordx2 v[112:113], v[116:117], off offset:32
	v_mul_f32_e32 v116, v161, v161
	v_fmac_f32_e32 v116, v160, v160
	v_fmac_f32_e32 v120, v164, v164
	v_fmac_f32_e32 v116, v162, v162
	v_fmac_f32_e32 v120, v165, v165
	v_fmac_f32_e32 v116, v163, v163
	v_add_f32_e32 v120, v120, v116
	v_pk_fma_f32 v[158:159], v[118:119], v[180:181], v[150:151]
	v_cvt_pk_bf16_f32 v116, v156, v157
	global_store_dwordx4 v[194:195], v[156:159], off offset:512 nt
	v_cvt_pk_bf16_f32 v117, v158, v159
	global_store_dwordx2 v[112:113], v[116:117], off offset:256
	v_mul_f32_e32 v116, v157, v157
	v_fmac_f32_e32 v116, v156, v156
	v_fmac_f32_e32 v116, v158, v158
	v_fmac_f32_e32 v116, v159, v159
	v_add_f32_e32 v120, v116, v120
	v_pk_fma_f32 v[126:127], v[114:115], v[180:181], v[146:147]
	v_cvt_pk_bf16_f32 v116, v124, v125
	global_store_dwordx4 v[194:195], v[124:127], off offset:576 nt
	v_cvt_pk_bf16_f32 v117, v126, v127
	global_store_dwordx2 v[112:113], v[116:117], off offset:288
	v_mul_f32_e32 v112, v125, v125
	v_and_b32_e32 v116, 64, v197
	v_fmac_f32_e32 v112, v124, v124
	v_xor_b32_e32 v113, 16, v197
	v_add_u32_e32 v116, 64, v116
	v_fmac_f32_e32 v112, v126, v126
	v_cmp_lt_i32_e32 vcc, v113, v116
	v_fmac_f32_e32 v112, v127, v127
	v_add_f32_e32 v112, v112, v120
	v_cndmask_b32_e32 v113, v197, v113, vcc
	v_lshlrev_b32_e32 v113, 2, v113
	ds_bpermute_b32 v113, v113, v112
	v_readlane_b32 s73, v238, 7
	s_waitcnt lgkmcnt(0)
	v_add_f32_e32 v112, v112, v113
	v_xor_b32_e32 v113, 32, v197
	v_cmp_lt_i32_e32 vcc, v113, v116
	s_nop 1
	v_cndmask_b32_e32 v113, v197, v113, vcc
	v_lshlrev_b32_e32 v113, 2, v113
	ds_bpermute_b32 v113, v113, v112
	s_and_saveexec_b64 s[16:17], s[36:37]
	s_cbranch_execz .LBB0_1305
	s_waitcnt lgkmcnt(0)
	v_add_f32_e32 v116, v112, v113
	v_lshlrev_b64 v[112:113], 7, v[188:189]
	v_lshl_add_u64 v[112:113], s[14:15], 0, v[112:113]
	global_store_dword v[112:113], v116, off

; DEVI unsigned pk_bf16(float lo, float hi) { unsigned r; asm("v_cvt_pk_bf16_f32 %0, %1, %2" : "=v"(r) : "v"(lo), "v"(hi)); return r; }
;     DEVI void operator()(const f32x4 (&acc)[2][2][4][2], const Unit& u, int wr, int wc, int fr, int fq, const LAS float*) const {
;     ...
;             const int ai = idx >> 2, m = idx & 3;
;             const size_t ro = (size_t)(row0 + ai * HALF + m * 16) * ldc + col0;
;             if (idx + 1 < 8) { const int ai2 = (idx + 1) >> 2, m2 = (idx + 1) & 3; const size_t ro2 = (size_t)(row0 + ai2 * HALF + m2 * 16) * ldc + col0;
; #pragma unroll
;                 for (int bj = 0; bj < 2; ++bj)
; #pragma unroll
;                     for (int n = 0; n < 2; ++n) nxt[bj][n] = *(const f32x4*)(R + ro2 + bj * HALF + n * 16); }
;             float ss = 0.f;
; #pragma unroll
;             for (int bj = 0; bj < 2; ++bj)
; #pragma unroll
;                 for (int n = 0; n < 2; ++n) {
;                     const f32x4 hn = cur[bj][n] + acc[ai][bj][m][n] * scale;
;                     *(f32x4*)(C + ro + bj * HALF + n * 16) = hn;
;                     if (HB) { u32x2 w; w.x = pk_bf16(hn[0], hn[1]); w.y = pk_bf16(hn[2], hn[3]); *(u32x2*)(HB + ro + bj * HALF + n * 16) = w;
;                         ss += hn[0] * hn[0] + hn[1] * hn[1] + hn[2] * hn[2] + hn[3] * hn[3]; } }
;             if (HB) { ss += __shfl_xor(ss, 16); ss += __shfl_xor(ss, 32); if (fq == 0) RS[(size_t)(row0 + ai * HALF + m * 16) * 32 + u.pn * 4 + wc] = ss; }
.LBB0_1307:
	v_readlane_b32 s72, v239, 34
	v_or_b32_e32 v150, 32, v188
	v_readlane_b32 s74, v239, 36
	v_readlane_b32 s73, v239, 35
	v_readlane_b32 s75, v239, 37
	v_mad_i64_i32 v[152:153], s[16:17], v150, s74, 0
	s_waitcnt lgkmcnt(0)
	v_lshl_add_u64 v[112:113], v[152:153], 2, v[186:187]
	global_load_dwordx4 v[124:127], v[112:113], off nt
	global_load_dwordx4 v[120:123], v[112:113], off offset:64 nt
	global_load_dwordx4 v[116:119], v[112:113], off offset:512 nt
	s_nop 0
	global_load_dwordx4 v[112:115], v[112:113], off offset:576 nt
	v_readlane_b32 s72, v240, 62
	v_lshl_add_u64 v[156:157], v[192:193], 0, v[182:183]
	v_readlane_b32 s76, v238, 2
	v_readlane_b32 s77, v238, 3
	v_mov_b32_e32 v181, v180
	v_pk_fma_f32 v[148:149], v[110:111], v[180:181], v[142:143]
	v_lshl_add_u64 v[154:155], v[156:157], 2, s[76:77]
	v_pk_fma_f32 v[146:147], v[108:109], v[184:185], v[140:141]
	s_and_b64 vcc, exec, s[40:41]
	v_pk_fma_f32 v[144:145], v[104:105], v[184:185], v[136:137]
	v_pk_fma_f32 v[140:141], v[100:101], v[184:185], v[132:133]
	v_pk_fma_f32 v[108:109], v[96:97], v[184:185], v[128:129]
	v_readlane_b32 s73, v240, 63
	v_readlane_b32 s74, v238, 0
	v_readlane_b32 s75, v238, 1
	v_readlane_b32 s78, v238, 4
	v_readlane_b32 s79, v238, 5
	global_store_dwordx4 v[154:155], v[146:149], off nt
	s_cbranch_vccnz .LBB0_1342
	v_readlane_b32 s72, v238, 6
	v_readlane_b32 s74, v238, 8
	v_readlane_b32 s75, v238, 9
	v_cvt_pk_bf16_f32 v100, v146, v147
	v_mul_f32_e32 v104, v147, v147
	v_cvt_pk_bf16_f32 v101, v148, v149
	v_fmac_f32_e32 v104, v146, v146
	v_lshl_add_u64 v[96:97], v[156:157], 1, s[74:75]
	global_store_dwordx2 v[96:97], v[100:101], off
	v_pk_fma_f32 v[146:147], v[106:107], v[180:181], v[138:139]
	v_cvt_pk_bf16_f32 v100, v144, v145
	global_store_dwordx4 v[154:155], v[144:147], off offset:64 nt
	v_cvt_pk_bf16_f32 v101, v146, v147
	global_store_dwordx2 v[96:97], v[100:101], off offset:32
	v_mul_f32_e32 v100, v145, v145
	v_fmac_f32_e32 v100, v144, v144
	v_fmac_f32_e32 v104, v148, v148
	v_fmac_f32_e32 v100, v146, v146
	v_fmac_f32_e32 v104, v149, v149
	v_fmac_f32_e32 v100, v147, v147
	v_add_f32_e32 v104, v104, v100
	v_pk_fma_f32 v[142:143], v[102:103], v[180:181], v[134:135]
	v_cvt_pk_bf16_f32 v100, v140, v141
	global_store_dwordx4 v[154:155], v[140:143], off offset:512 nt
	v_cvt_pk_bf16_f32 v101, v142, v143
	global_store_dwordx2 v[96:97], v[100:101], off offset:256
	v_mul_f32_e32 v100, v141, v141
	v_fmac_f32_e32 v100, v140, v140
	v_fmac_f32_e32 v100, v142, v142
	v_fmac_f32_e32 v100, v143, v143
	v_add_f32_e32 v104, v104, v100
	v_pk_fma_f32 v[110:111], v[98:99], v[180:181], v[130:131]
	v_cvt_pk_bf16_f32 v100, v108, v109
	global_store_dwordx4 v[154:155], v[108:111], off offset:576 nt
	v_cvt_pk_bf16_f32 v101, v110, v111
	global_store_dwordx2 v[96:97], v[100:101], off offset:288
	v_mul_f32_e32 v96, v109, v109
	v_and_b32_e32 v100, 64, v197
	v_fmac_f32_e32 v96, v108, v108
	v_xor_b32_e32 v97, 16, v197
	v_add_u32_e32 v100, 64, v100
	v_fmac_f32_e32 v96, v110, v110
	v_cmp_lt_i32_e32 vcc, v97, v100
	v_fmac_f32_e32 v96, v111, v111
	v_add_f32_e32 v96, v104, v96
	v_cndmask_b32_e32 v97, v197, v97, vcc
	v_lshlrev_b32_e32 v97, 2, v97
	ds_bpermute_b32 v97, v97, v96
	v_readlane_b32 s73, v238, 7
	s_waitcnt lgkmcnt(0)
	v_add_f32_e32 v96, v96, v97
	v_xor_b32_e32 v97, 32, v197
	v_cmp_lt_i32_e32 vcc, v97, v100
	s_nop 1
	v_cndmask_b32_e32 v97, v197, v97, vcc
	v_lshlrev_b32_e32 v97, 2, v97
	ds_bpermute_b32 v97, v97, v96
	s_and_saveexec_b64 s[16:17], s[36:37]
	s_cbranch_execz .LBB0_1310
	v_ashrrev_i32_e32 v191, 31, v190
	s_waitcnt lgkmcnt(0)
	v_add_f32_e32 v100, v96, v97
	v_lshlrev_b64 v[96:97], 7, v[190:191]
	v_lshl_add_u64 v[96:97], s[14:15], 0, v[96:97]
	global_store_dword v[96:97], v100, off

; DEVI unsigned pk_bf16(float lo, float hi) { unsigned r; asm("v_cvt_pk_bf16_f32 %0, %1, %2" : "=v"(r) : "v"(lo), "v"(hi)); return r; }
;     DEVI void operator()(const f32x4 (&acc)[2][2][4][2], const Unit& u, int wr, int wc, int fr, int fq, const LAS float*) const {
;     ...
;             const int ai = idx >> 2, m = idx & 3;
;             const size_t ro = (size_t)(row0 + ai * HALF + m * 16) * ldc + col0;
;             if (idx + 1 < 8) { const int ai2 = (idx + 1) >> 2, m2 = (idx + 1) & 3; const size_t ro2 = (size_t)(row0 + ai2 * HALF + m2 * 16) * ldc + col0;
; #pragma unroll
;                 for (int bj = 0; bj < 2; ++bj)
; #pragma unroll
;                     for (int n = 0; n < 2; ++n) nxt[bj][n] = *(const f32x4*)(R + ro2 + bj * HALF + n * 16); }
;             float ss = 0.f;
; #pragma unroll
;             for (int bj = 0; bj < 2; ++bj)
; #pragma unroll
;                 for (int n = 0; n < 2; ++n) {
;                     const f32x4 hn = cur[bj][n] + acc[ai][bj][m][n] * scale;
;                     *(f32x4*)(C + ro + bj * HALF + n * 16) = hn;
;                     if (HB) { u32x2 w; w.x = pk_bf16(hn[0], hn[1]); w.y = pk_bf16(hn[2], hn[3]); *(u32x2*)(HB + ro + bj * HALF + n * 16) = w;
;                         ss += hn[0] * hn[0] + hn[1] * hn[1] + hn[2] * hn[2] + hn[3] * hn[3]; } }
;             if (HB) { ss += __shfl_xor(ss, 16); ss += __shfl_xor(ss, 32); if (fq == 0) RS[(size_t)(row0 + ai * HALF + m * 16) * 32 + u.pn * 4 + wc] = ss; }
.LBB0_1312:
	v_readlane_b32 s72, v239, 34
	v_or_b32_e32 v134, 48, v188
	v_readlane_b32 s74, v239, 36
	v_readlane_b32 s73, v239, 35
	v_readlane_b32 s75, v239, 37
	v_mad_i64_i32 v[136:137], s[16:17], v134, s74, 0
	s_waitcnt lgkmcnt(0)
	v_lshl_add_u64 v[96:97], v[136:137], 2, v[186:187]
	global_load_dwordx4 v[108:111], v[96:97], off nt
	global_load_dwordx4 v[104:107], v[96:97], off offset:64 nt
	global_load_dwordx4 v[100:103], v[96:97], off offset:512 nt
	s_nop 0
	global_load_dwordx4 v[96:99], v[96:97], off offset:576 nt
	v_readlane_b32 s72, v240, 62
	v_lshl_add_u64 v[140:141], v[152:153], 0, v[182:183]
	v_readlane_b32 s76, v238, 2
	v_readlane_b32 s77, v238, 3
	v_mov_b32_e32 v181, v180
	s_waitcnt vmcnt(8)
	v_pk_fma_f32 v[132:133], v[94:95], v[180:181], v[126:127]
	v_lshl_add_u64 v[138:139], v[140:141], 2, s[76:77]
	v_pk_fma_f32 v[130:131], v[92:93], v[184:185], v[124:125]
	s_and_b64 vcc, exec, s[40:41]
	s_waitcnt vmcnt(7)
	v_pk_fma_f32 v[128:129], v[88:89], v[184:185], v[120:121]
	s_waitcnt vmcnt(6)
	v_pk_fma_f32 v[124:125], v[84:85], v[184:185], v[116:117]
	s_waitcnt vmcnt(5)
	v_pk_fma_f32 v[92:93], v[80:81], v[184:185], v[112:113]
	v_readlane_b32 s73, v240, 63
	v_readlane_b32 s74, v238, 0
	v_readlane_b32 s75, v238, 1
	v_readlane_b32 s78, v238, 4
	v_readlane_b32 s79, v238, 5
	global_store_dwordx4 v[138:139], v[130:133], off nt
	s_cbranch_vccnz .LBB0_1343
	v_readlane_b32 s72, v238, 6
	v_readlane_b32 s74, v238, 8
	v_readlane_b32 s75, v238, 9
	v_cvt_pk_bf16_f32 v84, v130, v131
	v_mul_f32_e32 v88, v131, v131
	v_cvt_pk_bf16_f32 v85, v132, v133
	v_fmac_f32_e32 v88, v130, v130
	v_lshl_add_u64 v[80:81], v[140:141], 1, s[74:75]
	global_store_dwordx2 v[80:81], v[84:85], off
	v_pk_fma_f32 v[130:131], v[90:91], v[180:181], v[122:123]
	v_cvt_pk_bf16_f32 v84, v128, v129
	global_store_dwordx4 v[138:139], v[128:131], off offset:64 nt
	v_cvt_pk_bf16_f32 v85, v130, v131
	global_store_dwordx2 v[80:81], v[84:85], off offset:32
	v_mul_f32_e32 v84, v129, v129
	v_fmac_f32_e32 v84, v128, v128
	v_fmac_f32_e32 v88, v132, v132
	v_fmac_f32_e32 v84, v130, v130
	v_fmac_f32_e32 v88, v133, v133
	v_fmac_f32_e32 v84, v131, v131
	v_add_f32_e32 v88, v88, v84
	v_pk_fma_f32 v[126:127], v[86:87], v[180:181], v[118:119]
	v_cvt_pk_bf16_f32 v84, v124, v125
	global_store_dwordx4 v[138:139], v[124:127], off offset:512 nt
	v_cvt_pk_bf16_f32 v85, v126, v127
	global_store_dwordx2 v[80:81], v[84:85], off offset:256
	v_mul_f32_e32 v84, v125, v125
	v_fmac_f32_e32 v84, v124, v124
	v_fmac_f32_e32 v84, v126, v126
	v_fmac_f32_e32 v84, v127, v127
	v_add_f32_e32 v88, v88, v84
	v_pk_fma_f32 v[94:95], v[82:83], v[180:181], v[114:115]
	v_cvt_pk_bf16_f32 v84, v92, v93
	global_store_dwordx4 v[138:139], v[92:95], off offset:576 nt
	v_cvt_pk_bf16_f32 v85, v94, v95
	global_store_dwordx2 v[80:81], v[84:85], off offset:288
	v_mul_f32_e32 v80, v93, v93
	v_and_b32_e32 v84, 64, v197
	v_fmac_f32_e32 v80, v92, v92
	v_xor_b32_e32 v81, 16, v197
	v_add_u32_e32 v84, 64, v84
	v_fmac_f32_e32 v80, v94, v94
	v_cmp_lt_i32_e32 vcc, v81, v84
	v_fmac_f32_e32 v80, v95, v95
	v_add_f32_e32 v80, v88, v80
	v_cndmask_b32_e32 v81, v197, v81, vcc
	v_lshlrev_b32_e32 v81, 2, v81
	ds_bpermute_b32 v81, v81, v80
	v_readlane_b32 s73, v238, 7
	s_waitcnt lgkmcnt(0)
	v_add_f32_e32 v80, v80, v81
	v_xor_b32_e32 v81, 32, v197
	v_cmp_lt_i32_e32 vcc, v81, v84
	s_nop 1
	v_cndmask_b32_e32 v81, v197, v81, vcc
	v_lshlrev_b32_e32 v81, 2, v81
	ds_bpermute_b32 v81, v81, v80
	s_and_saveexec_b64 s[16:17], s[36:37]
	s_cbranch_execz .LBB0_1315
	v_ashrrev_i32_e32 v151, 31, v150
	s_waitcnt lgkmcnt(0)
	v_add_f32_e32 v84, v80, v81
	v_lshlrev_b64 v[80:81], 7, v[150:151]
	v_lshl_add_u64 v[80:81], s[14:15], 0, v[80:81]
	global_store_dword v[80:81], v84, off

; DEVI unsigned pk_bf16(float lo, float hi) { unsigned r; asm("v_cvt_pk_bf16_f32 %0, %1, %2" : "=v"(r) : "v"(lo), "v"(hi)); return r; }
;     DEVI void operator()(const f32x4 (&acc)[2][2][4][2], const Unit& u, int wr, int wc, int fr, int fq, const LAS float*) const {
;     ...
;             const int ai = idx >> 2, m = idx & 3;
;             const size_t ro = (size_t)(row0 + ai * HALF + m * 16) * ldc + col0;
;             if (idx + 1 < 8) { const int ai2 = (idx + 1) >> 2, m2 = (idx + 1) & 3; const size_t ro2 = (size_t)(row0 + ai2 * HALF + m2 * 16) * ldc + col0;
; #pragma unroll
;                 for (int bj = 0; bj < 2; ++bj)
; #pragma unroll
;                     for (int n = 0; n < 2; ++n) nxt[bj][n] = *(const f32x4*)(R + ro2 + bj * HALF + n * 16); }
;             float ss = 0.f;
; #pragma unroll
;             for (int bj = 0; bj < 2; ++bj)
; #pragma unroll
;                 for (int n = 0; n < 2; ++n) {
;                     const f32x4 hn = cur[bj][n] + acc[ai][bj][m][n] * scale;
;                     *(f32x4*)(C + ro + bj * HALF + n * 16) = hn;
;                     if (HB) { u32x2 w; w.x = pk_bf16(hn[0], hn[1]); w.y = pk_bf16(hn[2], hn[3]); *(u32x2*)(HB + ro + bj * HALF + n * 16) = w;
;                         ss += hn[0] * hn[0] + hn[1] * hn[1] + hn[2] * hn[2] + hn[3] * hn[3]; } }
;             if (HB) { ss += __shfl_xor(ss, 16); ss += __shfl_xor(ss, 32); if (fq == 0) RS[(size_t)(row0 + ai * HALF + m * 16) * 32 + u.pn * 4 + wc] = ss; }
.LBB0_1317:
	v_readlane_b32 s72, v239, 34
	v_add_u32_e32 v118, 0x80, v188
	v_readlane_b32 s74, v239, 36
	v_readlane_b32 s73, v239, 35
	v_readlane_b32 s75, v239, 37
	v_mad_i64_i32 v[120:121], s[16:17], v118, s74, 0
	s_waitcnt lgkmcnt(0)
	v_lshl_add_u64 v[80:81], v[120:121], 2, v[186:187]
	global_load_dwordx4 v[92:95], v[80:81], off nt
	global_load_dwordx4 v[88:91], v[80:81], off offset:64 nt
	global_load_dwordx4 v[84:87], v[80:81], off offset:512 nt
	s_nop 0
	global_load_dwordx4 v[80:83], v[80:81], off offset:576 nt
	v_readlane_b32 s72, v240, 62
	v_lshl_add_u64 v[124:125], v[136:137], 0, v[182:183]
	v_readlane_b32 s76, v238, 2
	v_readlane_b32 s77, v238, 3
	v_mov_b32_e32 v181, v180
	s_waitcnt vmcnt(8)
	v_pk_fma_f32 v[116:117], v[78:79], v[180:181], v[110:111]
	v_lshl_add_u64 v[122:123], v[124:125], 2, s[76:77]
	v_pk_fma_f32 v[114:115], v[76:77], v[184:185], v[108:109]
	s_and_b64 vcc, exec, s[40:41]
	s_waitcnt vmcnt(7)
	v_pk_fma_f32 v[112:113], v[72:73], v[184:185], v[104:105]
	s_waitcnt vmcnt(6)
	v_pk_fma_f32 v[108:109], v[68:69], v[184:185], v[100:101]
	s_waitcnt vmcnt(5)
	v_pk_fma_f32 v[76:77], v[64:65], v[184:185], v[96:97]
	v_readlane_b32 s73, v240, 63
	v_readlane_b32 s74, v238, 0
	v_readlane_b32 s75, v238, 1
	v_readlane_b32 s78, v238, 4
	v_readlane_b32 s79, v238, 5
	global_store_dwordx4 v[122:123], v[114:117], off nt
	s_cbranch_vccnz .LBB0_1344
	v_readlane_b32 s72, v238, 6
	v_readlane_b32 s74, v238, 8
	v_readlane_b32 s75, v238, 9
	v_cvt_pk_bf16_f32 v68, v114, v115
	v_mul_f32_e32 v72, v115, v115
	v_cvt_pk_bf16_f32 v69, v116, v117
	v_fmac_f32_e32 v72, v114, v114
	v_lshl_add_u64 v[64:65], v[124:125], 1, s[74:75]
	global_store_dwordx2 v[64:65], v[68:69], off
	v_pk_fma_f32 v[114:115], v[74:75], v[180:181], v[106:107]
	v_cvt_pk_bf16_f32 v68, v112, v113
	global_store_dwordx4 v[122:123], v[112:115], off offset:64 nt
	v_cvt_pk_bf16_f32 v69, v114, v115
	global_store_dwordx2 v[64:65], v[68:69], off offset:32
	v_mul_f32_e32 v68, v113, v113
	v_fmac_f32_e32 v68, v112, v112
	v_fmac_f32_e32 v72, v116, v116
	v_fmac_f32_e32 v68, v114, v114
	v_fmac_f32_e32 v72, v117, v117
	v_fmac_f32_e32 v68, v115, v115
	v_add_f32_e32 v72, v72, v68
	v_pk_fma_f32 v[110:111], v[70:71], v[180:181], v[102:103]
	v_cvt_pk_bf16_f32 v68, v108, v109
	global_store_dwordx4 v[122:123], v[108:111], off offset:512 nt
	v_cvt_pk_bf16_f32 v69, v110, v111
	global_store_dwordx2 v[64:65], v[68:69], off offset:256
	v_mul_f32_e32 v68, v109, v109
	v_fmac_f32_e32 v68, v108, v108
	v_fmac_f32_e32 v68, v110, v110
	v_fmac_f32_e32 v68, v111, v111
	v_add_f32_e32 v72, v72, v68
	v_pk_fma_f32 v[78:79], v[66:67], v[180:181], v[98:99]
	v_cvt_pk_bf16_f32 v68, v76, v77
	global_store_dwordx4 v[122:123], v[76:79], off offset:576 nt
	v_cvt_pk_bf16_f32 v69, v78, v79
	global_store_dwordx2 v[64:65], v[68:69], off offset:288
	v_mul_f32_e32 v64, v77, v77
	v_and_b32_e32 v68, 64, v197
	v_fmac_f32_e32 v64, v76, v76
	v_xor_b32_e32 v65, 16, v197
	v_add_u32_e32 v68, 64, v68
	v_fmac_f32_e32 v64, v78, v78
	v_cmp_lt_i32_e32 vcc, v65, v68
	v_fmac_f32_e32 v64, v79, v79
	v_add_f32_e32 v64, v72, v64
	v_cndmask_b32_e32 v65, v197, v65, vcc
	v_lshlrev_b32_e32 v65, 2, v65
	ds_bpermute_b32 v65, v65, v64
	v_readlane_b32 s73, v238, 7
	s_waitcnt lgkmcnt(0)
	v_add_f32_e32 v64, v64, v65
	v_xor_b32_e32 v65, 32, v197
	v_cmp_lt_i32_e32 vcc, v65, v68
	s_nop 1
	v_cndmask_b32_e32 v65, v197, v65, vcc
	v_lshlrev_b32_e32 v65, 2, v65
	ds_bpermute_b32 v65, v65, v64
	s_and_saveexec_b64 s[16:17], s[36:37]
	s_cbranch_execz .LBB0_1320
	v_ashrrev_i32_e32 v135, 31, v134
	s_waitcnt lgkmcnt(0)
	v_add_f32_e32 v68, v64, v65
	v_lshlrev_b64 v[64:65], 7, v[134:135]
	v_lshl_add_u64 v[64:65], s[14:15], 0, v[64:65]
	global_store_dword v[64:65], v68, off

; DEVI unsigned pk_bf16(float lo, float hi) { unsigned r; asm("v_cvt_pk_bf16_f32 %0, %1, %2" : "=v"(r) : "v"(lo), "v"(hi)); return r; }
;     DEVI void operator()(const f32x4 (&acc)[2][2][4][2], const Unit& u, int wr, int wc, int fr, int fq, const LAS float*) const {
;     ...
;             const int ai = idx >> 2, m = idx & 3;
;             const size_t ro = (size_t)(row0 + ai * HALF + m * 16) * ldc + col0;
;             if (idx + 1 < 8) { const int ai2 = (idx + 1) >> 2, m2 = (idx + 1) & 3; const size_t ro2 = (size_t)(row0 + ai2 * HALF + m2 * 16) * ldc + col0;
; #pragma unroll
;                 for (int bj = 0; bj < 2; ++bj)
; #pragma unroll
;                     for (int n = 0; n < 2; ++n) nxt[bj][n] = *(const f32x4*)(R + ro2 + bj * HALF + n * 16); }
;             float ss = 0.f;
; #pragma unroll
;             for (int bj = 0; bj < 2; ++bj)
; #pragma unroll
;                 for (int n = 0; n < 2; ++n) {
;                     const f32x4 hn = cur[bj][n] + acc[ai][bj][m][n] * scale;
;                     *(f32x4*)(C + ro + bj * HALF + n * 16) = hn;
;                     if (HB) { u32x2 w; w.x = pk_bf16(hn[0], hn[1]); w.y = pk_bf16(hn[2], hn[3]); *(u32x2*)(HB + ro + bj * HALF + n * 16) = w;
;                         ss += hn[0] * hn[0] + hn[1] * hn[1] + hn[2] * hn[2] + hn[3] * hn[3]; } }
;             if (HB) { ss += __shfl_xor(ss, 16); ss += __shfl_xor(ss, 32); if (fq == 0) RS[(size_t)(row0 + ai * HALF + m * 16) * 32 + u.pn * 4 + wc] = ss; }
.LBB0_1322:
	v_readlane_b32 s72, v239, 34
	v_or_b32_e32 v102, 16, v118
	v_readlane_b32 s74, v239, 36
	v_readlane_b32 s73, v239, 35
	v_readlane_b32 s75, v239, 37
	v_mad_i64_i32 v[104:105], s[16:17], v102, s74, 0
	s_waitcnt lgkmcnt(0)
	v_lshl_add_u64 v[64:65], v[104:105], 2, v[186:187]
	global_load_dwordx4 v[76:79], v[64:65], off nt
	global_load_dwordx4 v[72:75], v[64:65], off offset:64 nt
	global_load_dwordx4 v[68:71], v[64:65], off offset:512 nt
	s_nop 0
	global_load_dwordx4 v[64:67], v[64:65], off offset:576 nt
	v_readlane_b32 s72, v240, 62
	v_lshl_add_u64 v[108:109], v[120:121], 0, v[182:183]
	v_readlane_b32 s76, v238, 2
	v_readlane_b32 s77, v238, 3
	v_mov_b32_e32 v181, v180
	v_ashrrev_i32_e32 v119, 31, v118
	v_lshl_add_u64 v[106:107], v[108:109], 2, s[76:77]
	s_waitcnt vmcnt(8)
	v_pk_fma_f32 v[100:101], v[62:63], v[180:181], v[94:95]
	v_pk_fma_f32 v[98:99], v[60:61], v[184:185], v[92:93]
	s_and_b64 vcc, exec, s[40:41]
	s_waitcnt vmcnt(7)
	v_pk_fma_f32 v[96:97], v[56:57], v[184:185], v[88:89]
	s_waitcnt vmcnt(6)
	v_pk_fma_f32 v[92:93], v[52:53], v[184:185], v[84:85]
	s_waitcnt vmcnt(5)
	v_pk_fma_f32 v[60:61], v[48:49], v[184:185], v[80:81]
	v_readlane_b32 s73, v240, 63
	v_readlane_b32 s74, v238, 0
	v_readlane_b32 s75, v238, 1
	v_readlane_b32 s78, v238, 4
	v_readlane_b32 s79, v238, 5
	global_store_dwordx4 v[106:107], v[98:101], off nt
	s_cbranch_vccnz .LBB0_1345
	v_readlane_b32 s72, v238, 6
	v_readlane_b32 s74, v238, 8
	v_readlane_b32 s75, v238, 9
	v_cvt_pk_bf16_f32 v52, v98, v99
	v_mul_f32_e32 v56, v99, v99
	v_cvt_pk_bf16_f32 v53, v100, v101
	v_fmac_f32_e32 v56, v98, v98
	v_lshl_add_u64 v[48:49], v[108:109], 1, s[74:75]
	global_store_dwordx2 v[48:49], v[52:53], off
	v_pk_fma_f32 v[98:99], v[58:59], v[180:181], v[90:91]
	v_cvt_pk_bf16_f32 v52, v96, v97
	global_store_dwordx4 v[106:107], v[96:99], off offset:64 nt
	v_cvt_pk_bf16_f32 v53, v98, v99
	global_store_dwordx2 v[48:49], v[52:53], off offset:32
	v_mul_f32_e32 v52, v97, v97
	v_fmac_f32_e32 v52, v96, v96
	v_fmac_f32_e32 v56, v100, v100
	v_fmac_f32_e32 v52, v98, v98
	v_fmac_f32_e32 v56, v101, v101
	v_fmac_f32_e32 v52, v99, v99
	v_add_f32_e32 v56, v56, v52
	v_pk_fma_f32 v[94:95], v[54:55], v[180:181], v[86:87]
	v_cvt_pk_bf16_f32 v52, v92, v93
	global_store_dwordx4 v[106:107], v[92:95], off offset:512 nt
	v_cvt_pk_bf16_f32 v53, v94, v95
	global_store_dwordx2 v[48:49], v[52:53], off offset:256
	v_mul_f32_e32 v52, v93, v93
	v_fmac_f32_e32 v52, v92, v92
	v_fmac_f32_e32 v52, v94, v94
	v_fmac_f32_e32 v52, v95, v95
	v_add_f32_e32 v56, v56, v52
	v_pk_fma_f32 v[62:63], v[50:51], v[180:181], v[82:83]
	v_cvt_pk_bf16_f32 v52, v60, v61
	global_store_dwordx4 v[106:107], v[60:63], off offset:576 nt
	v_cvt_pk_bf16_f32 v53, v62, v63
	global_store_dwordx2 v[48:49], v[52:53], off offset:288
	v_mul_f32_e32 v48, v61, v61
	v_and_b32_e32 v52, 64, v197
	v_fmac_f32_e32 v48, v60, v60
	v_xor_b32_e32 v49, 16, v197
	v_add_u32_e32 v52, 64, v52
	v_fmac_f32_e32 v48, v62, v62
	v_cmp_lt_i32_e32 vcc, v49, v52
	v_fmac_f32_e32 v48, v63, v63
	v_add_f32_e32 v48, v56, v48
	v_cndmask_b32_e32 v49, v197, v49, vcc
	v_lshlrev_b32_e32 v49, 2, v49
	ds_bpermute_b32 v49, v49, v48
	v_readlane_b32 s73, v238, 7
	s_waitcnt lgkmcnt(0)
	v_add_f32_e32 v48, v48, v49
	v_xor_b32_e32 v49, 32, v197
	v_cmp_lt_i32_e32 vcc, v49, v52
	s_nop 1
	v_cndmask_b32_e32 v49, v197, v49, vcc
	v_lshlrev_b32_e32 v49, 2, v49
	ds_bpermute_b32 v49, v49, v48
	s_and_saveexec_b64 s[16:17], s[36:37]
	s_cbranch_execz .LBB0_1325
	s_waitcnt lgkmcnt(0)
	v_add_f32_e32 v52, v48, v49
	v_lshlrev_b64 v[48:49], 7, v[118:119]
	v_lshl_add_u64 v[48:49], s[14:15], 0, v[48:49]
	global_store_dword v[48:49], v52, off

; DEVI unsigned pk_bf16(float lo, float hi) { unsigned r; asm("v_cvt_pk_bf16_f32 %0, %1, %2" : "=v"(r) : "v"(lo), "v"(hi)); return r; }
;     DEVI void operator()(const f32x4 (&acc)[2][2][4][2], const Unit& u, int wr, int wc, int fr, int fq, const LAS float*) const {
;     ...
;             const int ai = idx >> 2, m = idx & 3;
;             const size_t ro = (size_t)(row0 + ai * HALF + m * 16) * ldc + col0;
;             if (idx + 1 < 8) { const int ai2 = (idx + 1) >> 2, m2 = (idx + 1) & 3; const size_t ro2 = (size_t)(row0 + ai2 * HALF + m2 * 16) * ldc + col0;
; #pragma unroll
;                 for (int bj = 0; bj < 2; ++bj)
; #pragma unroll
;                     for (int n = 0; n < 2; ++n) nxt[bj][n] = *(const f32x4*)(R + ro2 + bj * HALF + n * 16); }
;             float ss = 0.f;
; #pragma unroll
;             for (int bj = 0; bj < 2; ++bj)
; #pragma unroll
;                 for (int n = 0; n < 2; ++n) {
;                     const f32x4 hn = cur[bj][n] + acc[ai][bj][m][n] * scale;
;                     *(f32x4*)(C + ro + bj * HALF + n * 16) = hn;
;                     if (HB) { u32x2 w; w.x = pk_bf16(hn[0], hn[1]); w.y = pk_bf16(hn[2], hn[3]); *(u32x2*)(HB + ro + bj * HALF + n * 16) = w;
;                         ss += hn[0] * hn[0] + hn[1] * hn[1] + hn[2] * hn[2] + hn[3] * hn[3]; } }
;             if (HB) { ss += __shfl_xor(ss, 16); ss += __shfl_xor(ss, 32); if (fq == 0) RS[(size_t)(row0 + ai * HALF + m * 16) * 32 + u.pn * 4 + wc] = ss; }
.LBB0_1327:
	v_readlane_b32 s72, v239, 34
	v_or_b32_e32 v86, 32, v118
	v_readlane_b32 s74, v239, 36
	v_readlane_b32 s73, v239, 35
	v_readlane_b32 s75, v239, 37
	v_mad_i64_i32 v[88:89], s[16:17], v86, s74, 0
	s_waitcnt lgkmcnt(0)
	v_lshl_add_u64 v[48:49], v[88:89], 2, v[186:187]
	global_load_dwordx4 v[60:63], v[48:49], off nt
	global_load_dwordx4 v[56:59], v[48:49], off offset:64 nt
	global_load_dwordx4 v[52:55], v[48:49], off offset:512 nt
	s_nop 0
	global_load_dwordx4 v[48:51], v[48:49], off offset:576 nt
	v_readlane_b32 s72, v240, 62
	v_lshl_add_u64 v[92:93], v[104:105], 0, v[182:183]
	v_readlane_b32 s76, v238, 2
	v_readlane_b32 s77, v238, 3
	v_mov_b32_e32 v181, v180
	s_waitcnt vmcnt(8)
	v_pk_fma_f32 v[84:85], v[46:47], v[180:181], v[78:79]
	v_lshl_add_u64 v[90:91], v[92:93], 2, s[76:77]
	v_pk_fma_f32 v[82:83], v[44:45], v[184:185], v[76:77]
	s_and_b64 vcc, exec, s[40:41]
	s_waitcnt vmcnt(7)
	v_pk_fma_f32 v[80:81], v[40:41], v[184:185], v[72:73]
	s_waitcnt vmcnt(6)
	v_pk_fma_f32 v[76:77], v[36:37], v[184:185], v[68:69]
	s_waitcnt vmcnt(5)
	v_pk_fma_f32 v[44:45], v[32:33], v[184:185], v[64:65]
	v_readlane_b32 s73, v240, 63
	v_readlane_b32 s74, v238, 0
	v_readlane_b32 s75, v238, 1
	v_readlane_b32 s78, v238, 4
	v_readlane_b32 s79, v238, 5
	global_store_dwordx4 v[90:91], v[82:85], off nt
	s_cbranch_vccnz .LBB0_1346
	v_readlane_b32 s72, v238, 6
	v_readlane_b32 s74, v238, 8
	v_readlane_b32 s75, v238, 9
	v_cvt_pk_bf16_f32 v36, v82, v83
	v_mul_f32_e32 v40, v83, v83
	v_cvt_pk_bf16_f32 v37, v84, v85
	v_fmac_f32_e32 v40, v82, v82
	v_lshl_add_u64 v[32:33], v[92:93], 1, s[74:75]
	global_store_dwordx2 v[32:33], v[36:37], off
	v_pk_fma_f32 v[82:83], v[42:43], v[180:181], v[74:75]
	v_cvt_pk_bf16_f32 v36, v80, v81
	global_store_dwordx4 v[90:91], v[80:83], off offset:64 nt
	v_cvt_pk_bf16_f32 v37, v82, v83
	global_store_dwordx2 v[32:33], v[36:37], off offset:32
	v_mul_f32_e32 v36, v81, v81
	v_fmac_f32_e32 v36, v80, v80
	v_fmac_f32_e32 v40, v84, v84
	v_fmac_f32_e32 v36, v82, v82
	v_fmac_f32_e32 v40, v85, v85
	v_fmac_f32_e32 v36, v83, v83
	v_add_f32_e32 v40, v40, v36
	v_pk_fma_f32 v[78:79], v[38:39], v[180:181], v[70:71]
	v_cvt_pk_bf16_f32 v36, v76, v77
	global_store_dwordx4 v[90:91], v[76:79], off offset:512 nt
	v_cvt_pk_bf16_f32 v37, v78, v79
	global_store_dwordx2 v[32:33], v[36:37], off offset:256
	v_mul_f32_e32 v36, v77, v77
	v_fmac_f32_e32 v36, v76, v76
	v_fmac_f32_e32 v36, v78, v78
	v_fmac_f32_e32 v36, v79, v79
	v_add_f32_e32 v40, v40, v36
	v_pk_fma_f32 v[46:47], v[34:35], v[180:181], v[66:67]
	v_cvt_pk_bf16_f32 v36, v44, v45
	global_store_dwordx4 v[90:91], v[44:47], off offset:576 nt
	v_cvt_pk_bf16_f32 v37, v46, v47
	global_store_dwordx2 v[32:33], v[36:37], off offset:288
	v_mul_f32_e32 v32, v45, v45
	v_and_b32_e32 v36, 64, v197
	v_fmac_f32_e32 v32, v44, v44
	v_xor_b32_e32 v33, 16, v197
	v_add_u32_e32 v36, 64, v36
	v_fmac_f32_e32 v32, v46, v46
	v_cmp_lt_i32_e32 vcc, v33, v36
	v_fmac_f32_e32 v32, v47, v47
	v_add_f32_e32 v32, v40, v32
	v_cndmask_b32_e32 v33, v197, v33, vcc
	v_lshlrev_b32_e32 v33, 2, v33
	ds_bpermute_b32 v33, v33, v32
	v_readlane_b32 s73, v238, 7
	s_waitcnt lgkmcnt(0)
	v_add_f32_e32 v32, v32, v33
	v_xor_b32_e32 v33, 32, v197
	v_cmp_lt_i32_e32 vcc, v33, v36
	s_nop 1
	v_cndmask_b32_e32 v33, v197, v33, vcc
	v_lshlrev_b32_e32 v33, 2, v33
	ds_bpermute_b32 v33, v33, v32
	s_and_saveexec_b64 s[16:17], s[36:37]
	s_cbranch_execz .LBB0_1330
	v_ashrrev_i32_e32 v103, 31, v102
	s_waitcnt lgkmcnt(0)
	v_add_f32_e32 v36, v32, v33
	v_lshlrev_b64 v[32:33], 7, v[102:103]
	v_lshl_add_u64 v[32:33], s[14:15], 0, v[32:33]
	global_store_dword v[32:33], v36, off

; DEVI unsigned pk_bf16(float lo, float hi) { unsigned r; asm("v_cvt_pk_bf16_f32 %0, %1, %2" : "=v"(r) : "v"(lo), "v"(hi)); return r; }
;     DEVI void operator()(const f32x4 (&acc)[2][2][4][2], const Unit& u, int wr, int wc, int fr, int fq, const LAS float*) const {
;     ...
;             const int ai = idx >> 2, m = idx & 3;
;             const size_t ro = (size_t)(row0 + ai * HALF + m * 16) * ldc + col0;
;             if (idx + 1 < 8) { const int ai2 = (idx + 1) >> 2, m2 = (idx + 1) & 3; const size_t ro2 = (size_t)(row0 + ai2 * HALF + m2 * 16) * ldc + col0;
; #pragma unroll
;                 for (int bj = 0; bj < 2; ++bj)
; #pragma unroll
;                     for (int n = 0; n < 2; ++n) nxt[bj][n] = *(const f32x4*)(R + ro2 + bj * HALF + n * 16); }
;             float ss = 0.f;
; #pragma unroll
;             for (int bj = 0; bj < 2; ++bj)
; #pragma unroll
;                 for (int n = 0; n < 2; ++n) {
;                     const f32x4 hn = cur[bj][n] + acc[ai][bj][m][n] * scale;
;                     *(f32x4*)(C + ro + bj * HALF + n * 16) = hn;
;                     if (HB) { u32x2 w; w.x = pk_bf16(hn[0], hn[1]); w.y = pk_bf16(hn[2], hn[3]); *(u32x2*)(HB + ro + bj * HALF + n * 16) = w;
;                         ss += hn[0] * hn[0] + hn[1] * hn[1] + hn[2] * hn[2] + hn[3] * hn[3]; } }
;             if (HB) { ss += __shfl_xor(ss, 16); ss += __shfl_xor(ss, 32); if (fq == 0) RS[(size_t)(row0 + ai * HALF + m * 16) * 32 + u.pn * 4 + wc] = ss; }
.LBB0_1332:
	v_readlane_b32 s72, v239, 34
	v_or_b32_e32 v70, 48, v118
	v_readlane_b32 s74, v239, 36
	v_readlane_b32 s73, v239, 35
	v_readlane_b32 s75, v239, 37
	v_mad_i64_i32 v[72:73], s[16:17], v70, s74, 0
	s_waitcnt lgkmcnt(0)
	v_lshl_add_u64 v[32:33], v[72:73], 2, v[186:187]
	global_load_dwordx4 v[44:47], v[32:33], off nt
	global_load_dwordx4 v[40:43], v[32:33], off offset:64 nt
	global_load_dwordx4 v[36:39], v[32:33], off offset:512 nt
	s_nop 0
	global_load_dwordx4 v[32:35], v[32:33], off offset:576 nt
	v_readlane_b32 s72, v240, 62
	v_lshl_add_u64 v[76:77], v[88:89], 0, v[182:183]
	v_readlane_b32 s76, v238, 2
	v_readlane_b32 s77, v238, 3
	v_mov_b32_e32 v181, v180
	s_waitcnt vmcnt(8)
	v_pk_fma_f32 v[68:69], v[30:31], v[180:181], v[62:63]
	v_lshl_add_u64 v[74:75], v[76:77], 2, s[76:77]
	v_pk_fma_f32 v[66:67], v[28:29], v[184:185], v[60:61]
	s_and_b64 vcc, exec, s[40:41]
	s_waitcnt vmcnt(7)
	v_pk_fma_f32 v[64:65], v[24:25], v[184:185], v[56:57]
	s_waitcnt vmcnt(6)
	v_pk_fma_f32 v[60:61], v[20:21], v[184:185], v[52:53]
	s_waitcnt vmcnt(5)
	v_pk_fma_f32 v[28:29], v[16:17], v[184:185], v[48:49]
	v_readlane_b32 s73, v240, 63
	v_readlane_b32 s74, v238, 0
	v_readlane_b32 s75, v238, 1
	v_readlane_b32 s78, v238, 4
	v_readlane_b32 s79, v238, 5
	global_store_dwordx4 v[74:75], v[66:69], off nt
	s_cbranch_vccnz .LBB0_1347
	v_readlane_b32 s72, v238, 6
	v_readlane_b32 s74, v238, 8
	v_readlane_b32 s75, v238, 9
	v_cvt_pk_bf16_f32 v20, v66, v67
	v_mul_f32_e32 v24, v67, v67
	v_cvt_pk_bf16_f32 v21, v68, v69
	v_fmac_f32_e32 v24, v66, v66
	v_lshl_add_u64 v[16:17], v[76:77], 1, s[74:75]
	global_store_dwordx2 v[16:17], v[20:21], off
	v_pk_fma_f32 v[66:67], v[26:27], v[180:181], v[58:59]
	v_cvt_pk_bf16_f32 v20, v64, v65
	global_store_dwordx4 v[74:75], v[64:67], off offset:64 nt
	v_cvt_pk_bf16_f32 v21, v66, v67
	global_store_dwordx2 v[16:17], v[20:21], off offset:32
	v_mul_f32_e32 v20, v65, v65
	v_fmac_f32_e32 v20, v64, v64
	v_fmac_f32_e32 v24, v68, v68
	v_fmac_f32_e32 v20, v66, v66
	v_fmac_f32_e32 v24, v69, v69
	v_fmac_f32_e32 v20, v67, v67
	v_add_f32_e32 v24, v24, v20
	v_pk_fma_f32 v[62:63], v[22:23], v[180:181], v[54:55]
	v_cvt_pk_bf16_f32 v20, v60, v61
	global_store_dwordx4 v[74:75], v[60:63], off offset:512 nt
	v_cvt_pk_bf16_f32 v21, v62, v63
	global_store_dwordx2 v[16:17], v[20:21], off offset:256
	v_mul_f32_e32 v20, v61, v61
	v_fmac_f32_e32 v20, v60, v60
	v_fmac_f32_e32 v20, v62, v62
	v_fmac_f32_e32 v20, v63, v63
	v_add_f32_e32 v24, v24, v20
	v_pk_fma_f32 v[30:31], v[18:19], v[180:181], v[50:51]
	v_cvt_pk_bf16_f32 v20, v28, v29
	global_store_dwordx4 v[74:75], v[28:31], off offset:576 nt
	v_cvt_pk_bf16_f32 v21, v30, v31
	global_store_dwordx2 v[16:17], v[20:21], off offset:288
	v_mul_f32_e32 v16, v29, v29
	v_and_b32_e32 v20, 64, v197
	v_fmac_f32_e32 v16, v28, v28
	v_xor_b32_e32 v17, 16, v197
	v_add_u32_e32 v20, 64, v20
	v_fmac_f32_e32 v16, v30, v30
	v_cmp_lt_i32_e32 vcc, v17, v20
	v_fmac_f32_e32 v16, v31, v31
	v_add_f32_e32 v16, v24, v16
	v_cndmask_b32_e32 v17, v197, v17, vcc
	v_lshlrev_b32_e32 v17, 2, v17
	ds_bpermute_b32 v17, v17, v16
	v_readlane_b32 s73, v238, 7
	s_waitcnt lgkmcnt(0)
	v_add_f32_e32 v16, v16, v17
	v_xor_b32_e32 v17, 32, v197
	v_cmp_lt_i32_e32 vcc, v17, v20
	s_nop 1
	v_cndmask_b32_e32 v17, v197, v17, vcc
	v_lshlrev_b32_e32 v17, 2, v17
	ds_bpermute_b32 v17, v17, v16
	s_and_saveexec_b64 s[16:17], s[36:37]
	s_cbranch_execz .LBB0_1335
	v_ashrrev_i32_e32 v87, 31, v86
	s_waitcnt lgkmcnt(0)
	v_add_f32_e32 v20, v16, v17
	v_lshlrev_b64 v[16:17], 7, v[86:87]
	v_lshl_add_u64 v[16:17], s[14:15], 0, v[16:17]
	global_store_dword v[16:17], v20, off

; DEVI unsigned pk_bf16(float lo, float hi) { unsigned r; asm("v_cvt_pk_bf16_f32 %0, %1, %2" : "=v"(r) : "v"(lo), "v"(hi)); return r; }
;     DEVI void operator()(const f32x4 (&acc)[2][2][4][2], const Unit& u, int wr, int wc, int fr, int fq, const LAS float*) const {
;     ...
;         const int row0 = u.pm * BM + wr * 64 + fr, col0 = u.pn * BM + wc * 32 + 4 * fq;
;         f32x4 cur[2][2], nxt[2][2];
;         { const size_t ro = (size_t)row0 * ldc + col0;
; #pragma unroll
;           for (int bj = 0; bj < 2; ++bj)
; #pragma unroll
;               for (int n = 0; n < 2; ++n) cur[bj][n] = *(const f32x4*)(R + ro + bj * HALF + n * 16); }
; #pragma unroll
;         for (int idx = 0; idx < 8; ++idx) {
;             const int ai = idx >> 2, m = idx & 3;
;             const size_t ro = (size_t)(row0 + ai * HALF + m * 16) * ldc + col0;
;             if (idx + 1 < 8) { const int ai2 = (idx + 1) >> 2, m2 = (idx + 1) & 3; const size_t ro2 = (size_t)(row0 + ai2 * HALF + m2 * 16) * ldc + col0;
; #pragma unroll
;                 for (int bj = 0; bj < 2; ++bj)
; #pragma unroll
;                     for (int n = 0; n < 2; ++n) nxt[bj][n] = *(const f32x4*)(R + ro2 + bj * HALF + n * 16); }
;             float ss = 0.f;
; #pragma unroll
;             for (int bj = 0; bj < 2; ++bj)
; #pragma unroll
;                 for (int n = 0; n < 2; ++n) {
;                     const f32x4 hn = cur[bj][n] + acc[ai][bj][m][n] * scale;
;                     *(f32x4*)(C + ro + bj * HALF + n * 16) = hn;
;                     if (HB) { u32x2 w; w.x = pk_bf16(hn[0], hn[1]); w.y = pk_bf16(hn[2], hn[3]); *(u32x2*)(HB + ro + bj * HALF + n * 16) = w;
;                         ss += hn[0] * hn[0] + hn[1] * hn[1] + hn[2] * hn[2] + hn[3] * hn[3]; } }
;             if (HB) { ss += __shfl_xor(ss, 16); ss += __shfl_xor(ss, 32); if (fq == 0) RS[(size_t)(row0 + ai * HALF + m * 16) * 32 + u.pn * 4 + wc] = ss; }
.LBB0_1576:
	v_readlane_b32 s84, v239, 50
	v_readlane_b32 s85, v239, 51
	v_readlane_b32 s86, v239, 52
	v_readlane_b32 s87, v239, 53
	v_lshl_add_u32 v188, s35, 8, v198
	v_lshl_or_b32 v182, s31, 8, v200
	s_mov_b32 s70, s86
	v_readlane_b32 s84, v238, 11
	v_mad_i64_i32 v[128:129], s[14:15], v188, s70, 0
	v_ashrrev_i32_e32 v183, 31, v182
	v_readlane_b32 s90, v238, 17
	v_readlane_b32 s91, v238, 18
	v_lshlrev_b64 v[130:131], 2, v[182:183]
	v_or_b32_e32 v190, 16, v188
	v_lshl_add_u64 v[128:129], v[128:129], 2, s[90:91]
	v_mov_b32_e32 v180, v204
	v_lshl_add_u64 v[128:129], v[128:129], 0, v[130:131]
	v_lshl_add_u64 v[186:187], s[90:91], 0, v[130:131]
	v_mad_i64_i32 v[192:193], s[16:17], v190, s70, 0
	global_load_dwordx4 v[160:163], v[128:129], off nt
	global_load_dwordx4 v[152:155], v[128:129], off offset:64 nt
	global_load_dwordx4 v[148:151], v[128:129], off offset:512 nt
	global_load_dwordx4 v[144:147], v[128:129], off offset:576 nt
	v_lshl_add_u64 v[128:129], v[192:193], 2, v[186:187]
	global_load_dwordx4 v[140:143], v[128:129], off nt
	global_load_dwordx4 v[136:139], v[128:129], off offset:64 nt
	global_load_dwordx4 v[132:135], v[128:129], off offset:512 nt
	s_nop 0
	global_load_dwordx4 v[128:131], v[128:129], off offset:576 nt
	s_lshl_b32 s14, s31, 2
	s_ashr_i32 s15, s14, 31
	s_lshl_b64 s[14:15], s[14:15], 2
	v_readlane_b32 s88, v238, 15
	v_readlane_b32 s89, v238, 16
	v_mov_b32_e32 v184, v180
	v_mov_b32_e32 v185, v180
	s_add_u32 s14, s4, s14
	v_mad_i64_i32 v[158:159], s[16:17], v188, s70, v[182:183]
	v_ashrrev_i32_e32 v189, 31, v188
	s_addc_u32 s15, s5, s15
	v_lshl_add_u64 v[194:195], v[158:159], 2, s[88:89]
	s_andn2_b64 vcc, exec, s[66:67]
	v_readlane_b32 s85, v238, 12
	v_readlane_b32 s86, v238, 13
	v_readlane_b32 s87, v238, 14
	s_waitcnt vmcnt(0)
	v_pk_fma_f32 v[164:165], v[126:127], v[180:181], v[162:163] op_sel_hi:[1,0,1]
	v_pk_fma_f32 v[162:163], v[124:125], v[180:181], v[160:161] op_sel_hi:[1,0,1]
	v_cndmask_b32_e64 v124, 0, 1, s[66:67]
	v_cmp_ne_u32_e64 s[40:41], 1, v124
	v_pk_fma_f32 v[160:161], v[120:121], v[184:185], v[152:153]
	v_pk_fma_f32 v[156:157], v[116:117], v[184:185], v[148:149]
	v_pk_fma_f32 v[124:125], v[112:113], v[184:185], v[144:145]
	global_store_dwordx4 v[194:195], v[162:165], off nt
	s_cbranch_vccnz .LBB0_1615
	v_readlane_b32 s84, v238, 19
	v_readlane_b32 s86, v238, 21
	v_readlane_b32 s87, v238, 22
	v_cvt_pk_bf16_f32 v116, v162, v163
	v_mul_f32_e32 v120, v163, v163
	v_mov_b32_e32 v181, v180
	v_lshl_add_u64 v[112:113], v[158:159], 1, s[86:87]
	v_cvt_pk_bf16_f32 v117, v164, v165
	global_store_dwordx2 v[112:113], v[116:117], off
	v_fmac_f32_e32 v120, v162, v162
	v_pk_fma_f32 v[162:163], v[122:123], v[180:181], v[154:155]
	v_cvt_pk_bf16_f32 v116, v160, v161
	global_store_dwordx4 v[194:195], v[160:163], off offset:64 nt
	v_cvt_pk_bf16_f32 v117, v162, v163
	global_store_dwordx2 v[112:113], v[116:117], off offset:32
	v_mul_f32_e32 v116, v161, v161
	v_fmac_f32_e32 v116, v160, v160
	v_fmac_f32_e32 v120, v164, v164
	v_fmac_f32_e32 v116, v162, v162
	v_fmac_f32_e32 v120, v165, v165
	v_fmac_f32_e32 v116, v163, v163
	v_add_f32_e32 v120, v120, v116
	v_pk_fma_f32 v[158:159], v[118:119], v[180:181], v[150:151]
	v_cvt_pk_bf16_f32 v116, v156, v157
	global_store_dwordx4 v[194:195], v[156:159], off offset:512 nt
	v_cvt_pk_bf16_f32 v117, v158, v159
	global_store_dwordx2 v[112:113], v[116:117], off offset:256
	v_mul_f32_e32 v116, v157, v157
	v_fmac_f32_e32 v116, v156, v156
	v_fmac_f32_e32 v116, v158, v158
	v_fmac_f32_e32 v116, v159, v159
	v_add_f32_e32 v120, v116, v120
	v_pk_fma_f32 v[126:127], v[114:115], v[180:181], v[146:147]
	v_cvt_pk_bf16_f32 v116, v124, v125
	global_store_dwordx4 v[194:195], v[124:127], off offset:576 nt
	v_cvt_pk_bf16_f32 v117, v126, v127
	global_store_dwordx2 v[112:113], v[116:117], off offset:288
	v_mul_f32_e32 v112, v125, v125
	v_and_b32_e32 v116, 64, v197
	v_fmac_f32_e32 v112, v124, v124
	v_xor_b32_e32 v113, 16, v197
	v_add_u32_e32 v116, 64, v116
	v_fmac_f32_e32 v112, v126, v126
	v_cmp_lt_i32_e32 vcc, v113, v116
	v_fmac_f32_e32 v112, v127, v127
	v_add_f32_e32 v112, v112, v120
	v_cndmask_b32_e32 v113, v197, v113, vcc
	v_lshlrev_b32_e32 v113, 2, v113
	ds_bpermute_b32 v113, v113, v112
	v_readlane_b32 s85, v238, 20
	s_waitcnt lgkmcnt(0)
	v_add_f32_e32 v112, v112, v113
	v_xor_b32_e32 v113, 32, v197
	v_cmp_lt_i32_e32 vcc, v113, v116
	s_nop 1
	v_cndmask_b32_e32 v113, v197, v113, vcc
	v_lshlrev_b32_e32 v113, 2, v113
	ds_bpermute_b32 v113, v113, v112
	s_and_saveexec_b64 s[16:17], s[36:37]
	s_cbranch_execz .LBB0_1579
	s_waitcnt lgkmcnt(0)
	v_add_f32_e32 v116, v112, v113
	v_lshlrev_b64 v[112:113], 7, v[188:189]
	v_lshl_add_u64 v[112:113], s[14:15], 0, v[112:113]
	global_store_dword v[112:113], v116, off

; DEVI unsigned pk_bf16(float lo, float hi) { unsigned r; asm("v_cvt_pk_bf16_f32 %0, %1, %2" : "=v"(r) : "v"(lo), "v"(hi)); return r; }
;     DEVI void operator()(const f32x4 (&acc)[2][2][4][2], const Unit& u, int wr, int wc, int fr, int fq, const LAS float*) const {
;     ...
;             const int ai = idx >> 2, m = idx & 3;
;             const size_t ro = (size_t)(row0 + ai * HALF + m * 16) * ldc + col0;
;             if (idx + 1 < 8) { const int ai2 = (idx + 1) >> 2, m2 = (idx + 1) & 3; const size_t ro2 = (size_t)(row0 + ai2 * HALF + m2 * 16) * ldc + col0;
; #pragma unroll
;                 for (int bj = 0; bj < 2; ++bj)
; #pragma unroll
;                     for (int n = 0; n < 2; ++n) nxt[bj][n] = *(const f32x4*)(R + ro2 + bj * HALF + n * 16); }
;             float ss = 0.f;
; #pragma unroll
;             for (int bj = 0; bj < 2; ++bj)
; #pragma unroll
;                 for (int n = 0; n < 2; ++n) {
;                     const f32x4 hn = cur[bj][n] + acc[ai][bj][m][n] * scale;
;                     *(f32x4*)(C + ro + bj * HALF + n * 16) = hn;
;                     if (HB) { u32x2 w; w.x = pk_bf16(hn[0], hn[1]); w.y = pk_bf16(hn[2], hn[3]); *(u32x2*)(HB + ro + bj * HALF + n * 16) = w;
;                         ss += hn[0] * hn[0] + hn[1] * hn[1] + hn[2] * hn[2] + hn[3] * hn[3]; } }
;             if (HB) { ss += __shfl_xor(ss, 16); ss += __shfl_xor(ss, 32); if (fq == 0) RS[(size_t)(row0 + ai * HALF + m * 16) * 32 + u.pn * 4 + wc] = ss; }
.LBB0_1581:
	v_readlane_b32 s84, v239, 50
	v_or_b32_e32 v150, 32, v188
	v_readlane_b32 s86, v239, 52
	v_readlane_b32 s85, v239, 51
	v_readlane_b32 s87, v239, 53
	v_mad_i64_i32 v[152:153], s[16:17], v150, s86, 0
	s_waitcnt lgkmcnt(0)
	v_lshl_add_u64 v[112:113], v[152:153], 2, v[186:187]
	global_load_dwordx4 v[124:127], v[112:113], off nt
	global_load_dwordx4 v[120:123], v[112:113], off offset:64 nt
	global_load_dwordx4 v[116:119], v[112:113], off offset:512 nt
	s_nop 0
	global_load_dwordx4 v[112:115], v[112:113], off offset:576 nt
	v_readlane_b32 s84, v238, 11
	v_lshl_add_u64 v[156:157], v[192:193], 0, v[182:183]
	v_readlane_b32 s88, v238, 15
	v_readlane_b32 s89, v238, 16
	v_mov_b32_e32 v181, v180
	v_pk_fma_f32 v[148:149], v[110:111], v[180:181], v[142:143]
	v_lshl_add_u64 v[154:155], v[156:157], 2, s[88:89]
	v_pk_fma_f32 v[146:147], v[108:109], v[184:185], v[140:141]
	s_and_b64 vcc, exec, s[40:41]
	v_pk_fma_f32 v[144:145], v[104:105], v[184:185], v[136:137]
	v_pk_fma_f32 v[140:141], v[100:101], v[184:185], v[132:133]
	v_pk_fma_f32 v[108:109], v[96:97], v[184:185], v[128:129]
	v_readlane_b32 s85, v238, 12
	v_readlane_b32 s86, v238, 13
	v_readlane_b32 s87, v238, 14
	v_readlane_b32 s90, v238, 17
	v_readlane_b32 s91, v238, 18
	global_store_dwordx4 v[154:155], v[146:149], off nt
	s_cbranch_vccnz .LBB0_1616
	v_readlane_b32 s84, v238, 19
	v_readlane_b32 s86, v238, 21
	v_readlane_b32 s87, v238, 22
	v_cvt_pk_bf16_f32 v100, v146, v147
	v_mul_f32_e32 v104, v147, v147
	v_cvt_pk_bf16_f32 v101, v148, v149
	v_fmac_f32_e32 v104, v146, v146
	v_lshl_add_u64 v[96:97], v[156:157], 1, s[86:87]
	global_store_dwordx2 v[96:97], v[100:101], off
	v_pk_fma_f32 v[146:147], v[106:107], v[180:181], v[138:139]
	v_cvt_pk_bf16_f32 v100, v144, v145
	global_store_dwordx4 v[154:155], v[144:147], off offset:64 nt
	v_cvt_pk_bf16_f32 v101, v146, v147
	global_store_dwordx2 v[96:97], v[100:101], off offset:32
	v_mul_f32_e32 v100, v145, v145
	v_fmac_f32_e32 v100, v144, v144
	v_fmac_f32_e32 v104, v148, v148
	v_fmac_f32_e32 v100, v146, v146
	v_fmac_f32_e32 v104, v149, v149
	v_fmac_f32_e32 v100, v147, v147
	v_add_f32_e32 v104, v104, v100
	v_pk_fma_f32 v[142:143], v[102:103], v[180:181], v[134:135]
	v_cvt_pk_bf16_f32 v100, v140, v141
	global_store_dwordx4 v[154:155], v[140:143], off offset:512 nt
	v_cvt_pk_bf16_f32 v101, v142, v143
	global_store_dwordx2 v[96:97], v[100:101], off offset:256
	v_mul_f32_e32 v100, v141, v141
	v_fmac_f32_e32 v100, v140, v140
	v_fmac_f32_e32 v100, v142, v142
	v_fmac_f32_e32 v100, v143, v143
	v_add_f32_e32 v104, v104, v100
	v_pk_fma_f32 v[110:111], v[98:99], v[180:181], v[130:131]
	v_cvt_pk_bf16_f32 v100, v108, v109
	global_store_dwordx4 v[154:155], v[108:111], off offset:576 nt
	v_cvt_pk_bf16_f32 v101, v110, v111
	global_store_dwordx2 v[96:97], v[100:101], off offset:288
	v_mul_f32_e32 v96, v109, v109
	v_and_b32_e32 v100, 64, v197
	v_fmac_f32_e32 v96, v108, v108
	v_xor_b32_e32 v97, 16, v197
	v_add_u32_e32 v100, 64, v100
	v_fmac_f32_e32 v96, v110, v110
	v_cmp_lt_i32_e32 vcc, v97, v100
	v_fmac_f32_e32 v96, v111, v111
	v_add_f32_e32 v96, v104, v96
	v_cndmask_b32_e32 v97, v197, v97, vcc
	v_lshlrev_b32_e32 v97, 2, v97
	ds_bpermute_b32 v97, v97, v96
	v_readlane_b32 s85, v238, 20
	s_waitcnt lgkmcnt(0)
	v_add_f32_e32 v96, v96, v97
	v_xor_b32_e32 v97, 32, v197
	v_cmp_lt_i32_e32 vcc, v97, v100
	s_nop 1
	v_cndmask_b32_e32 v97, v197, v97, vcc
	v_lshlrev_b32_e32 v97, 2, v97
	ds_bpermute_b32 v97, v97, v96
	s_and_saveexec_b64 s[16:17], s[36:37]
	s_cbranch_execz .LBB0_1584
	v_ashrrev_i32_e32 v191, 31, v190
	s_waitcnt lgkmcnt(0)
	v_add_f32_e32 v100, v96, v97
	v_lshlrev_b64 v[96:97], 7, v[190:191]
	v_lshl_add_u64 v[96:97], s[14:15], 0, v[96:97]
	global_store_dword v[96:97], v100, off

; DEVI unsigned pk_bf16(float lo, float hi) { unsigned r; asm("v_cvt_pk_bf16_f32 %0, %1, %2" : "=v"(r) : "v"(lo), "v"(hi)); return r; }
;     DEVI void operator()(const f32x4 (&acc)[2][2][4][2], const Unit& u, int wr, int wc, int fr, int fq, const LAS float*) const {
;     ...
;             const int ai = idx >> 2, m = idx & 3;
;             const size_t ro = (size_t)(row0 + ai * HALF + m * 16) * ldc + col0;
;             if (idx + 1 < 8) { const int ai2 = (idx + 1) >> 2, m2 = (idx + 1) & 3; const size_t ro2 = (size_t)(row0 + ai2 * HALF + m2 * 16) * ldc + col0;
; #pragma unroll
;                 for (int bj = 0; bj < 2; ++bj)
; #pragma unroll
;                     for (int n = 0; n < 2; ++n) nxt[bj][n] = *(const f32x4*)(R + ro2 + bj * HALF + n * 16); }
;             float ss = 0.f;
; #pragma unroll
;             for (int bj = 0; bj < 2; ++bj)
; #pragma unroll
;                 for (int n = 0; n < 2; ++n) {
;                     const f32x4 hn = cur[bj][n] + acc[ai][bj][m][n] * scale;
;                     *(f32x4*)(C + ro + bj * HALF + n * 16) = hn;
;                     if (HB) { u32x2 w; w.x = pk_bf16(hn[0], hn[1]); w.y = pk_bf16(hn[2], hn[3]); *(u32x2*)(HB + ro + bj * HALF + n * 16) = w;
;                         ss += hn[0] * hn[0] + hn[1] * hn[1] + hn[2] * hn[2] + hn[3] * hn[3]; } }
;             if (HB) { ss += __shfl_xor(ss, 16); ss += __shfl_xor(ss, 32); if (fq == 0) RS[(size_t)(row0 + ai * HALF + m * 16) * 32 + u.pn * 4 + wc] = ss; }
.LBB0_1586:
	v_readlane_b32 s84, v239, 50
	v_or_b32_e32 v134, 48, v188
	v_readlane_b32 s86, v239, 52
	v_readlane_b32 s85, v239, 51
	v_readlane_b32 s87, v239, 53
	v_mad_i64_i32 v[136:137], s[16:17], v134, s86, 0
	s_waitcnt lgkmcnt(0)
	v_lshl_add_u64 v[96:97], v[136:137], 2, v[186:187]
	global_load_dwordx4 v[108:111], v[96:97], off nt
	global_load_dwordx4 v[104:107], v[96:97], off offset:64 nt
	global_load_dwordx4 v[100:103], v[96:97], off offset:512 nt
	s_nop 0
	global_load_dwordx4 v[96:99], v[96:97], off offset:576 nt
	v_readlane_b32 s84, v238, 11
	v_lshl_add_u64 v[140:141], v[152:153], 0, v[182:183]
	v_readlane_b32 s88, v238, 15
	v_readlane_b32 s89, v238, 16
	v_mov_b32_e32 v181, v180
	s_waitcnt vmcnt(8)
	v_pk_fma_f32 v[132:133], v[94:95], v[180:181], v[126:127]
	v_lshl_add_u64 v[138:139], v[140:141], 2, s[88:89]
	v_pk_fma_f32 v[130:131], v[92:93], v[184:185], v[124:125]
	s_and_b64 vcc, exec, s[40:41]
	s_waitcnt vmcnt(7)
	v_pk_fma_f32 v[128:129], v[88:89], v[184:185], v[120:121]
	s_waitcnt vmcnt(6)
	v_pk_fma_f32 v[124:125], v[84:85], v[184:185], v[116:117]
	s_waitcnt vmcnt(5)
	v_pk_fma_f32 v[92:93], v[80:81], v[184:185], v[112:113]
	v_readlane_b32 s85, v238, 12
	v_readlane_b32 s86, v238, 13
	v_readlane_b32 s87, v238, 14
	v_readlane_b32 s90, v238, 17
	v_readlane_b32 s91, v238, 18
	global_store_dwordx4 v[138:139], v[130:133], off nt
	s_cbranch_vccnz .LBB0_1617
	v_readlane_b32 s84, v238, 19
	v_readlane_b32 s86, v238, 21
	v_readlane_b32 s87, v238, 22
	v_cvt_pk_bf16_f32 v84, v130, v131
	v_mul_f32_e32 v88, v131, v131
	v_cvt_pk_bf16_f32 v85, v132, v133
	v_fmac_f32_e32 v88, v130, v130
	v_lshl_add_u64 v[80:81], v[140:141], 1, s[86:87]
	global_store_dwordx2 v[80:81], v[84:85], off
	v_pk_fma_f32 v[130:131], v[90:91], v[180:181], v[122:123]
	v_cvt_pk_bf16_f32 v84, v128, v129
	global_store_dwordx4 v[138:139], v[128:131], off offset:64 nt
	v_cvt_pk_bf16_f32 v85, v130, v131
	global_store_dwordx2 v[80:81], v[84:85], off offset:32
	v_mul_f32_e32 v84, v129, v129
	v_fmac_f32_e32 v84, v128, v128
	v_fmac_f32_e32 v88, v132, v132
	v_fmac_f32_e32 v84, v130, v130
	v_fmac_f32_e32 v88, v133, v133
	v_fmac_f32_e32 v84, v131, v131
	v_add_f32_e32 v88, v88, v84
	v_pk_fma_f32 v[126:127], v[86:87], v[180:181], v[118:119]
	v_cvt_pk_bf16_f32 v84, v124, v125
	global_store_dwordx4 v[138:139], v[124:127], off offset:512 nt
	v_cvt_pk_bf16_f32 v85, v126, v127
	global_store_dwordx2 v[80:81], v[84:85], off offset:256
	v_mul_f32_e32 v84, v125, v125
	v_fmac_f32_e32 v84, v124, v124
	v_fmac_f32_e32 v84, v126, v126
	v_fmac_f32_e32 v84, v127, v127
	v_add_f32_e32 v88, v88, v84
	v_pk_fma_f32 v[94:95], v[82:83], v[180:181], v[114:115]
	v_cvt_pk_bf16_f32 v84, v92, v93
	global_store_dwordx4 v[138:139], v[92:95], off offset:576 nt
	v_cvt_pk_bf16_f32 v85, v94, v95
	global_store_dwordx2 v[80:81], v[84:85], off offset:288
	v_mul_f32_e32 v80, v93, v93
	v_and_b32_e32 v84, 64, v197
	v_fmac_f32_e32 v80, v92, v92
	v_xor_b32_e32 v81, 16, v197
	v_add_u32_e32 v84, 64, v84
	v_fmac_f32_e32 v80, v94, v94
	v_cmp_lt_i32_e32 vcc, v81, v84
	v_fmac_f32_e32 v80, v95, v95
	v_add_f32_e32 v80, v88, v80
	v_cndmask_b32_e32 v81, v197, v81, vcc
	v_lshlrev_b32_e32 v81, 2, v81
	ds_bpermute_b32 v81, v81, v80
	v_readlane_b32 s85, v238, 20
	s_waitcnt lgkmcnt(0)
	v_add_f32_e32 v80, v80, v81
	v_xor_b32_e32 v81, 32, v197
	v_cmp_lt_i32_e32 vcc, v81, v84
	s_nop 1
	v_cndmask_b32_e32 v81, v197, v81, vcc
	v_lshlrev_b32_e32 v81, 2, v81
	ds_bpermute_b32 v81, v81, v80
	s_and_saveexec_b64 s[16:17], s[36:37]
	s_cbranch_execz .LBB0_1589
	v_ashrrev_i32_e32 v151, 31, v150
	s_waitcnt lgkmcnt(0)
	v_add_f32_e32 v84, v80, v81
	v_lshlrev_b64 v[80:81], 7, v[150:151]
	v_lshl_add_u64 v[80:81], s[14:15], 0, v[80:81]
	global_store_dword v[80:81], v84, off

; DEVI unsigned pk_bf16(float lo, float hi) { unsigned r; asm("v_cvt_pk_bf16_f32 %0, %1, %2" : "=v"(r) : "v"(lo), "v"(hi)); return r; }
;     DEVI void operator()(const f32x4 (&acc)[2][2][4][2], const Unit& u, int wr, int wc, int fr, int fq, const LAS float*) const {
;     ...
;             const int ai = idx >> 2, m = idx & 3;
;             const size_t ro = (size_t)(row0 + ai * HALF + m * 16) * ldc + col0;
;             if (idx + 1 < 8) { const int ai2 = (idx + 1) >> 2, m2 = (idx + 1) & 3; const size_t ro2 = (size_t)(row0 + ai2 * HALF + m2 * 16) * ldc + col0;
; #pragma unroll
;                 for (int bj = 0; bj < 2; ++bj)
; #pragma unroll
;                     for (int n = 0; n < 2; ++n) nxt[bj][n] = *(const f32x4*)(R + ro2 + bj * HALF + n * 16); }
;             float ss = 0.f;
; #pragma unroll
;             for (int bj = 0; bj < 2; ++bj)
; #pragma unroll
;                 for (int n = 0; n < 2; ++n) {
;                     const f32x4 hn = cur[bj][n] + acc[ai][bj][m][n] * scale;
;                     *(f32x4*)(C + ro + bj * HALF + n * 16) = hn;
;                     if (HB) { u32x2 w; w.x = pk_bf16(hn[0], hn[1]); w.y = pk_bf16(hn[2], hn[3]); *(u32x2*)(HB + ro + bj * HALF + n * 16) = w;
;                         ss += hn[0] * hn[0] + hn[1] * hn[1] + hn[2] * hn[2] + hn[3] * hn[3]; } }
;             if (HB) { ss += __shfl_xor(ss, 16); ss += __shfl_xor(ss, 32); if (fq == 0) RS[(size_t)(row0 + ai * HALF + m * 16) * 32 + u.pn * 4 + wc] = ss; }
.LBB0_1591:
	v_readlane_b32 s84, v239, 50
	v_add_u32_e32 v118, 0x80, v188
	v_readlane_b32 s86, v239, 52
	v_readlane_b32 s85, v239, 51
	v_readlane_b32 s87, v239, 53
	v_mad_i64_i32 v[120:121], s[16:17], v118, s86, 0
	s_waitcnt lgkmcnt(0)
	v_lshl_add_u64 v[80:81], v[120:121], 2, v[186:187]
	global_load_dwordx4 v[92:95], v[80:81], off nt
	global_load_dwordx4 v[88:91], v[80:81], off offset:64 nt
	global_load_dwordx4 v[84:87], v[80:81], off offset:512 nt
	s_nop 0
	global_load_dwordx4 v[80:83], v[80:81], off offset:576 nt
	v_readlane_b32 s84, v238, 11
	v_lshl_add_u64 v[124:125], v[136:137], 0, v[182:183]
	v_readlane_b32 s88, v238, 15
	v_readlane_b32 s89, v238, 16
	v_mov_b32_e32 v181, v180
	s_waitcnt vmcnt(8)
	v_pk_fma_f32 v[116:117], v[78:79], v[180:181], v[110:111]
	v_lshl_add_u64 v[122:123], v[124:125], 2, s[88:89]
	v_pk_fma_f32 v[114:115], v[76:77], v[184:185], v[108:109]
	s_and_b64 vcc, exec, s[40:41]
	s_waitcnt vmcnt(7)
	v_pk_fma_f32 v[112:113], v[72:73], v[184:185], v[104:105]
	s_waitcnt vmcnt(6)
	v_pk_fma_f32 v[108:109], v[68:69], v[184:185], v[100:101]
	s_waitcnt vmcnt(5)
	v_pk_fma_f32 v[76:77], v[64:65], v[184:185], v[96:97]
	v_readlane_b32 s85, v238, 12
	v_readlane_b32 s86, v238, 13
	v_readlane_b32 s87, v238, 14
	v_readlane_b32 s90, v238, 17
	v_readlane_b32 s91, v238, 18
	global_store_dwordx4 v[122:123], v[114:117], off nt
	s_cbranch_vccnz .LBB0_1618
	v_readlane_b32 s84, v238, 19
	v_readlane_b32 s86, v238, 21
	v_readlane_b32 s87, v238, 22
	v_cvt_pk_bf16_f32 v68, v114, v115
	v_mul_f32_e32 v72, v115, v115
	v_cvt_pk_bf16_f32 v69, v116, v117
	v_fmac_f32_e32 v72, v114, v114
	v_lshl_add_u64 v[64:65], v[124:125], 1, s[86:87]
	global_store_dwordx2 v[64:65], v[68:69], off
	v_pk_fma_f32 v[114:115], v[74:75], v[180:181], v[106:107]
	v_cvt_pk_bf16_f32 v68, v112, v113
	global_store_dwordx4 v[122:123], v[112:115], off offset:64 nt
	v_cvt_pk_bf16_f32 v69, v114, v115
	global_store_dwordx2 v[64:65], v[68:69], off offset:32
	v_mul_f32_e32 v68, v113, v113
	v_fmac_f32_e32 v68, v112, v112
	v_fmac_f32_e32 v72, v116, v116
	v_fmac_f32_e32 v68, v114, v114
	v_fmac_f32_e32 v72, v117, v117
	v_fmac_f32_e32 v68, v115, v115
	v_add_f32_e32 v72, v72, v68
	v_pk_fma_f32 v[110:111], v[70:71], v[180:181], v[102:103]
	v_cvt_pk_bf16_f32 v68, v108, v109
	global_store_dwordx4 v[122:123], v[108:111], off offset:512 nt
	v_cvt_pk_bf16_f32 v69, v110, v111
	global_store_dwordx2 v[64:65], v[68:69], off offset:256
	v_mul_f32_e32 v68, v109, v109
	v_fmac_f32_e32 v68, v108, v108
	v_fmac_f32_e32 v68, v110, v110
	v_fmac_f32_e32 v68, v111, v111
	v_add_f32_e32 v72, v72, v68
	v_pk_fma_f32 v[78:79], v[66:67], v[180:181], v[98:99]
	v_cvt_pk_bf16_f32 v68, v76, v77
	global_store_dwordx4 v[122:123], v[76:79], off offset:576 nt
	v_cvt_pk_bf16_f32 v69, v78, v79
	global_store_dwordx2 v[64:65], v[68:69], off offset:288
	v_mul_f32_e32 v64, v77, v77
	v_and_b32_e32 v68, 64, v197
	v_fmac_f32_e32 v64, v76, v76
	v_xor_b32_e32 v65, 16, v197
	v_add_u32_e32 v68, 64, v68
	v_fmac_f32_e32 v64, v78, v78
	v_cmp_lt_i32_e32 vcc, v65, v68
	v_fmac_f32_e32 v64, v79, v79
	v_add_f32_e32 v64, v72, v64
	v_cndmask_b32_e32 v65, v197, v65, vcc
	v_lshlrev_b32_e32 v65, 2, v65
	ds_bpermute_b32 v65, v65, v64
	v_readlane_b32 s85, v238, 20
	s_waitcnt lgkmcnt(0)
	v_add_f32_e32 v64, v64, v65
	v_xor_b32_e32 v65, 32, v197
	v_cmp_lt_i32_e32 vcc, v65, v68
	s_nop 1
	v_cndmask_b32_e32 v65, v197, v65, vcc
	v_lshlrev_b32_e32 v65, 2, v65
	ds_bpermute_b32 v65, v65, v64
	s_and_saveexec_b64 s[16:17], s[36:37]
	s_cbranch_execz .LBB0_1594
	v_ashrrev_i32_e32 v135, 31, v134
	s_waitcnt lgkmcnt(0)
	v_add_f32_e32 v68, v64, v65
	v_lshlrev_b64 v[64:65], 7, v[134:135]
	v_lshl_add_u64 v[64:65], s[14:15], 0, v[64:65]
	global_store_dword v[64:65], v68, off

; DEVI unsigned pk_bf16(float lo, float hi) { unsigned r; asm("v_cvt_pk_bf16_f32 %0, %1, %2" : "=v"(r) : "v"(lo), "v"(hi)); return r; }
;     DEVI void operator()(const f32x4 (&acc)[2][2][4][2], const Unit& u, int wr, int wc, int fr, int fq, const LAS float*) const {
;     ...
;             const int ai = idx >> 2, m = idx & 3;
;             const size_t ro = (size_t)(row0 + ai * HALF + m * 16) * ldc + col0;
;             if (idx + 1 < 8) { const int ai2 = (idx + 1) >> 2, m2 = (idx + 1) & 3; const size_t ro2 = (size_t)(row0 + ai2 * HALF + m2 * 16) * ldc + col0;
; #pragma unroll
;                 for (int bj = 0; bj < 2; ++bj)
; #pragma unroll
;                     for (int n = 0; n < 2; ++n) nxt[bj][n] = *(const f32x4*)(R + ro2 + bj * HALF + n * 16); }
;             float ss = 0.f;
; #pragma unroll
;             for (int bj = 0; bj < 2; ++bj)
; #pragma unroll
;                 for (int n = 0; n < 2; ++n) {
;                     const f32x4 hn = cur[bj][n] + acc[ai][bj][m][n] * scale;
;                     *(f32x4*)(C + ro + bj * HALF + n * 16) = hn;
;                     if (HB) { u32x2 w; w.x = pk_bf16(hn[0], hn[1]); w.y = pk_bf16(hn[2], hn[3]); *(u32x2*)(HB + ro + bj * HALF + n * 16) = w;
;                         ss += hn[0] * hn[0] + hn[1] * hn[1] + hn[2] * hn[2] + hn[3] * hn[3]; } }
;             if (HB) { ss += __shfl_xor(ss, 16); ss += __shfl_xor(ss, 32); if (fq == 0) RS[(size_t)(row0 + ai * HALF + m * 16) * 32 + u.pn * 4 + wc] = ss; }
.LBB0_1596:
	v_readlane_b32 s84, v239, 50
	v_or_b32_e32 v102, 16, v118
	v_readlane_b32 s86, v239, 52
	v_readlane_b32 s85, v239, 51
	v_readlane_b32 s87, v239, 53
	v_mad_i64_i32 v[104:105], s[16:17], v102, s86, 0
	s_waitcnt lgkmcnt(0)
	v_lshl_add_u64 v[64:65], v[104:105], 2, v[186:187]
	global_load_dwordx4 v[76:79], v[64:65], off nt
	global_load_dwordx4 v[72:75], v[64:65], off offset:64 nt
	global_load_dwordx4 v[68:71], v[64:65], off offset:512 nt
	s_nop 0
	global_load_dwordx4 v[64:67], v[64:65], off offset:576 nt
	v_readlane_b32 s84, v238, 11
	v_lshl_add_u64 v[108:109], v[120:121], 0, v[182:183]
	v_readlane_b32 s88, v238, 15
	v_readlane_b32 s89, v238, 16
	v_mov_b32_e32 v181, v180
	v_ashrrev_i32_e32 v119, 31, v118
	v_lshl_add_u64 v[106:107], v[108:109], 2, s[88:89]
	s_waitcnt vmcnt(8)
	v_pk_fma_f32 v[100:101], v[62:63], v[180:181], v[94:95]
	v_pk_fma_f32 v[98:99], v[60:61], v[184:185], v[92:93]
	s_and_b64 vcc, exec, s[40:41]
	s_waitcnt vmcnt(7)
	v_pk_fma_f32 v[96:97], v[56:57], v[184:185], v[88:89]
	s_waitcnt vmcnt(6)
	v_pk_fma_f32 v[92:93], v[52:53], v[184:185], v[84:85]
	s_waitcnt vmcnt(5)
	v_pk_fma_f32 v[60:61], v[48:49], v[184:185], v[80:81]
	v_readlane_b32 s85, v238, 12
	v_readlane_b32 s86, v238, 13
	v_readlane_b32 s87, v238, 14
	v_readlane_b32 s90, v238, 17
	v_readlane_b32 s91, v238, 18
	global_store_dwordx4 v[106:107], v[98:101], off nt
	s_cbranch_vccnz .LBB0_1619
	v_readlane_b32 s84, v238, 19
	v_readlane_b32 s86, v238, 21
	v_readlane_b32 s87, v238, 22
	v_cvt_pk_bf16_f32 v52, v98, v99
	v_mul_f32_e32 v56, v99, v99
	v_cvt_pk_bf16_f32 v53, v100, v101
	v_fmac_f32_e32 v56, v98, v98
	v_lshl_add_u64 v[48:49], v[108:109], 1, s[86:87]
	global_store_dwordx2 v[48:49], v[52:53], off
	v_pk_fma_f32 v[98:99], v[58:59], v[180:181], v[90:91]
	v_cvt_pk_bf16_f32 v52, v96, v97
	global_store_dwordx4 v[106:107], v[96:99], off offset:64 nt
	v_cvt_pk_bf16_f32 v53, v98, v99
	global_store_dwordx2 v[48:49], v[52:53], off offset:32
	v_mul_f32_e32 v52, v97, v97
	v_fmac_f32_e32 v52, v96, v96
	v_fmac_f32_e32 v56, v100, v100
	v_fmac_f32_e32 v52, v98, v98
	v_fmac_f32_e32 v56, v101, v101
	v_fmac_f32_e32 v52, v99, v99
	v_add_f32_e32 v56, v56, v52
	v_pk_fma_f32 v[94:95], v[54:55], v[180:181], v[86:87]
	v_cvt_pk_bf16_f32 v52, v92, v93
	global_store_dwordx4 v[106:107], v[92:95], off offset:512 nt
	v_cvt_pk_bf16_f32 v53, v94, v95
	global_store_dwordx2 v[48:49], v[52:53], off offset:256
	v_mul_f32_e32 v52, v93, v93
	v_fmac_f32_e32 v52, v92, v92
	v_fmac_f32_e32 v52, v94, v94
	v_fmac_f32_e32 v52, v95, v95
	v_add_f32_e32 v56, v56, v52
	v_pk_fma_f32 v[62:63], v[50:51], v[180:181], v[82:83]
	v_cvt_pk_bf16_f32 v52, v60, v61
	global_store_dwordx4 v[106:107], v[60:63], off offset:576 nt
	v_cvt_pk_bf16_f32 v53, v62, v63
	global_store_dwordx2 v[48:49], v[52:53], off offset:288
	v_mul_f32_e32 v48, v61, v61
	v_and_b32_e32 v52, 64, v197
	v_fmac_f32_e32 v48, v60, v60
	v_xor_b32_e32 v49, 16, v197
	v_add_u32_e32 v52, 64, v52
	v_fmac_f32_e32 v48, v62, v62
	v_cmp_lt_i32_e32 vcc, v49, v52
	v_fmac_f32_e32 v48, v63, v63
	v_add_f32_e32 v48, v56, v48
	v_cndmask_b32_e32 v49, v197, v49, vcc
	v_lshlrev_b32_e32 v49, 2, v49
	ds_bpermute_b32 v49, v49, v48
	v_readlane_b32 s85, v238, 20
	s_waitcnt lgkmcnt(0)
	v_add_f32_e32 v48, v48, v49
	v_xor_b32_e32 v49, 32, v197
	v_cmp_lt_i32_e32 vcc, v49, v52
	s_nop 1
	v_cndmask_b32_e32 v49, v197, v49, vcc
	v_lshlrev_b32_e32 v49, 2, v49
	ds_bpermute_b32 v49, v49, v48
	s_and_saveexec_b64 s[16:17], s[36:37]
	s_cbranch_execz .LBB0_1599
	s_waitcnt lgkmcnt(0)
	v_add_f32_e32 v52, v48, v49
	v_lshlrev_b64 v[48:49], 7, v[118:119]
	v_lshl_add_u64 v[48:49], s[14:15], 0, v[48:49]
	global_store_dword v[48:49], v52, off

; DEVI unsigned pk_bf16(float lo, float hi) { unsigned r; asm("v_cvt_pk_bf16_f32 %0, %1, %2" : "=v"(r) : "v"(lo), "v"(hi)); return r; }
;     DEVI void operator()(const f32x4 (&acc)[2][2][4][2], const Unit& u, int wr, int wc, int fr, int fq, const LAS float*) const {
;     ...
;             const int ai = idx >> 2, m = idx & 3;
;             const size_t ro = (size_t)(row0 + ai * HALF + m * 16) * ldc + col0;
;             if (idx + 1 < 8) { const int ai2 = (idx + 1) >> 2, m2 = (idx + 1) & 3; const size_t ro2 = (size_t)(row0 + ai2 * HALF + m2 * 16) * ldc + col0;
; #pragma unroll
;                 for (int bj = 0; bj < 2; ++bj)
; #pragma unroll
;                     for (int n = 0; n < 2; ++n) nxt[bj][n] = *(const f32x4*)(R + ro2 + bj * HALF + n * 16); }
;             float ss = 0.f;
; #pragma unroll
;             for (int bj = 0; bj < 2; ++bj)
; #pragma unroll
;                 for (int n = 0; n < 2; ++n) {
;                     const f32x4 hn = cur[bj][n] + acc[ai][bj][m][n] * scale;
;                     *(f32x4*)(C + ro + bj * HALF + n * 16) = hn;
;                     if (HB) { u32x2 w; w.x = pk_bf16(hn[0], hn[1]); w.y = pk_bf16(hn[2], hn[3]); *(u32x2*)(HB + ro + bj * HALF + n * 16) = w;
;                         ss += hn[0] * hn[0] + hn[1] * hn[1] + hn[2] * hn[2] + hn[3] * hn[3]; } }
;             if (HB) { ss += __shfl_xor(ss, 16); ss += __shfl_xor(ss, 32); if (fq == 0) RS[(size_t)(row0 + ai * HALF + m * 16) * 32 + u.pn * 4 + wc] = ss; }
.LBB0_1601:
	v_readlane_b32 s84, v239, 50
	v_or_b32_e32 v86, 32, v118
	v_readlane_b32 s86, v239, 52
	v_readlane_b32 s85, v239, 51
	v_readlane_b32 s87, v239, 53
	v_mad_i64_i32 v[88:89], s[16:17], v86, s86, 0
	s_waitcnt lgkmcnt(0)
	v_lshl_add_u64 v[48:49], v[88:89], 2, v[186:187]
	global_load_dwordx4 v[60:63], v[48:49], off nt
	global_load_dwordx4 v[56:59], v[48:49], off offset:64 nt
	global_load_dwordx4 v[52:55], v[48:49], off offset:512 nt
	s_nop 0
	global_load_dwordx4 v[48:51], v[48:49], off offset:576 nt
	v_readlane_b32 s84, v238, 11
	v_lshl_add_u64 v[92:93], v[104:105], 0, v[182:183]
	v_readlane_b32 s88, v238, 15
	v_readlane_b32 s89, v238, 16
	v_mov_b32_e32 v181, v180
	s_waitcnt vmcnt(8)
	v_pk_fma_f32 v[84:85], v[46:47], v[180:181], v[78:79]
	v_lshl_add_u64 v[90:91], v[92:93], 2, s[88:89]
	v_pk_fma_f32 v[82:83], v[44:45], v[184:185], v[76:77]
	s_and_b64 vcc, exec, s[40:41]
	s_waitcnt vmcnt(7)
	v_pk_fma_f32 v[80:81], v[40:41], v[184:185], v[72:73]
	s_waitcnt vmcnt(6)
	v_pk_fma_f32 v[76:77], v[36:37], v[184:185], v[68:69]
	s_waitcnt vmcnt(5)
	v_pk_fma_f32 v[44:45], v[32:33], v[184:185], v[64:65]
	v_readlane_b32 s85, v238, 12
	v_readlane_b32 s86, v238, 13
	v_readlane_b32 s87, v238, 14
	v_readlane_b32 s90, v238, 17
	v_readlane_b32 s91, v238, 18
	global_store_dwordx4 v[90:91], v[82:85], off nt
	s_cbranch_vccnz .LBB0_1620
	v_readlane_b32 s84, v238, 19
	v_readlane_b32 s86, v238, 21
	v_readlane_b32 s87, v238, 22
	v_cvt_pk_bf16_f32 v36, v82, v83
	v_mul_f32_e32 v40, v83, v83
	v_cvt_pk_bf16_f32 v37, v84, v85
	v_fmac_f32_e32 v40, v82, v82
	v_lshl_add_u64 v[32:33], v[92:93], 1, s[86:87]
	global_store_dwordx2 v[32:33], v[36:37], off
	v_pk_fma_f32 v[82:83], v[42:43], v[180:181], v[74:75]
	v_cvt_pk_bf16_f32 v36, v80, v81
	global_store_dwordx4 v[90:91], v[80:83], off offset:64 nt
	v_cvt_pk_bf16_f32 v37, v82, v83
	global_store_dwordx2 v[32:33], v[36:37], off offset:32
	v_mul_f32_e32 v36, v81, v81
	v_fmac_f32_e32 v36, v80, v80
	v_fmac_f32_e32 v40, v84, v84
	v_fmac_f32_e32 v36, v82, v82
	v_fmac_f32_e32 v40, v85, v85
	v_fmac_f32_e32 v36, v83, v83
	v_add_f32_e32 v40, v40, v36
	v_pk_fma_f32 v[78:79], v[38:39], v[180:181], v[70:71]
	v_cvt_pk_bf16_f32 v36, v76, v77
	global_store_dwordx4 v[90:91], v[76:79], off offset:512 nt
	v_cvt_pk_bf16_f32 v37, v78, v79
	global_store_dwordx2 v[32:33], v[36:37], off offset:256
	v_mul_f32_e32 v36, v77, v77
	v_fmac_f32_e32 v36, v76, v76
	v_fmac_f32_e32 v36, v78, v78
	v_fmac_f32_e32 v36, v79, v79
	v_add_f32_e32 v40, v40, v36
	v_pk_fma_f32 v[46:47], v[34:35], v[180:181], v[66:67]
	v_cvt_pk_bf16_f32 v36, v44, v45
	global_store_dwordx4 v[90:91], v[44:47], off offset:576 nt
	v_cvt_pk_bf16_f32 v37, v46, v47
	global_store_dwordx2 v[32:33], v[36:37], off offset:288
	v_mul_f32_e32 v32, v45, v45
	v_and_b32_e32 v36, 64, v197
	v_fmac_f32_e32 v32, v44, v44
	v_xor_b32_e32 v33, 16, v197
	v_add_u32_e32 v36, 64, v36
	v_fmac_f32_e32 v32, v46, v46
	v_cmp_lt_i32_e32 vcc, v33, v36
	v_fmac_f32_e32 v32, v47, v47
	v_add_f32_e32 v32, v40, v32
	v_cndmask_b32_e32 v33, v197, v33, vcc
	v_lshlrev_b32_e32 v33, 2, v33
	ds_bpermute_b32 v33, v33, v32
	v_readlane_b32 s85, v238, 20
	s_waitcnt lgkmcnt(0)
	v_add_f32_e32 v32, v32, v33
	v_xor_b32_e32 v33, 32, v197
	v_cmp_lt_i32_e32 vcc, v33, v36
	s_nop 1
	v_cndmask_b32_e32 v33, v197, v33, vcc
	v_lshlrev_b32_e32 v33, 2, v33
	ds_bpermute_b32 v33, v33, v32
	s_and_saveexec_b64 s[16:17], s[36:37]
	s_cbranch_execz .LBB0_1604
	v_ashrrev_i32_e32 v103, 31, v102
	s_waitcnt lgkmcnt(0)
	v_add_f32_e32 v36, v32, v33
	v_lshlrev_b64 v[32:33], 7, v[102:103]
	v_lshl_add_u64 v[32:33], s[14:15], 0, v[32:33]
	global_store_dword v[32:33], v36, off

; DEVI unsigned pk_bf16(float lo, float hi) { unsigned r; asm("v_cvt_pk_bf16_f32 %0, %1, %2" : "=v"(r) : "v"(lo), "v"(hi)); return r; }
;     DEVI void operator()(const f32x4 (&acc)[2][2][4][2], const Unit& u, int wr, int wc, int fr, int fq, const LAS float*) const {
;     ...
;             const int ai = idx >> 2, m = idx & 3;
;             const size_t ro = (size_t)(row0 + ai * HALF + m * 16) * ldc + col0;
;             if (idx + 1 < 8) { const int ai2 = (idx + 1) >> 2, m2 = (idx + 1) & 3; const size_t ro2 = (size_t)(row0 + ai2 * HALF + m2 * 16) * ldc + col0;
; #pragma unroll
;                 for (int bj = 0; bj < 2; ++bj)
; #pragma unroll
;                     for (int n = 0; n < 2; ++n) nxt[bj][n] = *(const f32x4*)(R + ro2 + bj * HALF + n * 16); }
;             float ss = 0.f;
; #pragma unroll
;             for (int bj = 0; bj < 2; ++bj)
; #pragma unroll
;                 for (int n = 0; n < 2; ++n) {
;                     const f32x4 hn = cur[bj][n] + acc[ai][bj][m][n] * scale;
;                     *(f32x4*)(C + ro + bj * HALF + n * 16) = hn;
;                     if (HB) { u32x2 w; w.x = pk_bf16(hn[0], hn[1]); w.y = pk_bf16(hn[2], hn[3]); *(u32x2*)(HB + ro + bj * HALF + n * 16) = w;
;                         ss += hn[0] * hn[0] + hn[1] * hn[1] + hn[2] * hn[2] + hn[3] * hn[3]; } }
;             if (HB) { ss += __shfl_xor(ss, 16); ss += __shfl_xor(ss, 32); if (fq == 0) RS[(size_t)(row0 + ai * HALF + m * 16) * 32 + u.pn * 4 + wc] = ss; }
.LBB0_1606:
	v_readlane_b32 s84, v239, 50
	v_or_b32_e32 v70, 48, v118
	v_readlane_b32 s86, v239, 52
	v_readlane_b32 s85, v239, 51
	v_readlane_b32 s87, v239, 53
	v_mad_i64_i32 v[72:73], s[16:17], v70, s86, 0
	s_waitcnt lgkmcnt(0)
	v_lshl_add_u64 v[32:33], v[72:73], 2, v[186:187]
	global_load_dwordx4 v[44:47], v[32:33], off nt
	global_load_dwordx4 v[40:43], v[32:33], off offset:64 nt
	global_load_dwordx4 v[36:39], v[32:33], off offset:512 nt
	s_nop 0
	global_load_dwordx4 v[32:35], v[32:33], off offset:576 nt
	v_readlane_b32 s84, v238, 11
	v_lshl_add_u64 v[76:77], v[88:89], 0, v[182:183]
	v_readlane_b32 s88, v238, 15
	v_readlane_b32 s89, v238, 16
	v_mov_b32_e32 v181, v180
	s_waitcnt vmcnt(8)
	v_pk_fma_f32 v[68:69], v[30:31], v[180:181], v[62:63]
	v_lshl_add_u64 v[74:75], v[76:77], 2, s[88:89]
	v_pk_fma_f32 v[66:67], v[28:29], v[184:185], v[60:61]
	s_and_b64 vcc, exec, s[40:41]
	s_waitcnt vmcnt(7)
	v_pk_fma_f32 v[64:65], v[24:25], v[184:185], v[56:57]
	s_waitcnt vmcnt(6)
	v_pk_fma_f32 v[60:61], v[20:21], v[184:185], v[52:53]
	s_waitcnt vmcnt(5)
	v_pk_fma_f32 v[28:29], v[16:17], v[184:185], v[48:49]
	v_readlane_b32 s85, v238, 12
	v_readlane_b32 s86, v238, 13
	v_readlane_b32 s87, v238, 14
	v_readlane_b32 s90, v238, 17
	v_readlane_b32 s91, v238, 18
	global_store_dwordx4 v[74:75], v[66:69], off nt
	s_cbranch_vccnz .LBB0_1621
	v_readlane_b32 s84, v238, 19
	v_readlane_b32 s86, v238, 21
	v_readlane_b32 s87, v238, 22
	v_cvt_pk_bf16_f32 v20, v66, v67
	v_mul_f32_e32 v24, v67, v67
	v_cvt_pk_bf16_f32 v21, v68, v69
	v_fmac_f32_e32 v24, v66, v66
	v_lshl_add_u64 v[16:17], v[76:77], 1, s[86:87]
	global_store_dwordx2 v[16:17], v[20:21], off
	v_pk_fma_f32 v[66:67], v[26:27], v[180:181], v[58:59]
	v_cvt_pk_bf16_f32 v20, v64, v65
	global_store_dwordx4 v[74:75], v[64:67], off offset:64 nt
	v_cvt_pk_bf16_f32 v21, v66, v67
	global_store_dwordx2 v[16:17], v[20:21], off offset:32
	v_mul_f32_e32 v20, v65, v65
	v_fmac_f32_e32 v20, v64, v64
	v_fmac_f32_e32 v24, v68, v68
	v_fmac_f32_e32 v20, v66, v66
	v_fmac_f32_e32 v24, v69, v69
	v_fmac_f32_e32 v20, v67, v67
	v_add_f32_e32 v24, v24, v20
	v_pk_fma_f32 v[62:63], v[22:23], v[180:181], v[54:55]
	v_cvt_pk_bf16_f32 v20, v60, v61
	global_store_dwordx4 v[74:75], v[60:63], off offset:512 nt
	v_cvt_pk_bf16_f32 v21, v62, v63
	global_store_dwordx2 v[16:17], v[20:21], off offset:256
	v_mul_f32_e32 v20, v61, v61
	v_fmac_f32_e32 v20, v60, v60
	v_fmac_f32_e32 v20, v62, v62
	v_fmac_f32_e32 v20, v63, v63
	v_add_f32_e32 v24, v24, v20
	v_pk_fma_f32 v[30:31], v[18:19], v[180:181], v[50:51]
	v_cvt_pk_bf16_f32 v20, v28, v29
	global_store_dwordx4 v[74:75], v[28:31], off offset:576 nt
	v_cvt_pk_bf16_f32 v21, v30, v31
	global_store_dwordx2 v[16:17], v[20:21], off offset:288
	v_mul_f32_e32 v16, v29, v29
	v_and_b32_e32 v20, 64, v197
	v_fmac_f32_e32 v16, v28, v28
	v_xor_b32_e32 v17, 16, v197
	v_add_u32_e32 v20, 64, v20
	v_fmac_f32_e32 v16, v30, v30
	v_cmp_lt_i32_e32 vcc, v17, v20
	v_fmac_f32_e32 v16, v31, v31
	v_add_f32_e32 v16, v24, v16
	v_cndmask_b32_e32 v17, v197, v17, vcc
	v_lshlrev_b32_e32 v17, 2, v17
	ds_bpermute_b32 v17, v17, v16
	v_readlane_b32 s85, v238, 20
	s_waitcnt lgkmcnt(0)
	v_add_f32_e32 v16, v16, v17
	v_xor_b32_e32 v17, 32, v197
	v_cmp_lt_i32_e32 vcc, v17, v20
	s_nop 1
	v_cndmask_b32_e32 v17, v197, v17, vcc
	v_lshlrev_b32_e32 v17, 2, v17
	ds_bpermute_b32 v17, v17, v16
	s_and_saveexec_b64 s[16:17], s[36:37]
	s_cbranch_execz .LBB0_1609
	v_ashrrev_i32_e32 v87, 31, v86
	s_waitcnt lgkmcnt(0)
	v_add_f32_e32 v20, v16, v17
	v_lshlrev_b64 v[16:17], 7, v[86:87]
	v_lshl_add_u64 v[16:17], s[14:15], 0, v[16:17]
	global_store_dword v[16:17], v20, off

; DEVI unsigned pk_bf16(float lo, float hi) { unsigned r; asm("v_cvt_pk_bf16_f32 %0, %1, %2" : "=v"(r) : "v"(lo), "v"(hi)); return r; }
;     DEVI void operator()(const f32x4 (&acc)[2][2][4][2], const Unit& u, int wr, int wc, int fr, int fq, const LAS float*) const {
;     ...
;         const int row0 = u.pm * BM + wr * 64 + fr, col0 = u.pn * BM + wc * 32 + 4 * fq;
;         f32x4 cur[2][2], nxt[2][2];
;         { const size_t ro = (size_t)row0 * ldc + col0;
; #pragma unroll
;           for (int bj = 0; bj < 2; ++bj)
; #pragma unroll
;               for (int n = 0; n < 2; ++n) cur[bj][n] = *(const f32x4*)(R + ro + bj * HALF + n * 16); }
; #pragma unroll
;         for (int idx = 0; idx < 8; ++idx) {
;             const int ai = idx >> 2, m = idx & 3;
;             const size_t ro = (size_t)(row0 + ai * HALF + m * 16) * ldc + col0;
;             if (idx + 1 < 8) { const int ai2 = (idx + 1) >> 2, m2 = (idx + 1) & 3; const size_t ro2 = (size_t)(row0 + ai2 * HALF + m2 * 16) * ldc + col0;
; #pragma unroll
;                 for (int bj = 0; bj < 2; ++bj)
; #pragma unroll
;                     for (int n = 0; n < 2; ++n) nxt[bj][n] = *(const f32x4*)(R + ro2 + bj * HALF + n * 16); }
;             float ss = 0.f;
; #pragma unroll
;             for (int bj = 0; bj < 2; ++bj)
; #pragma unroll
;                 for (int n = 0; n < 2; ++n) {
;                     const f32x4 hn = cur[bj][n] + acc[ai][bj][m][n] * scale;
;                     *(f32x4*)(C + ro + bj * HALF + n * 16) = hn;
;                     if (HB) { u32x2 w; w.x = pk_bf16(hn[0], hn[1]); w.y = pk_bf16(hn[2], hn[3]); *(u32x2*)(HB + ro + bj * HALF + n * 16) = w;
;                         ss += hn[0] * hn[0] + hn[1] * hn[1] + hn[2] * hn[2] + hn[3] * hn[3]; } }
;             if (HB) { ss += __shfl_xor(ss, 16); ss += __shfl_xor(ss, 32); if (fq == 0) RS[(size_t)(row0 + ai * HALF + m * 16) * 32 + u.pn * 4 + wc] = ss; }
.LBB0_1850:
	v_lshl_add_u32 v188, s63, 8, v198
	v_lshl_or_b32 v182, s31, 8, v200
	v_readlane_b32 s84, v238, 24
	v_mad_i64_i32 v[128:129], s[14:15], v188, s66, 0
	v_ashrrev_i32_e32 v183, 31, v182
	v_readlane_b32 s90, v238, 30
	v_readlane_b32 s91, v238, 31
	v_lshlrev_b64 v[130:131], 2, v[182:183]
	v_or_b32_e32 v190, 16, v188
	v_lshl_add_u64 v[128:129], v[128:129], 2, s[90:91]
	v_mov_b32_e32 v180, v204
	v_lshl_add_u64 v[128:129], v[128:129], 0, v[130:131]
	v_lshl_add_u64 v[186:187], s[90:91], 0, v[130:131]
	v_mad_i64_i32 v[192:193], s[16:17], v190, s66, 0
	global_load_dwordx4 v[160:163], v[128:129], off nt
	global_load_dwordx4 v[152:155], v[128:129], off offset:64 nt
	global_load_dwordx4 v[148:151], v[128:129], off offset:512 nt
	global_load_dwordx4 v[140:143], v[128:129], off offset:576 nt
	v_lshl_add_u64 v[128:129], v[192:193], 2, v[186:187]
	global_load_dwordx4 v[144:147], v[128:129], off nt
	global_load_dwordx4 v[136:139], v[128:129], off offset:64 nt
	global_load_dwordx4 v[132:135], v[128:129], off offset:512 nt
	s_nop 0
	global_load_dwordx4 v[128:131], v[128:129], off offset:576 nt
	s_lshl_b32 s14, s31, 2
	s_ashr_i32 s15, s14, 31
	s_lshl_b64 s[14:15], s[14:15], 2
	v_readlane_b32 s88, v238, 28
	v_readlane_b32 s89, v238, 29
	v_mov_b32_e32 v184, v180
	v_mov_b32_e32 v185, v180
	s_add_u32 s14, s4, s14
	v_mad_i64_i32 v[158:159], s[16:17], v188, s66, v[182:183]
	v_ashrrev_i32_e32 v189, 31, v188
	s_addc_u32 s15, s5, s15
	v_lshl_add_u64 v[194:195], v[158:159], 2, s[88:89]
	s_andn2_b64 vcc, exec, s[54:55]
	v_readlane_b32 s85, v238, 25
	v_readlane_b32 s86, v238, 26
	v_readlane_b32 s87, v238, 27
	s_waitcnt vmcnt(0)
	v_pk_fma_f32 v[164:165], v[126:127], v[180:181], v[162:163] op_sel_hi:[1,0,1]
	v_pk_fma_f32 v[162:163], v[124:125], v[180:181], v[160:161] op_sel_hi:[1,0,1]
	v_cndmask_b32_e64 v124, 0, 1, s[54:55]
	v_cmp_ne_u32_e64 s[38:39], 1, v124
	v_pk_fma_f32 v[160:161], v[120:121], v[184:185], v[152:153]
	v_pk_fma_f32 v[156:157], v[116:117], v[184:185], v[148:149]
	v_pk_fma_f32 v[124:125], v[112:113], v[184:185], v[140:141]
	global_store_dwordx4 v[194:195], v[162:165], off nt
	s_cbranch_vccnz .LBB0_1889
	v_readlane_b32 s84, v238, 32
	v_readlane_b32 s86, v238, 34
	v_readlane_b32 s87, v238, 35
	v_cvt_pk_bf16_f32 v116, v162, v163
	v_mul_f32_e32 v120, v163, v163
	v_mov_b32_e32 v181, v180
	v_lshl_add_u64 v[112:113], v[158:159], 1, s[86:87]
	v_cvt_pk_bf16_f32 v117, v164, v165
	global_store_dwordx2 v[112:113], v[116:117], off
	v_fmac_f32_e32 v120, v162, v162
	v_pk_fma_f32 v[162:163], v[122:123], v[180:181], v[154:155]
	v_cvt_pk_bf16_f32 v116, v160, v161
	global_store_dwordx4 v[194:195], v[160:163], off offset:64 nt
	v_cvt_pk_bf16_f32 v117, v162, v163
	global_store_dwordx2 v[112:113], v[116:117], off offset:32
	v_mul_f32_e32 v116, v161, v161
	v_fmac_f32_e32 v116, v160, v160
	v_fmac_f32_e32 v120, v164, v164
	v_fmac_f32_e32 v116, v162, v162
	v_fmac_f32_e32 v120, v165, v165
	v_fmac_f32_e32 v116, v163, v163
	v_add_f32_e32 v120, v120, v116
	v_pk_fma_f32 v[158:159], v[118:119], v[180:181], v[150:151]
	v_cvt_pk_bf16_f32 v116, v156, v157
	global_store_dwordx4 v[194:195], v[156:159], off offset:512 nt
	v_cvt_pk_bf16_f32 v117, v158, v159
	global_store_dwordx2 v[112:113], v[116:117], off offset:256
	v_mul_f32_e32 v116, v157, v157
	v_fmac_f32_e32 v116, v156, v156
	v_fmac_f32_e32 v116, v158, v158
	v_fmac_f32_e32 v116, v159, v159
	v_add_f32_e32 v120, v116, v120
	v_pk_fma_f32 v[126:127], v[114:115], v[180:181], v[142:143]
	v_cvt_pk_bf16_f32 v116, v124, v125
	global_store_dwordx4 v[194:195], v[124:127], off offset:576 nt
	v_cvt_pk_bf16_f32 v117, v126, v127
	global_store_dwordx2 v[112:113], v[116:117], off offset:288
	v_mul_f32_e32 v112, v125, v125
	v_and_b32_e32 v116, 64, v197
	v_fmac_f32_e32 v112, v124, v124
	v_xor_b32_e32 v113, 16, v197
	v_add_u32_e32 v116, 64, v116
	v_fmac_f32_e32 v112, v126, v126
	v_cmp_lt_i32_e32 vcc, v113, v116
	v_fmac_f32_e32 v112, v127, v127
	v_add_f32_e32 v112, v112, v120
	v_cndmask_b32_e32 v113, v197, v113, vcc
	v_lshlrev_b32_e32 v113, 2, v113
	ds_bpermute_b32 v113, v113, v112
	v_readlane_b32 s85, v238, 33
	s_waitcnt lgkmcnt(0)
	v_add_f32_e32 v112, v112, v113
	v_xor_b32_e32 v113, 32, v197
	v_cmp_lt_i32_e32 vcc, v113, v116
	s_nop 1
	v_cndmask_b32_e32 v113, v197, v113, vcc
	v_lshlrev_b32_e32 v113, 2, v113
	ds_bpermute_b32 v113, v113, v112
	s_and_saveexec_b64 s[16:17], s[34:35]
	s_cbranch_execz .LBB0_1853
	s_waitcnt lgkmcnt(0)
	v_add_f32_e32 v116, v112, v113
	v_lshlrev_b64 v[112:113], 7, v[188:189]
	v_lshl_add_u64 v[112:113], s[14:15], 0, v[112:113]
	global_store_dword v[112:113], v116, off

; DEVI unsigned pk_bf16(float lo, float hi) { unsigned r; asm("v_cvt_pk_bf16_f32 %0, %1, %2" : "=v"(r) : "v"(lo), "v"(hi)); return r; }
;     DEVI void operator()(const f32x4 (&acc)[2][2][4][2], const Unit& u, int wr, int wc, int fr, int fq, const LAS float*) const {
;     ...
;             const int ai = idx >> 2, m = idx & 3;
;             const size_t ro = (size_t)(row0 + ai * HALF + m * 16) * ldc + col0;
;             if (idx + 1 < 8) { const int ai2 = (idx + 1) >> 2, m2 = (idx + 1) & 3; const size_t ro2 = (size_t)(row0 + ai2 * HALF + m2 * 16) * ldc + col0;
; #pragma unroll
;                 for (int bj = 0; bj < 2; ++bj)
; #pragma unroll
;                     for (int n = 0; n < 2; ++n) nxt[bj][n] = *(const f32x4*)(R + ro2 + bj * HALF + n * 16); }
;             float ss = 0.f;
; #pragma unroll
;             for (int bj = 0; bj < 2; ++bj)
; #pragma unroll
;                 for (int n = 0; n < 2; ++n) {
;                     const f32x4 hn = cur[bj][n] + acc[ai][bj][m][n] * scale;
;                     *(f32x4*)(C + ro + bj * HALF + n * 16) = hn;
;                     if (HB) { u32x2 w; w.x = pk_bf16(hn[0], hn[1]); w.y = pk_bf16(hn[2], hn[3]); *(u32x2*)(HB + ro + bj * HALF + n * 16) = w;
;                         ss += hn[0] * hn[0] + hn[1] * hn[1] + hn[2] * hn[2] + hn[3] * hn[3]; } }
;             if (HB) { ss += __shfl_xor(ss, 16); ss += __shfl_xor(ss, 32); if (fq == 0) RS[(size_t)(row0 + ai * HALF + m * 16) * 32 + u.pn * 4 + wc] = ss; }
.LBB0_1855:
	v_or_b32_e32 v150, 32, v188
	v_mad_i64_i32 v[152:153], s[16:17], v150, s66, 0
	s_waitcnt lgkmcnt(0)
	v_lshl_add_u64 v[112:113], v[152:153], 2, v[186:187]
	global_load_dwordx4 v[124:127], v[112:113], off nt
	global_load_dwordx4 v[120:123], v[112:113], off offset:64 nt
	global_load_dwordx4 v[116:119], v[112:113], off offset:512 nt
	s_nop 0
	global_load_dwordx4 v[112:115], v[112:113], off offset:576 nt
	v_readlane_b32 s84, v238, 24
	v_lshl_add_u64 v[142:143], v[192:193], 0, v[182:183]
	v_readlane_b32 s88, v238, 28
	v_readlane_b32 s89, v238, 29
	v_mov_b32_e32 v181, v180
	v_pk_fma_f32 v[148:149], v[110:111], v[180:181], v[146:147]
	v_lshl_add_u64 v[154:155], v[142:143], 2, s[88:89]
	v_pk_fma_f32 v[146:147], v[108:109], v[184:185], v[144:145]
	s_and_b64 vcc, exec, s[38:39]
	v_pk_fma_f32 v[144:145], v[104:105], v[184:185], v[136:137]
	v_pk_fma_f32 v[140:141], v[100:101], v[184:185], v[132:133]
	v_pk_fma_f32 v[108:109], v[96:97], v[184:185], v[128:129]
	v_readlane_b32 s85, v238, 25
	v_readlane_b32 s86, v238, 26
	v_readlane_b32 s87, v238, 27
	v_readlane_b32 s90, v238, 30
	v_readlane_b32 s91, v238, 31
	global_store_dwordx4 v[154:155], v[146:149], off nt
	s_cbranch_vccnz .LBB0_1890
	v_readlane_b32 s84, v238, 32
	v_readlane_b32 s86, v238, 34
	v_readlane_b32 s87, v238, 35
	v_cvt_pk_bf16_f32 v100, v146, v147
	v_mul_f32_e32 v104, v147, v147
	v_cvt_pk_bf16_f32 v101, v148, v149
	v_fmac_f32_e32 v104, v146, v146
	v_lshl_add_u64 v[96:97], v[142:143], 1, s[86:87]
	global_store_dwordx2 v[96:97], v[100:101], off
	v_pk_fma_f32 v[146:147], v[106:107], v[180:181], v[138:139]
	v_cvt_pk_bf16_f32 v100, v144, v145
	global_store_dwordx4 v[154:155], v[144:147], off offset:64 nt
	v_cvt_pk_bf16_f32 v101, v146, v147
	global_store_dwordx2 v[96:97], v[100:101], off offset:32
	v_mul_f32_e32 v100, v145, v145
	v_fmac_f32_e32 v100, v144, v144
	v_fmac_f32_e32 v104, v148, v148
	v_fmac_f32_e32 v100, v146, v146
	v_fmac_f32_e32 v104, v149, v149
	v_fmac_f32_e32 v100, v147, v147
	v_add_f32_e32 v104, v104, v100
	v_pk_fma_f32 v[142:143], v[102:103], v[180:181], v[134:135]
	v_cvt_pk_bf16_f32 v100, v140, v141
	global_store_dwordx4 v[154:155], v[140:143], off offset:512 nt
	v_cvt_pk_bf16_f32 v101, v142, v143
	global_store_dwordx2 v[96:97], v[100:101], off offset:256
	v_mul_f32_e32 v100, v141, v141
	v_fmac_f32_e32 v100, v140, v140
	v_fmac_f32_e32 v100, v142, v142
	v_fmac_f32_e32 v100, v143, v143
	v_add_f32_e32 v104, v104, v100
	v_pk_fma_f32 v[110:111], v[98:99], v[180:181], v[130:131]
	v_cvt_pk_bf16_f32 v100, v108, v109
	global_store_dwordx4 v[154:155], v[108:111], off offset:576 nt
	v_cvt_pk_bf16_f32 v101, v110, v111
	global_store_dwordx2 v[96:97], v[100:101], off offset:288
	v_mul_f32_e32 v96, v109, v109
	v_and_b32_e32 v100, 64, v197
	v_fmac_f32_e32 v96, v108, v108
	v_xor_b32_e32 v97, 16, v197
	v_add_u32_e32 v100, 64, v100
	v_fmac_f32_e32 v96, v110, v110
	v_cmp_lt_i32_e32 vcc, v97, v100
	v_fmac_f32_e32 v96, v111, v111
	v_add_f32_e32 v96, v104, v96
	v_cndmask_b32_e32 v97, v197, v97, vcc
	v_lshlrev_b32_e32 v97, 2, v97
	ds_bpermute_b32 v97, v97, v96
	v_readlane_b32 s85, v238, 33
	s_waitcnt lgkmcnt(0)
	v_add_f32_e32 v96, v96, v97
	v_xor_b32_e32 v97, 32, v197
	v_cmp_lt_i32_e32 vcc, v97, v100
	s_nop 1
	v_cndmask_b32_e32 v97, v197, v97, vcc
	v_lshlrev_b32_e32 v97, 2, v97
	ds_bpermute_b32 v97, v97, v96
	s_and_saveexec_b64 s[16:17], s[34:35]
	s_cbranch_execz .LBB0_1858
	v_ashrrev_i32_e32 v191, 31, v190
	s_waitcnt lgkmcnt(0)
	v_add_f32_e32 v100, v96, v97
	v_lshlrev_b64 v[96:97], 7, v[190:191]
	v_lshl_add_u64 v[96:97], s[14:15], 0, v[96:97]
	global_store_dword v[96:97], v100, off

; DEVI unsigned pk_bf16(float lo, float hi) { unsigned r; asm("v_cvt_pk_bf16_f32 %0, %1, %2" : "=v"(r) : "v"(lo), "v"(hi)); return r; }
;     DEVI void operator()(const f32x4 (&acc)[2][2][4][2], const Unit& u, int wr, int wc, int fr, int fq, const LAS float*) const {
;     ...
;             const int ai = idx >> 2, m = idx & 3;
;             const size_t ro = (size_t)(row0 + ai * HALF + m * 16) * ldc + col0;
;             if (idx + 1 < 8) { const int ai2 = (idx + 1) >> 2, m2 = (idx + 1) & 3; const size_t ro2 = (size_t)(row0 + ai2 * HALF + m2 * 16) * ldc + col0;
; #pragma unroll
;                 for (int bj = 0; bj < 2; ++bj)
; #pragma unroll
;                     for (int n = 0; n < 2; ++n) nxt[bj][n] = *(const f32x4*)(R + ro2 + bj * HALF + n * 16); }
;             float ss = 0.f;
; #pragma unroll
;             for (int bj = 0; bj < 2; ++bj)
; #pragma unroll
;                 for (int n = 0; n < 2; ++n) {
;                     const f32x4 hn = cur[bj][n] + acc[ai][bj][m][n] * scale;
;                     *(f32x4*)(C + ro + bj * HALF + n * 16) = hn;
;                     if (HB) { u32x2 w; w.x = pk_bf16(hn[0], hn[1]); w.y = pk_bf16(hn[2], hn[3]); *(u32x2*)(HB + ro + bj * HALF + n * 16) = w;
;                         ss += hn[0] * hn[0] + hn[1] * hn[1] + hn[2] * hn[2] + hn[3] * hn[3]; } }
;             if (HB) { ss += __shfl_xor(ss, 16); ss += __shfl_xor(ss, 32); if (fq == 0) RS[(size_t)(row0 + ai * HALF + m * 16) * 32 + u.pn * 4 + wc] = ss; }
.LBB0_1860:
	v_or_b32_e32 v134, 48, v188
	v_mad_i64_i32 v[136:137], s[16:17], v134, s66, 0
	s_waitcnt lgkmcnt(0)
	v_lshl_add_u64 v[96:97], v[136:137], 2, v[186:187]
	global_load_dwordx4 v[108:111], v[96:97], off nt
	global_load_dwordx4 v[104:107], v[96:97], off offset:64 nt
	global_load_dwordx4 v[100:103], v[96:97], off offset:512 nt
	s_nop 0
	global_load_dwordx4 v[96:99], v[96:97], off offset:576 nt
	v_readlane_b32 s84, v238, 24
	v_lshl_add_u64 v[140:141], v[152:153], 0, v[182:183]
	v_readlane_b32 s88, v238, 28
	v_readlane_b32 s89, v238, 29
	v_mov_b32_e32 v181, v180
	s_waitcnt vmcnt(8)
	v_pk_fma_f32 v[132:133], v[94:95], v[180:181], v[126:127]
	v_lshl_add_u64 v[138:139], v[140:141], 2, s[88:89]
	v_pk_fma_f32 v[130:131], v[92:93], v[184:185], v[124:125]
	s_and_b64 vcc, exec, s[38:39]
	s_waitcnt vmcnt(7)
	v_pk_fma_f32 v[128:129], v[88:89], v[184:185], v[120:121]
	s_waitcnt vmcnt(6)
	v_pk_fma_f32 v[124:125], v[84:85], v[184:185], v[116:117]
	s_waitcnt vmcnt(5)
	v_pk_fma_f32 v[92:93], v[80:81], v[184:185], v[112:113]
	v_readlane_b32 s85, v238, 25
	v_readlane_b32 s86, v238, 26
	v_readlane_b32 s87, v238, 27
	v_readlane_b32 s90, v238, 30
	v_readlane_b32 s91, v238, 31
	global_store_dwordx4 v[138:139], v[130:133], off nt
	s_cbranch_vccnz .LBB0_1891
	v_readlane_b32 s84, v238, 32
	v_readlane_b32 s86, v238, 34
	v_readlane_b32 s87, v238, 35
	v_cvt_pk_bf16_f32 v84, v130, v131
	v_mul_f32_e32 v88, v131, v131
	v_cvt_pk_bf16_f32 v85, v132, v133
	v_fmac_f32_e32 v88, v130, v130
	v_lshl_add_u64 v[80:81], v[140:141], 1, s[86:87]
	global_store_dwordx2 v[80:81], v[84:85], off
	v_pk_fma_f32 v[130:131], v[90:91], v[180:181], v[122:123]
	v_cvt_pk_bf16_f32 v84, v128, v129
	global_store_dwordx4 v[138:139], v[128:131], off offset:64 nt
	v_cvt_pk_bf16_f32 v85, v130, v131
	global_store_dwordx2 v[80:81], v[84:85], off offset:32
	v_mul_f32_e32 v84, v129, v129
	v_fmac_f32_e32 v84, v128, v128
	v_fmac_f32_e32 v88, v132, v132
	v_fmac_f32_e32 v84, v130, v130
	v_fmac_f32_e32 v88, v133, v133
	v_fmac_f32_e32 v84, v131, v131
	v_add_f32_e32 v88, v88, v84
	v_pk_fma_f32 v[126:127], v[86:87], v[180:181], v[118:119]
	v_cvt_pk_bf16_f32 v84, v124, v125
	global_store_dwordx4 v[138:139], v[124:127], off offset:512 nt
	v_cvt_pk_bf16_f32 v85, v126, v127
	global_store_dwordx2 v[80:81], v[84:85], off offset:256
	v_mul_f32_e32 v84, v125, v125
	v_fmac_f32_e32 v84, v124, v124
	v_fmac_f32_e32 v84, v126, v126
	v_fmac_f32_e32 v84, v127, v127
	v_add_f32_e32 v88, v88, v84
	v_pk_fma_f32 v[94:95], v[82:83], v[180:181], v[114:115]
	v_cvt_pk_bf16_f32 v84, v92, v93
	global_store_dwordx4 v[138:139], v[92:95], off offset:576 nt
	v_cvt_pk_bf16_f32 v85, v94, v95
	global_store_dwordx2 v[80:81], v[84:85], off offset:288
	v_mul_f32_e32 v80, v93, v93
	v_and_b32_e32 v84, 64, v197
	v_fmac_f32_e32 v80, v92, v92
	v_xor_b32_e32 v81, 16, v197
	v_add_u32_e32 v84, 64, v84
	v_fmac_f32_e32 v80, v94, v94
	v_cmp_lt_i32_e32 vcc, v81, v84
	v_fmac_f32_e32 v80, v95, v95
	v_add_f32_e32 v80, v88, v80
	v_cndmask_b32_e32 v81, v197, v81, vcc
	v_lshlrev_b32_e32 v81, 2, v81
	ds_bpermute_b32 v81, v81, v80
	v_readlane_b32 s85, v238, 33
	s_waitcnt lgkmcnt(0)
	v_add_f32_e32 v80, v80, v81
	v_xor_b32_e32 v81, 32, v197
	v_cmp_lt_i32_e32 vcc, v81, v84
	s_nop 1
	v_cndmask_b32_e32 v81, v197, v81, vcc
	v_lshlrev_b32_e32 v81, 2, v81
	ds_bpermute_b32 v81, v81, v80
	s_and_saveexec_b64 s[16:17], s[34:35]
	s_cbranch_execz .LBB0_1863
	v_ashrrev_i32_e32 v151, 31, v150
	s_waitcnt lgkmcnt(0)
	v_add_f32_e32 v84, v80, v81
	v_lshlrev_b64 v[80:81], 7, v[150:151]
	v_lshl_add_u64 v[80:81], s[14:15], 0, v[80:81]
	global_store_dword v[80:81], v84, off

; DEVI unsigned pk_bf16(float lo, float hi) { unsigned r; asm("v_cvt_pk_bf16_f32 %0, %1, %2" : "=v"(r) : "v"(lo), "v"(hi)); return r; }
;     DEVI void operator()(const f32x4 (&acc)[2][2][4][2], const Unit& u, int wr, int wc, int fr, int fq, const LAS float*) const {
;     ...
;             const int ai = idx >> 2, m = idx & 3;
;             const size_t ro = (size_t)(row0 + ai * HALF + m * 16) * ldc + col0;
;             if (idx + 1 < 8) { const int ai2 = (idx + 1) >> 2, m2 = (idx + 1) & 3; const size_t ro2 = (size_t)(row0 + ai2 * HALF + m2 * 16) * ldc + col0;
; #pragma unroll
;                 for (int bj = 0; bj < 2; ++bj)
; #pragma unroll
;                     for (int n = 0; n < 2; ++n) nxt[bj][n] = *(const f32x4*)(R + ro2 + bj * HALF + n * 16); }
;             float ss = 0.f;
; #pragma unroll
;             for (int bj = 0; bj < 2; ++bj)
; #pragma unroll
;                 for (int n = 0; n < 2; ++n) {
;                     const f32x4 hn = cur[bj][n] + acc[ai][bj][m][n] * scale;
;                     *(f32x4*)(C + ro + bj * HALF + n * 16) = hn;
;                     if (HB) { u32x2 w; w.x = pk_bf16(hn[0], hn[1]); w.y = pk_bf16(hn[2], hn[3]); *(u32x2*)(HB + ro + bj * HALF + n * 16) = w;
;                         ss += hn[0] * hn[0] + hn[1] * hn[1] + hn[2] * hn[2] + hn[3] * hn[3]; } }
;             if (HB) { ss += __shfl_xor(ss, 16); ss += __shfl_xor(ss, 32); if (fq == 0) RS[(size_t)(row0 + ai * HALF + m * 16) * 32 + u.pn * 4 + wc] = ss; }
.LBB0_1865:
	v_add_u32_e32 v118, 0x80, v188
	v_mad_i64_i32 v[120:121], s[16:17], v118, s66, 0
	s_waitcnt lgkmcnt(0)
	v_lshl_add_u64 v[80:81], v[120:121], 2, v[186:187]
	global_load_dwordx4 v[92:95], v[80:81], off nt
	global_load_dwordx4 v[88:91], v[80:81], off offset:64 nt
	global_load_dwordx4 v[84:87], v[80:81], off offset:512 nt
	s_nop 0
	global_load_dwordx4 v[80:83], v[80:81], off offset:576 nt
	v_readlane_b32 s84, v238, 24
	v_lshl_add_u64 v[124:125], v[136:137], 0, v[182:183]
	v_readlane_b32 s88, v238, 28
	v_readlane_b32 s89, v238, 29
	v_mov_b32_e32 v181, v180
	s_waitcnt vmcnt(8)
	v_pk_fma_f32 v[116:117], v[78:79], v[180:181], v[110:111]
	v_lshl_add_u64 v[122:123], v[124:125], 2, s[88:89]
	v_pk_fma_f32 v[114:115], v[76:77], v[184:185], v[108:109]
	s_and_b64 vcc, exec, s[38:39]
	s_waitcnt vmcnt(7)
	v_pk_fma_f32 v[112:113], v[72:73], v[184:185], v[104:105]
	s_waitcnt vmcnt(6)
	v_pk_fma_f32 v[108:109], v[68:69], v[184:185], v[100:101]
	s_waitcnt vmcnt(5)
	v_pk_fma_f32 v[76:77], v[64:65], v[184:185], v[96:97]
	v_readlane_b32 s85, v238, 25
	v_readlane_b32 s86, v238, 26
	v_readlane_b32 s87, v238, 27
	v_readlane_b32 s90, v238, 30
	v_readlane_b32 s91, v238, 31
	global_store_dwordx4 v[122:123], v[114:117], off nt
	s_cbranch_vccnz .LBB0_1892
	v_readlane_b32 s84, v238, 32
	v_readlane_b32 s86, v238, 34
	v_readlane_b32 s87, v238, 35
	v_cvt_pk_bf16_f32 v68, v114, v115
	v_mul_f32_e32 v72, v115, v115
	v_cvt_pk_bf16_f32 v69, v116, v117
	v_fmac_f32_e32 v72, v114, v114
	v_lshl_add_u64 v[64:65], v[124:125], 1, s[86:87]
	global_store_dwordx2 v[64:65], v[68:69], off
	v_pk_fma_f32 v[114:115], v[74:75], v[180:181], v[106:107]
	v_cvt_pk_bf16_f32 v68, v112, v113
	global_store_dwordx4 v[122:123], v[112:115], off offset:64 nt
	v_cvt_pk_bf16_f32 v69, v114, v115
	global_store_dwordx2 v[64:65], v[68:69], off offset:32
	v_mul_f32_e32 v68, v113, v113
	v_fmac_f32_e32 v68, v112, v112
	v_fmac_f32_e32 v72, v116, v116
	v_fmac_f32_e32 v68, v114, v114
	v_fmac_f32_e32 v72, v117, v117
	v_fmac_f32_e32 v68, v115, v115
	v_add_f32_e32 v72, v72, v68
	v_pk_fma_f32 v[110:111], v[70:71], v[180:181], v[102:103]
	v_cvt_pk_bf16_f32 v68, v108, v109
	global_store_dwordx4 v[122:123], v[108:111], off offset:512 nt
	v_cvt_pk_bf16_f32 v69, v110, v111
	global_store_dwordx2 v[64:65], v[68:69], off offset:256
	v_mul_f32_e32 v68, v109, v109
	v_fmac_f32_e32 v68, v108, v108
	v_fmac_f32_e32 v68, v110, v110
	v_fmac_f32_e32 v68, v111, v111
	v_add_f32_e32 v72, v72, v68
	v_pk_fma_f32 v[78:79], v[66:67], v[180:181], v[98:99]
	v_cvt_pk_bf16_f32 v68, v76, v77
	global_store_dwordx4 v[122:123], v[76:79], off offset:576 nt
	v_cvt_pk_bf16_f32 v69, v78, v79
	global_store_dwordx2 v[64:65], v[68:69], off offset:288
	v_mul_f32_e32 v64, v77, v77
	v_and_b32_e32 v68, 64, v197
	v_fmac_f32_e32 v64, v76, v76
	v_xor_b32_e32 v65, 16, v197
	v_add_u32_e32 v68, 64, v68
	v_fmac_f32_e32 v64, v78, v78
	v_cmp_lt_i32_e32 vcc, v65, v68
	v_fmac_f32_e32 v64, v79, v79
	v_add_f32_e32 v64, v72, v64
	v_cndmask_b32_e32 v65, v197, v65, vcc
	v_lshlrev_b32_e32 v65, 2, v65
	ds_bpermute_b32 v65, v65, v64
	v_readlane_b32 s85, v238, 33
	s_waitcnt lgkmcnt(0)
	v_add_f32_e32 v64, v64, v65
	v_xor_b32_e32 v65, 32, v197
	v_cmp_lt_i32_e32 vcc, v65, v68
	s_nop 1
	v_cndmask_b32_e32 v65, v197, v65, vcc
	v_lshlrev_b32_e32 v65, 2, v65
	ds_bpermute_b32 v65, v65, v64
	s_and_saveexec_b64 s[16:17], s[34:35]
	s_cbranch_execz .LBB0_1868
	v_ashrrev_i32_e32 v135, 31, v134
	s_waitcnt lgkmcnt(0)
	v_add_f32_e32 v68, v64, v65
	v_lshlrev_b64 v[64:65], 7, v[134:135]
	v_lshl_add_u64 v[64:65], s[14:15], 0, v[64:65]
	global_store_dword v[64:65], v68, off

; DEVI unsigned pk_bf16(float lo, float hi) { unsigned r; asm("v_cvt_pk_bf16_f32 %0, %1, %2" : "=v"(r) : "v"(lo), "v"(hi)); return r; }
;     DEVI void operator()(const f32x4 (&acc)[2][2][4][2], const Unit& u, int wr, int wc, int fr, int fq, const LAS float*) const {
;     ...
;             const int ai = idx >> 2, m = idx & 3;
;             const size_t ro = (size_t)(row0 + ai * HALF + m * 16) * ldc + col0;
;             if (idx + 1 < 8) { const int ai2 = (idx + 1) >> 2, m2 = (idx + 1) & 3; const size_t ro2 = (size_t)(row0 + ai2 * HALF + m2 * 16) * ldc + col0;
; #pragma unroll
;                 for (int bj = 0; bj < 2; ++bj)
; #pragma unroll
;                     for (int n = 0; n < 2; ++n) nxt[bj][n] = *(const f32x4*)(R + ro2 + bj * HALF + n * 16); }
;             float ss = 0.f;
; #pragma unroll
;             for (int bj = 0; bj < 2; ++bj)
; #pragma unroll
;                 for (int n = 0; n < 2; ++n) {
;                     const f32x4 hn = cur[bj][n] + acc[ai][bj][m][n] * scale;
;                     *(f32x4*)(C + ro + bj * HALF + n * 16) = hn;
;                     if (HB) { u32x2 w; w.x = pk_bf16(hn[0], hn[1]); w.y = pk_bf16(hn[2], hn[3]); *(u32x2*)(HB + ro + bj * HALF + n * 16) = w;
;                         ss += hn[0] * hn[0] + hn[1] * hn[1] + hn[2] * hn[2] + hn[3] * hn[3]; } }
;             if (HB) { ss += __shfl_xor(ss, 16); ss += __shfl_xor(ss, 32); if (fq == 0) RS[(size_t)(row0 + ai * HALF + m * 16) * 32 + u.pn * 4 + wc] = ss; }
.LBB0_1870:
	v_or_b32_e32 v102, 16, v118
	v_mad_i64_i32 v[104:105], s[16:17], v102, s66, 0
	s_waitcnt lgkmcnt(0)
	v_lshl_add_u64 v[64:65], v[104:105], 2, v[186:187]
	global_load_dwordx4 v[76:79], v[64:65], off nt
	global_load_dwordx4 v[72:75], v[64:65], off offset:64 nt
	global_load_dwordx4 v[68:71], v[64:65], off offset:512 nt
	s_nop 0
	global_load_dwordx4 v[64:67], v[64:65], off offset:576 nt
	v_readlane_b32 s84, v238, 24
	v_lshl_add_u64 v[108:109], v[120:121], 0, v[182:183]
	v_readlane_b32 s88, v238, 28
	v_readlane_b32 s89, v238, 29
	v_mov_b32_e32 v181, v180
	v_ashrrev_i32_e32 v119, 31, v118
	v_lshl_add_u64 v[106:107], v[108:109], 2, s[88:89]
	s_waitcnt vmcnt(8)
	v_pk_fma_f32 v[100:101], v[62:63], v[180:181], v[94:95]
	v_pk_fma_f32 v[98:99], v[60:61], v[184:185], v[92:93]
	s_and_b64 vcc, exec, s[38:39]
	s_waitcnt vmcnt(7)
	v_pk_fma_f32 v[96:97], v[56:57], v[184:185], v[88:89]
	s_waitcnt vmcnt(6)
	v_pk_fma_f32 v[92:93], v[52:53], v[184:185], v[84:85]
	s_waitcnt vmcnt(5)
	v_pk_fma_f32 v[60:61], v[48:49], v[184:185], v[80:81]
	v_readlane_b32 s85, v238, 25
	v_readlane_b32 s86, v238, 26
	v_readlane_b32 s87, v238, 27
	v_readlane_b32 s90, v238, 30
	v_readlane_b32 s91, v238, 31
	global_store_dwordx4 v[106:107], v[98:101], off nt
	s_cbranch_vccnz .LBB0_1893
	v_readlane_b32 s84, v238, 32
	v_readlane_b32 s86, v238, 34
	v_readlane_b32 s87, v238, 35
	v_cvt_pk_bf16_f32 v52, v98, v99
	v_mul_f32_e32 v56, v99, v99
	v_cvt_pk_bf16_f32 v53, v100, v101
	v_fmac_f32_e32 v56, v98, v98
	v_lshl_add_u64 v[48:49], v[108:109], 1, s[86:87]
	global_store_dwordx2 v[48:49], v[52:53], off
	v_pk_fma_f32 v[98:99], v[58:59], v[180:181], v[90:91]
	v_cvt_pk_bf16_f32 v52, v96, v97
	global_store_dwordx4 v[106:107], v[96:99], off offset:64 nt
	v_cvt_pk_bf16_f32 v53, v98, v99
	global_store_dwordx2 v[48:49], v[52:53], off offset:32
	v_mul_f32_e32 v52, v97, v97
	v_fmac_f32_e32 v52, v96, v96
	v_fmac_f32_e32 v56, v100, v100
	v_fmac_f32_e32 v52, v98, v98
	v_fmac_f32_e32 v56, v101, v101
	v_fmac_f32_e32 v52, v99, v99
	v_add_f32_e32 v56, v56, v52
	v_pk_fma_f32 v[94:95], v[54:55], v[180:181], v[86:87]
	v_cvt_pk_bf16_f32 v52, v92, v93
	global_store_dwordx4 v[106:107], v[92:95], off offset:512 nt
	v_cvt_pk_bf16_f32 v53, v94, v95
	global_store_dwordx2 v[48:49], v[52:53], off offset:256
	v_mul_f32_e32 v52, v93, v93
	v_fmac_f32_e32 v52, v92, v92
	v_fmac_f32_e32 v52, v94, v94
	v_fmac_f32_e32 v52, v95, v95
	v_add_f32_e32 v56, v56, v52
	v_pk_fma_f32 v[62:63], v[50:51], v[180:181], v[82:83]
	v_cvt_pk_bf16_f32 v52, v60, v61
	global_store_dwordx4 v[106:107], v[60:63], off offset:576 nt
	v_cvt_pk_bf16_f32 v53, v62, v63
	global_store_dwordx2 v[48:49], v[52:53], off offset:288
	v_mul_f32_e32 v48, v61, v61
	v_and_b32_e32 v52, 64, v197
	v_fmac_f32_e32 v48, v60, v60
	v_xor_b32_e32 v49, 16, v197
	v_add_u32_e32 v52, 64, v52
	v_fmac_f32_e32 v48, v62, v62
	v_cmp_lt_i32_e32 vcc, v49, v52
	v_fmac_f32_e32 v48, v63, v63
	v_add_f32_e32 v48, v56, v48
	v_cndmask_b32_e32 v49, v197, v49, vcc
	v_lshlrev_b32_e32 v49, 2, v49
	ds_bpermute_b32 v49, v49, v48
	v_readlane_b32 s85, v238, 33
	s_waitcnt lgkmcnt(0)
	v_add_f32_e32 v48, v48, v49
	v_xor_b32_e32 v49, 32, v197
	v_cmp_lt_i32_e32 vcc, v49, v52
	s_nop 1
	v_cndmask_b32_e32 v49, v197, v49, vcc
	v_lshlrev_b32_e32 v49, 2, v49
	ds_bpermute_b32 v49, v49, v48
	s_and_saveexec_b64 s[16:17], s[34:35]
	s_cbranch_execz .LBB0_1873
	s_waitcnt lgkmcnt(0)
	v_add_f32_e32 v52, v48, v49
	v_lshlrev_b64 v[48:49], 7, v[118:119]
	v_lshl_add_u64 v[48:49], s[14:15], 0, v[48:49]
	global_store_dword v[48:49], v52, off

; DEVI unsigned pk_bf16(float lo, float hi) { unsigned r; asm("v_cvt_pk_bf16_f32 %0, %1, %2" : "=v"(r) : "v"(lo), "v"(hi)); return r; }
;     DEVI void operator()(const f32x4 (&acc)[2][2][4][2], const Unit& u, int wr, int wc, int fr, int fq, const LAS float*) const {
;     ...
;             const int ai = idx >> 2, m = idx & 3;
;             const size_t ro = (size_t)(row0 + ai * HALF + m * 16) * ldc + col0;
;             if (idx + 1 < 8) { const int ai2 = (idx + 1) >> 2, m2 = (idx + 1) & 3; const size_t ro2 = (size_t)(row0 + ai2 * HALF + m2 * 16) * ldc + col0;
; #pragma unroll
;                 for (int bj = 0; bj < 2; ++bj)
; #pragma unroll
;                     for (int n = 0; n < 2; ++n) nxt[bj][n] = *(const f32x4*)(R + ro2 + bj * HALF + n * 16); }
;             float ss = 0.f;
; #pragma unroll
;             for (int bj = 0; bj < 2; ++bj)
; #pragma unroll
;                 for (int n = 0; n < 2; ++n) {
;                     const f32x4 hn = cur[bj][n] + acc[ai][bj][m][n] * scale;
;                     *(f32x4*)(C + ro + bj * HALF + n * 16) = hn;
;                     if (HB) { u32x2 w; w.x = pk_bf16(hn[0], hn[1]); w.y = pk_bf16(hn[2], hn[3]); *(u32x2*)(HB + ro + bj * HALF + n * 16) = w;
;                         ss += hn[0] * hn[0] + hn[1] * hn[1] + hn[2] * hn[2] + hn[3] * hn[3]; } }
;             if (HB) { ss += __shfl_xor(ss, 16); ss += __shfl_xor(ss, 32); if (fq == 0) RS[(size_t)(row0 + ai * HALF + m * 16) * 32 + u.pn * 4 + wc] = ss; }
.LBB0_1875:
	v_or_b32_e32 v86, 32, v118
	v_mad_i64_i32 v[88:89], s[16:17], v86, s66, 0
	s_waitcnt lgkmcnt(0)
	v_lshl_add_u64 v[48:49], v[88:89], 2, v[186:187]
	global_load_dwordx4 v[60:63], v[48:49], off nt
	global_load_dwordx4 v[56:59], v[48:49], off offset:64 nt
	global_load_dwordx4 v[52:55], v[48:49], off offset:512 nt
	s_nop 0
	global_load_dwordx4 v[48:51], v[48:49], off offset:576 nt
	v_readlane_b32 s84, v238, 24
	v_lshl_add_u64 v[92:93], v[104:105], 0, v[182:183]
	v_readlane_b32 s88, v238, 28
	v_readlane_b32 s89, v238, 29
	v_mov_b32_e32 v181, v180
	s_waitcnt vmcnt(8)
	v_pk_fma_f32 v[84:85], v[46:47], v[180:181], v[78:79]
	v_lshl_add_u64 v[90:91], v[92:93], 2, s[88:89]
	v_pk_fma_f32 v[82:83], v[44:45], v[184:185], v[76:77]
	s_and_b64 vcc, exec, s[38:39]
	s_waitcnt vmcnt(7)
	v_pk_fma_f32 v[80:81], v[40:41], v[184:185], v[72:73]
	s_waitcnt vmcnt(6)
	v_pk_fma_f32 v[76:77], v[36:37], v[184:185], v[68:69]
	s_waitcnt vmcnt(5)
	v_pk_fma_f32 v[44:45], v[32:33], v[184:185], v[64:65]
	v_readlane_b32 s85, v238, 25
	v_readlane_b32 s86, v238, 26
	v_readlane_b32 s87, v238, 27
	v_readlane_b32 s90, v238, 30
	v_readlane_b32 s91, v238, 31
	global_store_dwordx4 v[90:91], v[82:85], off nt
	s_cbranch_vccnz .LBB0_1894
	v_readlane_b32 s84, v238, 32
	v_readlane_b32 s86, v238, 34
	v_readlane_b32 s87, v238, 35
	v_cvt_pk_bf16_f32 v36, v82, v83
	v_mul_f32_e32 v40, v83, v83
	v_cvt_pk_bf16_f32 v37, v84, v85
	v_fmac_f32_e32 v40, v82, v82
	v_lshl_add_u64 v[32:33], v[92:93], 1, s[86:87]
	global_store_dwordx2 v[32:33], v[36:37], off
	v_pk_fma_f32 v[82:83], v[42:43], v[180:181], v[74:75]
	v_cvt_pk_bf16_f32 v36, v80, v81
	global_store_dwordx4 v[90:91], v[80:83], off offset:64 nt
	v_cvt_pk_bf16_f32 v37, v82, v83
	global_store_dwordx2 v[32:33], v[36:37], off offset:32
	v_mul_f32_e32 v36, v81, v81
	v_fmac_f32_e32 v36, v80, v80
	v_fmac_f32_e32 v40, v84, v84
	v_fmac_f32_e32 v36, v82, v82
	v_fmac_f32_e32 v40, v85, v85
	v_fmac_f32_e32 v36, v83, v83
	v_add_f32_e32 v40, v40, v36
	v_pk_fma_f32 v[78:79], v[38:39], v[180:181], v[70:71]
	v_cvt_pk_bf16_f32 v36, v76, v77
	global_store_dwordx4 v[90:91], v[76:79], off offset:512 nt
	v_cvt_pk_bf16_f32 v37, v78, v79
	global_store_dwordx2 v[32:33], v[36:37], off offset:256
	v_mul_f32_e32 v36, v77, v77
	v_fmac_f32_e32 v36, v76, v76
	v_fmac_f32_e32 v36, v78, v78
	v_fmac_f32_e32 v36, v79, v79
	v_add_f32_e32 v40, v40, v36
	v_pk_fma_f32 v[46:47], v[34:35], v[180:181], v[66:67]
	v_cvt_pk_bf16_f32 v36, v44, v45
	global_store_dwordx4 v[90:91], v[44:47], off offset:576 nt
	v_cvt_pk_bf16_f32 v37, v46, v47
	global_store_dwordx2 v[32:33], v[36:37], off offset:288
	v_mul_f32_e32 v32, v45, v45
	v_and_b32_e32 v36, 64, v197
	v_fmac_f32_e32 v32, v44, v44
	v_xor_b32_e32 v33, 16, v197
	v_add_u32_e32 v36, 64, v36
	v_fmac_f32_e32 v32, v46, v46
	v_cmp_lt_i32_e32 vcc, v33, v36
	v_fmac_f32_e32 v32, v47, v47
	v_add_f32_e32 v32, v40, v32
	v_cndmask_b32_e32 v33, v197, v33, vcc
	v_lshlrev_b32_e32 v33, 2, v33
	ds_bpermute_b32 v33, v33, v32
	v_readlane_b32 s85, v238, 33
	s_waitcnt lgkmcnt(0)
	v_add_f32_e32 v32, v32, v33
	v_xor_b32_e32 v33, 32, v197
	v_cmp_lt_i32_e32 vcc, v33, v36
	s_nop 1
	v_cndmask_b32_e32 v33, v197, v33, vcc
	v_lshlrev_b32_e32 v33, 2, v33
	ds_bpermute_b32 v33, v33, v32
	s_and_saveexec_b64 s[16:17], s[34:35]
	s_cbranch_execz .LBB0_1878
	v_ashrrev_i32_e32 v103, 31, v102
	s_waitcnt lgkmcnt(0)
	v_add_f32_e32 v36, v32, v33
	v_lshlrev_b64 v[32:33], 7, v[102:103]
	v_lshl_add_u64 v[32:33], s[14:15], 0, v[32:33]
	global_store_dword v[32:33], v36, off

; DEVI unsigned pk_bf16(float lo, float hi) { unsigned r; asm("v_cvt_pk_bf16_f32 %0, %1, %2" : "=v"(r) : "v"(lo), "v"(hi)); return r; }
;     DEVI void operator()(const f32x4 (&acc)[2][2][4][2], const Unit& u, int wr, int wc, int fr, int fq, const LAS float*) const {
;     ...
;             const int ai = idx >> 2, m = idx & 3;
;             const size_t ro = (size_t)(row0 + ai * HALF + m * 16) * ldc + col0;
;             if (idx + 1 < 8) { const int ai2 = (idx + 1) >> 2, m2 = (idx + 1) & 3; const size_t ro2 = (size_t)(row0 + ai2 * HALF + m2 * 16) * ldc + col0;
; #pragma unroll
;                 for (int bj = 0; bj < 2; ++bj)
; #pragma unroll
;                     for (int n = 0; n < 2; ++n) nxt[bj][n] = *(const f32x4*)(R + ro2 + bj * HALF + n * 16); }
;             float ss = 0.f;
; #pragma unroll
;             for (int bj = 0; bj < 2; ++bj)
; #pragma unroll
;                 for (int n = 0; n < 2; ++n) {
;                     const f32x4 hn = cur[bj][n] + acc[ai][bj][m][n] * scale;
;                     *(f32x4*)(C + ro + bj * HALF + n * 16) = hn;
;                     if (HB) { u32x2 w; w.x = pk_bf16(hn[0], hn[1]); w.y = pk_bf16(hn[2], hn[3]); *(u32x2*)(HB + ro + bj * HALF + n * 16) = w;
;                         ss += hn[0] * hn[0] + hn[1] * hn[1] + hn[2] * hn[2] + hn[3] * hn[3]; } }
;             if (HB) { ss += __shfl_xor(ss, 16); ss += __shfl_xor(ss, 32); if (fq == 0) RS[(size_t)(row0 + ai * HALF + m * 16) * 32 + u.pn * 4 + wc] = ss; }
.LBB0_1880:
	v_or_b32_e32 v70, 48, v118
	v_mad_i64_i32 v[72:73], s[16:17], v70, s66, 0
	s_waitcnt lgkmcnt(0)
	v_lshl_add_u64 v[32:33], v[72:73], 2, v[186:187]
	global_load_dwordx4 v[44:47], v[32:33], off nt
	global_load_dwordx4 v[40:43], v[32:33], off offset:64 nt
	global_load_dwordx4 v[36:39], v[32:33], off offset:512 nt
	s_nop 0
	global_load_dwordx4 v[32:35], v[32:33], off offset:576 nt
	v_readlane_b32 s84, v238, 24
	v_lshl_add_u64 v[76:77], v[88:89], 0, v[182:183]
	v_readlane_b32 s88, v238, 28
	v_readlane_b32 s89, v238, 29
	v_mov_b32_e32 v181, v180
	s_waitcnt vmcnt(8)
	v_pk_fma_f32 v[68:69], v[30:31], v[180:181], v[62:63]
	v_lshl_add_u64 v[74:75], v[76:77], 2, s[88:89]
	v_pk_fma_f32 v[66:67], v[28:29], v[184:185], v[60:61]
	s_and_b64 vcc, exec, s[38:39]
	s_waitcnt vmcnt(7)
	v_pk_fma_f32 v[64:65], v[24:25], v[184:185], v[56:57]
	s_waitcnt vmcnt(6)
	v_pk_fma_f32 v[60:61], v[20:21], v[184:185], v[52:53]
	s_waitcnt vmcnt(5)
	v_pk_fma_f32 v[28:29], v[16:17], v[184:185], v[48:49]
	v_readlane_b32 s85, v238, 25
	v_readlane_b32 s86, v238, 26
	v_readlane_b32 s87, v238, 27
	v_readlane_b32 s90, v238, 30
	v_readlane_b32 s91, v238, 31
	global_store_dwordx4 v[74:75], v[66:69], off nt
	s_cbranch_vccnz .LBB0_1895
	v_readlane_b32 s84, v238, 32
	v_readlane_b32 s86, v238, 34
	v_readlane_b32 s87, v238, 35
	v_cvt_pk_bf16_f32 v20, v66, v67
	v_mul_f32_e32 v24, v67, v67
	v_cvt_pk_bf16_f32 v21, v68, v69
	v_fmac_f32_e32 v24, v66, v66
	v_lshl_add_u64 v[16:17], v[76:77], 1, s[86:87]
	global_store_dwordx2 v[16:17], v[20:21], off
	v_pk_fma_f32 v[66:67], v[26:27], v[180:181], v[58:59]
	v_cvt_pk_bf16_f32 v20, v64, v65
	global_store_dwordx4 v[74:75], v[64:67], off offset:64 nt
	v_cvt_pk_bf16_f32 v21, v66, v67
	global_store_dwordx2 v[16:17], v[20:21], off offset:32
	v_mul_f32_e32 v20, v65, v65
	v_fmac_f32_e32 v20, v64, v64
	v_fmac_f32_e32 v24, v68, v68
	v_fmac_f32_e32 v20, v66, v66
	v_fmac_f32_e32 v24, v69, v69
	v_fmac_f32_e32 v20, v67, v67
	v_add_f32_e32 v24, v24, v20
	v_pk_fma_f32 v[62:63], v[22:23], v[180:181], v[54:55]
	v_cvt_pk_bf16_f32 v20, v60, v61
	global_store_dwordx4 v[74:75], v[60:63], off offset:512 nt
	v_cvt_pk_bf16_f32 v21, v62, v63
	global_store_dwordx2 v[16:17], v[20:21], off offset:256
	v_mul_f32_e32 v20, v61, v61
	v_fmac_f32_e32 v20, v60, v60
	v_fmac_f32_e32 v20, v62, v62
	v_fmac_f32_e32 v20, v63, v63
	v_add_f32_e32 v24, v24, v20
	v_pk_fma_f32 v[30:31], v[18:19], v[180:181], v[50:51]
	v_cvt_pk_bf16_f32 v20, v28, v29
	global_store_dwordx4 v[74:75], v[28:31], off offset:576 nt
	v_cvt_pk_bf16_f32 v21, v30, v31
	global_store_dwordx2 v[16:17], v[20:21], off offset:288
	v_mul_f32_e32 v16, v29, v29
	v_and_b32_e32 v20, 64, v197
	v_fmac_f32_e32 v16, v28, v28
	v_xor_b32_e32 v17, 16, v197
	v_add_u32_e32 v20, 64, v20
	v_fmac_f32_e32 v16, v30, v30
	v_cmp_lt_i32_e32 vcc, v17, v20
	v_fmac_f32_e32 v16, v31, v31
	v_add_f32_e32 v16, v24, v16
	v_cndmask_b32_e32 v17, v197, v17, vcc
	v_lshlrev_b32_e32 v17, 2, v17
	ds_bpermute_b32 v17, v17, v16
	v_readlane_b32 s85, v238, 33
	s_waitcnt lgkmcnt(0)
	v_add_f32_e32 v16, v16, v17
	v_xor_b32_e32 v17, 32, v197
	v_cmp_lt_i32_e32 vcc, v17, v20
	s_nop 1
	v_cndmask_b32_e32 v17, v197, v17, vcc
	v_lshlrev_b32_e32 v17, 2, v17
	ds_bpermute_b32 v17, v17, v16
	s_and_saveexec_b64 s[16:17], s[34:35]
	s_cbranch_execz .LBB0_1883
	v_ashrrev_i32_e32 v87, 31, v86
	s_waitcnt lgkmcnt(0)
	v_add_f32_e32 v20, v16, v17
	v_lshlrev_b64 v[16:17], 7, v[86:87]
	v_lshl_add_u64 v[16:17], s[14:15], 0, v[16:17]
	global_store_dword v[16:17], v20, off

; DEVI unsigned pk_bf16(float lo, float hi) { unsigned r; asm("v_cvt_pk_bf16_f32 %0, %1, %2" : "=v"(r) : "v"(lo), "v"(hi)); return r; }
;     DEVI void operator()(const f32x4 (&acc)[2][2][4][2], const Unit& u, int wr, int wc, int fr, int fq, const LAS float*) const {
;     ...
;         const int row0 = u.pm * BM + wr * 64 + fr, col0 = u.pn * BM + wc * 32 + 4 * fq;
;         f32x4 cur[2][2], nxt[2][2];
;         { const size_t ro = (size_t)row0 * ldc + col0;
; #pragma unroll
;           for (int bj = 0; bj < 2; ++bj)
; #pragma unroll
;               for (int n = 0; n < 2; ++n) cur[bj][n] = *(const f32x4*)(R + ro + bj * HALF + n * 16); }
; #pragma unroll
;         for (int idx = 0; idx < 8; ++idx) {
;             const int ai = idx >> 2, m = idx & 3;
;             const size_t ro = (size_t)(row0 + ai * HALF + m * 16) * ldc + col0;
;             if (idx + 1 < 8) { const int ai2 = (idx + 1) >> 2, m2 = (idx + 1) & 3; const size_t ro2 = (size_t)(row0 + ai2 * HALF + m2 * 16) * ldc + col0;
; #pragma unroll
;                 for (int bj = 0; bj < 2; ++bj)
; #pragma unroll
;                     for (int n = 0; n < 2; ++n) nxt[bj][n] = *(const f32x4*)(R + ro2 + bj * HALF + n * 16); }
;             float ss = 0.f;
; #pragma unroll
;             for (int bj = 0; bj < 2; ++bj)
; #pragma unroll
;                 for (int n = 0; n < 2; ++n) {
;                     const f32x4 hn = cur[bj][n] + acc[ai][bj][m][n] * scale;
;                     *(f32x4*)(C + ro + bj * HALF + n * 16) = hn;
;                     if (HB) { u32x2 w; w.x = pk_bf16(hn[0], hn[1]); w.y = pk_bf16(hn[2], hn[3]); *(u32x2*)(HB + ro + bj * HALF + n * 16) = w;
;                         ss += hn[0] * hn[0] + hn[1] * hn[1] + hn[2] * hn[2] + hn[3] * hn[3]; } }
;             if (HB) { ss += __shfl_xor(ss, 16); ss += __shfl_xor(ss, 32); if (fq == 0) RS[(size_t)(row0 + ai * HALF + m * 16) * 32 + u.pn * 4 + wc] = ss; }
.LBB0_2367:
	v_readlane_b32 s60, v241, 14
	v_readlane_b32 s61, v241, 15
	v_readlane_b32 s62, v241, 16
	v_readlane_b32 s63, v241, 17
	v_lshl_add_u32 v188, s57, 8, v198
	v_lshl_or_b32 v182, s31, 8, v200
	s_mov_b32 s38, s62
	v_readlane_b32 s60, v238, 37
	v_mad_i64_i32 v[128:129], s[14:15], v188, s38, 0
	v_ashrrev_i32_e32 v183, 31, v182
	v_readlane_b32 s66, v238, 43
	v_readlane_b32 s67, v238, 44
	v_lshlrev_b64 v[130:131], 2, v[182:183]
	v_or_b32_e32 v190, 16, v188
	v_lshl_add_u64 v[128:129], v[128:129], 2, s[66:67]
	v_mov_b32_e32 v180, v204
	v_lshl_add_u64 v[128:129], v[128:129], 0, v[130:131]
	v_lshl_add_u64 v[186:187], s[66:67], 0, v[130:131]
	v_mad_i64_i32 v[192:193], s[16:17], v190, s38, 0
	global_load_dwordx4 v[160:163], v[128:129], off nt
	global_load_dwordx4 v[152:155], v[128:129], off offset:64 nt
	global_load_dwordx4 v[148:151], v[128:129], off offset:512 nt
	global_load_dwordx4 v[144:147], v[128:129], off offset:576 nt
	v_lshl_add_u64 v[128:129], v[192:193], 2, v[186:187]
	global_load_dwordx4 v[140:143], v[128:129], off nt
	global_load_dwordx4 v[136:139], v[128:129], off offset:64 nt
	global_load_dwordx4 v[132:135], v[128:129], off offset:512 nt
	s_nop 0
	global_load_dwordx4 v[128:131], v[128:129], off offset:576 nt
	s_lshl_b32 s14, s31, 2
	s_ashr_i32 s15, s14, 31
	s_lshl_b64 s[14:15], s[14:15], 2
	v_readlane_b32 s64, v238, 41
	v_readlane_b32 s65, v238, 42
	v_mov_b32_e32 v184, v180
	v_mov_b32_e32 v185, v180
	s_add_u32 s14, s4, s14
	s_waitcnt vmcnt(0)
	v_mad_i64_i32 v[158:159], s[16:17], v188, s38, v[182:183]
	v_ashrrev_i32_e32 v189, 31, v188
	s_addc_u32 s15, s5, s15
	v_lshl_add_u64 v[194:195], v[158:159], 2, s[64:65]
	s_andn2_b64 vcc, exec, s[46:47]
	v_readlane_b32 s61, v238, 38
	v_readlane_b32 s62, v238, 39
	v_readlane_b32 s63, v238, 40
	v_pk_fma_f32 v[164:165], v[126:127], v[180:181], v[162:163] op_sel_hi:[1,0,1]
	v_pk_fma_f32 v[162:163], v[124:125], v[180:181], v[160:161] op_sel_hi:[1,0,1]
	v_cndmask_b32_e64 v124, 0, 1, s[46:47]
	v_cmp_ne_u32_e64 s[38:39], 1, v124
	v_pk_fma_f32 v[160:161], v[120:121], v[184:185], v[152:153]
	v_pk_fma_f32 v[156:157], v[116:117], v[184:185], v[148:149]
	v_pk_fma_f32 v[124:125], v[112:113], v[184:185], v[144:145]
	global_store_dwordx4 v[194:195], v[162:165], off nt
	s_cbranch_vccnz .LBB0_2406
	v_readlane_b32 s60, v238, 45
	v_readlane_b32 s62, v238, 47
	v_readlane_b32 s63, v238, 48
	v_cvt_pk_bf16_f32 v116, v162, v163
	v_mul_f32_e32 v120, v163, v163
	v_mov_b32_e32 v181, v180
	v_lshl_add_u64 v[112:113], v[158:159], 1, s[62:63]
	v_cvt_pk_bf16_f32 v117, v164, v165
	global_store_dwordx2 v[112:113], v[116:117], off
	v_fmac_f32_e32 v120, v162, v162
	v_pk_fma_f32 v[162:163], v[122:123], v[180:181], v[154:155]
	v_cvt_pk_bf16_f32 v116, v160, v161
	global_store_dwordx4 v[194:195], v[160:163], off offset:64 nt
	v_cvt_pk_bf16_f32 v117, v162, v163
	global_store_dwordx2 v[112:113], v[116:117], off offset:32
	v_mul_f32_e32 v116, v161, v161
	v_fmac_f32_e32 v116, v160, v160
	v_fmac_f32_e32 v120, v164, v164
	v_fmac_f32_e32 v116, v162, v162
	v_fmac_f32_e32 v120, v165, v165
	v_fmac_f32_e32 v116, v163, v163
	v_add_f32_e32 v120, v120, v116
	v_pk_fma_f32 v[158:159], v[118:119], v[180:181], v[150:151]
	v_cvt_pk_bf16_f32 v116, v156, v157
	global_store_dwordx4 v[194:195], v[156:159], off offset:512 nt
	v_cvt_pk_bf16_f32 v117, v158, v159
	global_store_dwordx2 v[112:113], v[116:117], off offset:256
	v_mul_f32_e32 v116, v157, v157
	v_fmac_f32_e32 v116, v156, v156
	v_fmac_f32_e32 v116, v158, v158
	v_fmac_f32_e32 v116, v159, v159
	v_add_f32_e32 v120, v116, v120
	v_pk_fma_f32 v[126:127], v[114:115], v[180:181], v[146:147]
	v_cvt_pk_bf16_f32 v116, v124, v125
	global_store_dwordx4 v[194:195], v[124:127], off offset:576 nt
	v_cvt_pk_bf16_f32 v117, v126, v127
	global_store_dwordx2 v[112:113], v[116:117], off offset:288
	v_mul_f32_e32 v112, v125, v125
	v_and_b32_e32 v116, 64, v197
	v_fmac_f32_e32 v112, v124, v124
	v_xor_b32_e32 v113, 16, v197
	v_add_u32_e32 v116, 64, v116
	v_fmac_f32_e32 v112, v126, v126
	v_cmp_lt_i32_e32 vcc, v113, v116
	v_fmac_f32_e32 v112, v127, v127
	v_add_f32_e32 v112, v112, v120
	v_cndmask_b32_e32 v113, v197, v113, vcc
	v_lshlrev_b32_e32 v113, 2, v113
	ds_bpermute_b32 v113, v113, v112
	v_readlane_b32 s61, v238, 46
	s_waitcnt lgkmcnt(0)
	v_add_f32_e32 v112, v112, v113
	v_xor_b32_e32 v113, 32, v197
	v_cmp_lt_i32_e32 vcc, v113, v116
	s_nop 1
	v_cndmask_b32_e32 v113, v197, v113, vcc
	v_lshlrev_b32_e32 v113, 2, v113
	ds_bpermute_b32 v113, v113, v112
	s_and_saveexec_b64 s[16:17], s[34:35]
	s_cbranch_execz .LBB0_2370
	s_waitcnt lgkmcnt(0)
	v_add_f32_e32 v116, v112, v113
	v_lshlrev_b64 v[112:113], 7, v[188:189]
	v_lshl_add_u64 v[112:113], s[14:15], 0, v[112:113]
	global_store_dword v[112:113], v116, off

; DEVI unsigned pk_bf16(float lo, float hi) { unsigned r; asm("v_cvt_pk_bf16_f32 %0, %1, %2" : "=v"(r) : "v"(lo), "v"(hi)); return r; }
;     DEVI void operator()(const f32x4 (&acc)[2][2][4][2], const Unit& u, int wr, int wc, int fr, int fq, const LAS float*) const {
;     ...
;             const int ai = idx >> 2, m = idx & 3;
;             const size_t ro = (size_t)(row0 + ai * HALF + m * 16) * ldc + col0;
;             if (idx + 1 < 8) { const int ai2 = (idx + 1) >> 2, m2 = (idx + 1) & 3; const size_t ro2 = (size_t)(row0 + ai2 * HALF + m2 * 16) * ldc + col0;
; #pragma unroll
;                 for (int bj = 0; bj < 2; ++bj)
; #pragma unroll
;                     for (int n = 0; n < 2; ++n) nxt[bj][n] = *(const f32x4*)(R + ro2 + bj * HALF + n * 16); }
;             float ss = 0.f;
; #pragma unroll
;             for (int bj = 0; bj < 2; ++bj)
; #pragma unroll
;                 for (int n = 0; n < 2; ++n) {
;                     const f32x4 hn = cur[bj][n] + acc[ai][bj][m][n] * scale;
;                     *(f32x4*)(C + ro + bj * HALF + n * 16) = hn;
;                     if (HB) { u32x2 w; w.x = pk_bf16(hn[0], hn[1]); w.y = pk_bf16(hn[2], hn[3]); *(u32x2*)(HB + ro + bj * HALF + n * 16) = w;
;                         ss += hn[0] * hn[0] + hn[1] * hn[1] + hn[2] * hn[2] + hn[3] * hn[3]; } }
;             if (HB) { ss += __shfl_xor(ss, 16); ss += __shfl_xor(ss, 32); if (fq == 0) RS[(size_t)(row0 + ai * HALF + m * 16) * 32 + u.pn * 4 + wc] = ss; }
.LBB0_2372:
	v_readlane_b32 s60, v241, 14
	v_or_b32_e32 v150, 32, v188
	v_readlane_b32 s62, v241, 16
	v_readlane_b32 s61, v241, 15
	v_readlane_b32 s63, v241, 17
	v_mad_i64_i32 v[152:153], s[16:17], v150, s62, 0
	s_waitcnt lgkmcnt(0)
	v_lshl_add_u64 v[112:113], v[152:153], 2, v[186:187]
	global_load_dwordx4 v[124:127], v[112:113], off nt
	global_load_dwordx4 v[120:123], v[112:113], off offset:64 nt
	global_load_dwordx4 v[116:119], v[112:113], off offset:512 nt
	s_nop 0
	global_load_dwordx4 v[112:115], v[112:113], off offset:576 nt
	v_readlane_b32 s60, v238, 37
	v_lshl_add_u64 v[156:157], v[192:193], 0, v[182:183]
	v_readlane_b32 s64, v238, 41
	v_readlane_b32 s65, v238, 42
	v_mov_b32_e32 v181, v180
	v_pk_fma_f32 v[148:149], v[110:111], v[180:181], v[142:143]
	v_lshl_add_u64 v[154:155], v[156:157], 2, s[64:65]
	v_pk_fma_f32 v[146:147], v[108:109], v[184:185], v[140:141]
	s_and_b64 vcc, exec, s[38:39]
	v_pk_fma_f32 v[144:145], v[104:105], v[184:185], v[136:137]
	v_pk_fma_f32 v[140:141], v[100:101], v[184:185], v[132:133]
	v_pk_fma_f32 v[108:109], v[96:97], v[184:185], v[128:129]
	v_readlane_b32 s61, v238, 38
	v_readlane_b32 s62, v238, 39
	v_readlane_b32 s63, v238, 40
	v_readlane_b32 s66, v238, 43
	v_readlane_b32 s67, v238, 44
	global_store_dwordx4 v[154:155], v[146:149], off nt
	s_cbranch_vccnz .LBB0_2407
	v_readlane_b32 s60, v238, 45
	v_readlane_b32 s62, v238, 47
	v_readlane_b32 s63, v238, 48
	v_cvt_pk_bf16_f32 v100, v146, v147
	v_mul_f32_e32 v104, v147, v147
	v_cvt_pk_bf16_f32 v101, v148, v149
	v_fmac_f32_e32 v104, v146, v146
	v_lshl_add_u64 v[96:97], v[156:157], 1, s[62:63]
	global_store_dwordx2 v[96:97], v[100:101], off
	v_pk_fma_f32 v[146:147], v[106:107], v[180:181], v[138:139]
	v_cvt_pk_bf16_f32 v100, v144, v145
	global_store_dwordx4 v[154:155], v[144:147], off offset:64 nt
	v_cvt_pk_bf16_f32 v101, v146, v147
	global_store_dwordx2 v[96:97], v[100:101], off offset:32
	v_mul_f32_e32 v100, v145, v145
	v_fmac_f32_e32 v100, v144, v144
	v_fmac_f32_e32 v104, v148, v148
	v_fmac_f32_e32 v100, v146, v146
	v_fmac_f32_e32 v104, v149, v149
	v_fmac_f32_e32 v100, v147, v147
	v_add_f32_e32 v104, v104, v100
	v_pk_fma_f32 v[142:143], v[102:103], v[180:181], v[134:135]
	v_cvt_pk_bf16_f32 v100, v140, v141
	global_store_dwordx4 v[154:155], v[140:143], off offset:512 nt
	v_cvt_pk_bf16_f32 v101, v142, v143
	global_store_dwordx2 v[96:97], v[100:101], off offset:256
	v_mul_f32_e32 v100, v141, v141
	v_fmac_f32_e32 v100, v140, v140
	v_fmac_f32_e32 v100, v142, v142
	v_fmac_f32_e32 v100, v143, v143
	v_add_f32_e32 v104, v104, v100
	v_pk_fma_f32 v[110:111], v[98:99], v[180:181], v[130:131]
	v_cvt_pk_bf16_f32 v100, v108, v109
	global_store_dwordx4 v[154:155], v[108:111], off offset:576 nt
	v_cvt_pk_bf16_f32 v101, v110, v111
	global_store_dwordx2 v[96:97], v[100:101], off offset:288
	v_mul_f32_e32 v96, v109, v109
	v_and_b32_e32 v100, 64, v197
	v_fmac_f32_e32 v96, v108, v108
	v_xor_b32_e32 v97, 16, v197
	v_add_u32_e32 v100, 64, v100
	v_fmac_f32_e32 v96, v110, v110
	v_cmp_lt_i32_e32 vcc, v97, v100
	v_fmac_f32_e32 v96, v111, v111
	v_add_f32_e32 v96, v104, v96
	v_cndmask_b32_e32 v97, v197, v97, vcc
	v_lshlrev_b32_e32 v97, 2, v97
	ds_bpermute_b32 v97, v97, v96
	v_readlane_b32 s61, v238, 46
	s_waitcnt lgkmcnt(0)
	v_add_f32_e32 v96, v96, v97
	v_xor_b32_e32 v97, 32, v197
	v_cmp_lt_i32_e32 vcc, v97, v100
	s_nop 1
	v_cndmask_b32_e32 v97, v197, v97, vcc
	v_lshlrev_b32_e32 v97, 2, v97
	ds_bpermute_b32 v97, v97, v96
	s_and_saveexec_b64 s[16:17], s[34:35]
	s_cbranch_execz .LBB0_2375
	v_ashrrev_i32_e32 v191, 31, v190
	s_waitcnt lgkmcnt(0)
	v_add_f32_e32 v100, v96, v97
	v_lshlrev_b64 v[96:97], 7, v[190:191]
	v_lshl_add_u64 v[96:97], s[14:15], 0, v[96:97]
	global_store_dword v[96:97], v100, off

; DEVI unsigned pk_bf16(float lo, float hi) { unsigned r; asm("v_cvt_pk_bf16_f32 %0, %1, %2" : "=v"(r) : "v"(lo), "v"(hi)); return r; }
;     DEVI void operator()(const f32x4 (&acc)[2][2][4][2], const Unit& u, int wr, int wc, int fr, int fq, const LAS float*) const {
;     ...
;             const int ai = idx >> 2, m = idx & 3;
;             const size_t ro = (size_t)(row0 + ai * HALF + m * 16) * ldc + col0;
;             if (idx + 1 < 8) { const int ai2 = (idx + 1) >> 2, m2 = (idx + 1) & 3; const size_t ro2 = (size_t)(row0 + ai2 * HALF + m2 * 16) * ldc + col0;
; #pragma unroll
;                 for (int bj = 0; bj < 2; ++bj)
; #pragma unroll
;                     for (int n = 0; n < 2; ++n) nxt[bj][n] = *(const f32x4*)(R + ro2 + bj * HALF + n * 16); }
;             float ss = 0.f;
; #pragma unroll
;             for (int bj = 0; bj < 2; ++bj)
; #pragma unroll
;                 for (int n = 0; n < 2; ++n) {
;                     const f32x4 hn = cur[bj][n] + acc[ai][bj][m][n] * scale;
;                     *(f32x4*)(C + ro + bj * HALF + n * 16) = hn;
;                     if (HB) { u32x2 w; w.x = pk_bf16(hn[0], hn[1]); w.y = pk_bf16(hn[2], hn[3]); *(u32x2*)(HB + ro + bj * HALF + n * 16) = w;
;                         ss += hn[0] * hn[0] + hn[1] * hn[1] + hn[2] * hn[2] + hn[3] * hn[3]; } }
;             if (HB) { ss += __shfl_xor(ss, 16); ss += __shfl_xor(ss, 32); if (fq == 0) RS[(size_t)(row0 + ai * HALF + m * 16) * 32 + u.pn * 4 + wc] = ss; }
.LBB0_2377:
	v_readlane_b32 s60, v241, 14
	v_or_b32_e32 v134, 48, v188
	v_readlane_b32 s62, v241, 16
	v_readlane_b32 s61, v241, 15
	v_readlane_b32 s63, v241, 17
	v_mad_i64_i32 v[136:137], s[16:17], v134, s62, 0
	s_waitcnt lgkmcnt(0)
	v_lshl_add_u64 v[96:97], v[136:137], 2, v[186:187]
	global_load_dwordx4 v[108:111], v[96:97], off nt
	global_load_dwordx4 v[104:107], v[96:97], off offset:64 nt
	global_load_dwordx4 v[100:103], v[96:97], off offset:512 nt
	s_nop 0
	global_load_dwordx4 v[96:99], v[96:97], off offset:576 nt
	v_readlane_b32 s60, v238, 37
	v_lshl_add_u64 v[140:141], v[152:153], 0, v[182:183]
	v_readlane_b32 s64, v238, 41
	v_readlane_b32 s65, v238, 42
	v_mov_b32_e32 v181, v180
	s_waitcnt vmcnt(8)
	v_pk_fma_f32 v[132:133], v[94:95], v[180:181], v[126:127]
	v_lshl_add_u64 v[138:139], v[140:141], 2, s[64:65]
	v_pk_fma_f32 v[130:131], v[92:93], v[184:185], v[124:125]
	s_and_b64 vcc, exec, s[38:39]
	s_waitcnt vmcnt(7)
	v_pk_fma_f32 v[128:129], v[88:89], v[184:185], v[120:121]
	s_waitcnt vmcnt(6)
	v_pk_fma_f32 v[124:125], v[84:85], v[184:185], v[116:117]
	s_waitcnt vmcnt(5)
	v_pk_fma_f32 v[92:93], v[80:81], v[184:185], v[112:113]
	v_readlane_b32 s61, v238, 38
	v_readlane_b32 s62, v238, 39
	v_readlane_b32 s63, v238, 40
	v_readlane_b32 s66, v238, 43
	v_readlane_b32 s67, v238, 44
	global_store_dwordx4 v[138:139], v[130:133], off nt
	s_cbranch_vccnz .LBB0_2408
	v_readlane_b32 s60, v238, 45
	v_readlane_b32 s62, v238, 47
	v_readlane_b32 s63, v238, 48
	v_cvt_pk_bf16_f32 v84, v130, v131
	v_mul_f32_e32 v88, v131, v131
	v_cvt_pk_bf16_f32 v85, v132, v133
	v_fmac_f32_e32 v88, v130, v130
	v_lshl_add_u64 v[80:81], v[140:141], 1, s[62:63]
	global_store_dwordx2 v[80:81], v[84:85], off
	v_pk_fma_f32 v[130:131], v[90:91], v[180:181], v[122:123]
	v_cvt_pk_bf16_f32 v84, v128, v129
	global_store_dwordx4 v[138:139], v[128:131], off offset:64 nt
	v_cvt_pk_bf16_f32 v85, v130, v131
	global_store_dwordx2 v[80:81], v[84:85], off offset:32
	v_mul_f32_e32 v84, v129, v129
	v_fmac_f32_e32 v84, v128, v128
	v_fmac_f32_e32 v88, v132, v132
	v_fmac_f32_e32 v84, v130, v130
	v_fmac_f32_e32 v88, v133, v133
	v_fmac_f32_e32 v84, v131, v131
	v_add_f32_e32 v88, v88, v84
	v_pk_fma_f32 v[126:127], v[86:87], v[180:181], v[118:119]
	v_cvt_pk_bf16_f32 v84, v124, v125
	global_store_dwordx4 v[138:139], v[124:127], off offset:512 nt
	v_cvt_pk_bf16_f32 v85, v126, v127
	global_store_dwordx2 v[80:81], v[84:85], off offset:256
	v_mul_f32_e32 v84, v125, v125
	v_fmac_f32_e32 v84, v124, v124
	v_fmac_f32_e32 v84, v126, v126
	v_fmac_f32_e32 v84, v127, v127
	v_add_f32_e32 v88, v88, v84
	v_pk_fma_f32 v[94:95], v[82:83], v[180:181], v[114:115]
	v_cvt_pk_bf16_f32 v84, v92, v93
	global_store_dwordx4 v[138:139], v[92:95], off offset:576 nt
	v_cvt_pk_bf16_f32 v85, v94, v95
	global_store_dwordx2 v[80:81], v[84:85], off offset:288
	v_mul_f32_e32 v80, v93, v93
	v_and_b32_e32 v84, 64, v197
	v_fmac_f32_e32 v80, v92, v92
	v_xor_b32_e32 v81, 16, v197
	v_add_u32_e32 v84, 64, v84
	v_fmac_f32_e32 v80, v94, v94
	v_cmp_lt_i32_e32 vcc, v81, v84
	v_fmac_f32_e32 v80, v95, v95
	v_add_f32_e32 v80, v88, v80
	v_cndmask_b32_e32 v81, v197, v81, vcc
	v_lshlrev_b32_e32 v81, 2, v81
	ds_bpermute_b32 v81, v81, v80
	v_readlane_b32 s61, v238, 46
	s_waitcnt lgkmcnt(0)
	v_add_f32_e32 v80, v80, v81
	v_xor_b32_e32 v81, 32, v197
	v_cmp_lt_i32_e32 vcc, v81, v84
	s_nop 1
	v_cndmask_b32_e32 v81, v197, v81, vcc
	v_lshlrev_b32_e32 v81, 2, v81
	ds_bpermute_b32 v81, v81, v80
	s_and_saveexec_b64 s[16:17], s[34:35]
	s_cbranch_execz .LBB0_2380
	v_ashrrev_i32_e32 v151, 31, v150
	s_waitcnt lgkmcnt(0)
	v_add_f32_e32 v84, v80, v81
	v_lshlrev_b64 v[80:81], 7, v[150:151]
	v_lshl_add_u64 v[80:81], s[14:15], 0, v[80:81]
	global_store_dword v[80:81], v84, off

; DEVI unsigned pk_bf16(float lo, float hi) { unsigned r; asm("v_cvt_pk_bf16_f32 %0, %1, %2" : "=v"(r) : "v"(lo), "v"(hi)); return r; }
;     DEVI void operator()(const f32x4 (&acc)[2][2][4][2], const Unit& u, int wr, int wc, int fr, int fq, const LAS float*) const {
;     ...
;             const int ai = idx >> 2, m = idx & 3;
;             const size_t ro = (size_t)(row0 + ai * HALF + m * 16) * ldc + col0;
;             if (idx + 1 < 8) { const int ai2 = (idx + 1) >> 2, m2 = (idx + 1) & 3; const size_t ro2 = (size_t)(row0 + ai2 * HALF + m2 * 16) * ldc + col0;
; #pragma unroll
;                 for (int bj = 0; bj < 2; ++bj)
; #pragma unroll
;                     for (int n = 0; n < 2; ++n) nxt[bj][n] = *(const f32x4*)(R + ro2 + bj * HALF + n * 16); }
;             float ss = 0.f;
; #pragma unroll
;             for (int bj = 0; bj < 2; ++bj)
; #pragma unroll
;                 for (int n = 0; n < 2; ++n) {
;                     const f32x4 hn = cur[bj][n] + acc[ai][bj][m][n] * scale;
;                     *(f32x4*)(C + ro + bj * HALF + n * 16) = hn;
;                     if (HB) { u32x2 w; w.x = pk_bf16(hn[0], hn[1]); w.y = pk_bf16(hn[2], hn[3]); *(u32x2*)(HB + ro + bj * HALF + n * 16) = w;
;                         ss += hn[0] * hn[0] + hn[1] * hn[1] + hn[2] * hn[2] + hn[3] * hn[3]; } }
;             if (HB) { ss += __shfl_xor(ss, 16); ss += __shfl_xor(ss, 32); if (fq == 0) RS[(size_t)(row0 + ai * HALF + m * 16) * 32 + u.pn * 4 + wc] = ss; }
.LBB0_2382:
	v_readlane_b32 s60, v241, 14
	v_add_u32_e32 v118, 0x80, v188
	v_readlane_b32 s62, v241, 16
	v_readlane_b32 s61, v241, 15
	v_readlane_b32 s63, v241, 17
	v_mad_i64_i32 v[120:121], s[16:17], v118, s62, 0
	s_waitcnt lgkmcnt(0)
	v_lshl_add_u64 v[80:81], v[120:121], 2, v[186:187]
	global_load_dwordx4 v[92:95], v[80:81], off nt
	global_load_dwordx4 v[88:91], v[80:81], off offset:64 nt
	global_load_dwordx4 v[84:87], v[80:81], off offset:512 nt
	s_nop 0
	global_load_dwordx4 v[80:83], v[80:81], off offset:576 nt
	v_readlane_b32 s60, v238, 37
	v_lshl_add_u64 v[124:125], v[136:137], 0, v[182:183]
	v_readlane_b32 s64, v238, 41
	v_readlane_b32 s65, v238, 42
	v_mov_b32_e32 v181, v180
	s_waitcnt vmcnt(8)
	v_pk_fma_f32 v[116:117], v[78:79], v[180:181], v[110:111]
	v_lshl_add_u64 v[122:123], v[124:125], 2, s[64:65]
	v_pk_fma_f32 v[114:115], v[76:77], v[184:185], v[108:109]
	s_and_b64 vcc, exec, s[38:39]
	s_waitcnt vmcnt(7)
	v_pk_fma_f32 v[112:113], v[72:73], v[184:185], v[104:105]
	s_waitcnt vmcnt(6)
	v_pk_fma_f32 v[108:109], v[68:69], v[184:185], v[100:101]
	s_waitcnt vmcnt(5)
	v_pk_fma_f32 v[76:77], v[64:65], v[184:185], v[96:97]
	v_readlane_b32 s61, v238, 38
	v_readlane_b32 s62, v238, 39
	v_readlane_b32 s63, v238, 40
	v_readlane_b32 s66, v238, 43
	v_readlane_b32 s67, v238, 44
	global_store_dwordx4 v[122:123], v[114:117], off nt
	s_cbranch_vccnz .LBB0_2409
	v_readlane_b32 s60, v238, 45
	v_readlane_b32 s62, v238, 47
	v_readlane_b32 s63, v238, 48
	v_cvt_pk_bf16_f32 v68, v114, v115
	v_mul_f32_e32 v72, v115, v115
	v_cvt_pk_bf16_f32 v69, v116, v117
	v_fmac_f32_e32 v72, v114, v114
	v_lshl_add_u64 v[64:65], v[124:125], 1, s[62:63]
	global_store_dwordx2 v[64:65], v[68:69], off
	v_pk_fma_f32 v[114:115], v[74:75], v[180:181], v[106:107]
	v_cvt_pk_bf16_f32 v68, v112, v113
	global_store_dwordx4 v[122:123], v[112:115], off offset:64 nt
	v_cvt_pk_bf16_f32 v69, v114, v115
	global_store_dwordx2 v[64:65], v[68:69], off offset:32
	v_mul_f32_e32 v68, v113, v113
	v_fmac_f32_e32 v68, v112, v112
	v_fmac_f32_e32 v72, v116, v116
	v_fmac_f32_e32 v68, v114, v114
	v_fmac_f32_e32 v72, v117, v117
	v_fmac_f32_e32 v68, v115, v115
	v_add_f32_e32 v72, v72, v68
	v_pk_fma_f32 v[110:111], v[70:71], v[180:181], v[102:103]
	v_cvt_pk_bf16_f32 v68, v108, v109
	global_store_dwordx4 v[122:123], v[108:111], off offset:512 nt
	v_cvt_pk_bf16_f32 v69, v110, v111
	global_store_dwordx2 v[64:65], v[68:69], off offset:256
	v_mul_f32_e32 v68, v109, v109
	v_fmac_f32_e32 v68, v108, v108
	v_fmac_f32_e32 v68, v110, v110
	v_fmac_f32_e32 v68, v111, v111
	v_add_f32_e32 v72, v72, v68
	v_pk_fma_f32 v[78:79], v[66:67], v[180:181], v[98:99]
	v_cvt_pk_bf16_f32 v68, v76, v77
	global_store_dwordx4 v[122:123], v[76:79], off offset:576 nt
	v_cvt_pk_bf16_f32 v69, v78, v79
	global_store_dwordx2 v[64:65], v[68:69], off offset:288
	v_mul_f32_e32 v64, v77, v77
	v_and_b32_e32 v68, 64, v197
	v_fmac_f32_e32 v64, v76, v76
	v_xor_b32_e32 v65, 16, v197
	v_add_u32_e32 v68, 64, v68
	v_fmac_f32_e32 v64, v78, v78
	v_cmp_lt_i32_e32 vcc, v65, v68
	v_fmac_f32_e32 v64, v79, v79
	v_add_f32_e32 v64, v72, v64
	v_cndmask_b32_e32 v65, v197, v65, vcc
	v_lshlrev_b32_e32 v65, 2, v65
	ds_bpermute_b32 v65, v65, v64
	v_readlane_b32 s61, v238, 46
	s_waitcnt lgkmcnt(0)
	v_add_f32_e32 v64, v64, v65
	v_xor_b32_e32 v65, 32, v197
	v_cmp_lt_i32_e32 vcc, v65, v68
	s_nop 1
	v_cndmask_b32_e32 v65, v197, v65, vcc
	v_lshlrev_b32_e32 v65, 2, v65
	ds_bpermute_b32 v65, v65, v64
	s_and_saveexec_b64 s[16:17], s[34:35]
	s_cbranch_execz .LBB0_2385
	v_ashrrev_i32_e32 v135, 31, v134
	s_waitcnt lgkmcnt(0)
	v_add_f32_e32 v68, v64, v65
	v_lshlrev_b64 v[64:65], 7, v[134:135]
	v_lshl_add_u64 v[64:65], s[14:15], 0, v[64:65]
	global_store_dword v[64:65], v68, off

; DEVI unsigned pk_bf16(float lo, float hi) { unsigned r; asm("v_cvt_pk_bf16_f32 %0, %1, %2" : "=v"(r) : "v"(lo), "v"(hi)); return r; }
;     DEVI void operator()(const f32x4 (&acc)[2][2][4][2], const Unit& u, int wr, int wc, int fr, int fq, const LAS float*) const {
;     ...
;             const int ai = idx >> 2, m = idx & 3;
;             const size_t ro = (size_t)(row0 + ai * HALF + m * 16) * ldc + col0;
;             if (idx + 1 < 8) { const int ai2 = (idx + 1) >> 2, m2 = (idx + 1) & 3; const size_t ro2 = (size_t)(row0 + ai2 * HALF + m2 * 16) * ldc + col0;
; #pragma unroll
;                 for (int bj = 0; bj < 2; ++bj)
; #pragma unroll
;                     for (int n = 0; n < 2; ++n) nxt[bj][n] = *(const f32x4*)(R + ro2 + bj * HALF + n * 16); }
;             float ss = 0.f;
; #pragma unroll
;             for (int bj = 0; bj < 2; ++bj)
; #pragma unroll
;                 for (int n = 0; n < 2; ++n) {
;                     const f32x4 hn = cur[bj][n] + acc[ai][bj][m][n] * scale;
;                     *(f32x4*)(C + ro + bj * HALF + n * 16) = hn;
;                     if (HB) { u32x2 w; w.x = pk_bf16(hn[0], hn[1]); w.y = pk_bf16(hn[2], hn[3]); *(u32x2*)(HB + ro + bj * HALF + n * 16) = w;
;                         ss += hn[0] * hn[0] + hn[1] * hn[1] + hn[2] * hn[2] + hn[3] * hn[3]; } }
;             if (HB) { ss += __shfl_xor(ss, 16); ss += __shfl_xor(ss, 32); if (fq == 0) RS[(size_t)(row0 + ai * HALF + m * 16) * 32 + u.pn * 4 + wc] = ss; }
.LBB0_2387:
	v_readlane_b32 s60, v241, 14
	v_or_b32_e32 v102, 16, v118
	v_readlane_b32 s62, v241, 16
	v_readlane_b32 s61, v241, 15
	v_readlane_b32 s63, v241, 17
	v_mad_i64_i32 v[104:105], s[16:17], v102, s62, 0
	s_waitcnt lgkmcnt(0)
	v_lshl_add_u64 v[64:65], v[104:105], 2, v[186:187]
	global_load_dwordx4 v[76:79], v[64:65], off nt
	global_load_dwordx4 v[72:75], v[64:65], off offset:64 nt
	global_load_dwordx4 v[68:71], v[64:65], off offset:512 nt
	s_nop 0
	global_load_dwordx4 v[64:67], v[64:65], off offset:576 nt
	v_readlane_b32 s60, v238, 37
	v_lshl_add_u64 v[108:109], v[120:121], 0, v[182:183]
	v_readlane_b32 s64, v238, 41
	v_readlane_b32 s65, v238, 42
	v_mov_b32_e32 v181, v180
	v_ashrrev_i32_e32 v119, 31, v118
	v_lshl_add_u64 v[106:107], v[108:109], 2, s[64:65]
	s_waitcnt vmcnt(8)
	v_pk_fma_f32 v[100:101], v[62:63], v[180:181], v[94:95]
	v_pk_fma_f32 v[98:99], v[60:61], v[184:185], v[92:93]
	s_and_b64 vcc, exec, s[38:39]
	s_waitcnt vmcnt(7)
	v_pk_fma_f32 v[96:97], v[56:57], v[184:185], v[88:89]
	s_waitcnt vmcnt(6)
	v_pk_fma_f32 v[92:93], v[52:53], v[184:185], v[84:85]
	s_waitcnt vmcnt(5)
	v_pk_fma_f32 v[60:61], v[48:49], v[184:185], v[80:81]
	v_readlane_b32 s61, v238, 38
	v_readlane_b32 s62, v238, 39
	v_readlane_b32 s63, v238, 40
	v_readlane_b32 s66, v238, 43
	v_readlane_b32 s67, v238, 44
	global_store_dwordx4 v[106:107], v[98:101], off nt
	s_cbranch_vccnz .LBB0_2410
	v_readlane_b32 s60, v238, 45
	v_readlane_b32 s62, v238, 47
	v_readlane_b32 s63, v238, 48
	v_cvt_pk_bf16_f32 v52, v98, v99
	v_mul_f32_e32 v56, v99, v99
	v_cvt_pk_bf16_f32 v53, v100, v101
	v_fmac_f32_e32 v56, v98, v98
	v_lshl_add_u64 v[48:49], v[108:109], 1, s[62:63]
	global_store_dwordx2 v[48:49], v[52:53], off
	v_pk_fma_f32 v[98:99], v[58:59], v[180:181], v[90:91]
	v_cvt_pk_bf16_f32 v52, v96, v97
	global_store_dwordx4 v[106:107], v[96:99], off offset:64 nt
	v_cvt_pk_bf16_f32 v53, v98, v99
	global_store_dwordx2 v[48:49], v[52:53], off offset:32
	v_mul_f32_e32 v52, v97, v97
	v_fmac_f32_e32 v52, v96, v96
	v_fmac_f32_e32 v56, v100, v100
	v_fmac_f32_e32 v52, v98, v98
	v_fmac_f32_e32 v56, v101, v101
	v_fmac_f32_e32 v52, v99, v99
	v_add_f32_e32 v56, v56, v52
	v_pk_fma_f32 v[94:95], v[54:55], v[180:181], v[86:87]
	v_cvt_pk_bf16_f32 v52, v92, v93
	global_store_dwordx4 v[106:107], v[92:95], off offset:512 nt
	v_cvt_pk_bf16_f32 v53, v94, v95
	global_store_dwordx2 v[48:49], v[52:53], off offset:256
	v_mul_f32_e32 v52, v93, v93
	v_fmac_f32_e32 v52, v92, v92
	v_fmac_f32_e32 v52, v94, v94
	v_fmac_f32_e32 v52, v95, v95
	v_add_f32_e32 v56, v56, v52
	v_pk_fma_f32 v[62:63], v[50:51], v[180:181], v[82:83]
	v_cvt_pk_bf16_f32 v52, v60, v61
	global_store_dwordx4 v[106:107], v[60:63], off offset:576 nt
	v_cvt_pk_bf16_f32 v53, v62, v63
	global_store_dwordx2 v[48:49], v[52:53], off offset:288
	v_mul_f32_e32 v48, v61, v61
	v_and_b32_e32 v52, 64, v197
	v_fmac_f32_e32 v48, v60, v60
	v_xor_b32_e32 v49, 16, v197
	v_add_u32_e32 v52, 64, v52
	v_fmac_f32_e32 v48, v62, v62
	v_cmp_lt_i32_e32 vcc, v49, v52
	v_fmac_f32_e32 v48, v63, v63
	v_add_f32_e32 v48, v56, v48
	v_cndmask_b32_e32 v49, v197, v49, vcc
	v_lshlrev_b32_e32 v49, 2, v49
	ds_bpermute_b32 v49, v49, v48
	v_readlane_b32 s61, v238, 46
	s_waitcnt lgkmcnt(0)
	v_add_f32_e32 v48, v48, v49
	v_xor_b32_e32 v49, 32, v197
	v_cmp_lt_i32_e32 vcc, v49, v52
	s_nop 1
	v_cndmask_b32_e32 v49, v197, v49, vcc
	v_lshlrev_b32_e32 v49, 2, v49
	ds_bpermute_b32 v49, v49, v48
	s_and_saveexec_b64 s[16:17], s[34:35]
	s_cbranch_execz .LBB0_2390
	s_waitcnt lgkmcnt(0)
	v_add_f32_e32 v52, v48, v49
	v_lshlrev_b64 v[48:49], 7, v[118:119]
	v_lshl_add_u64 v[48:49], s[14:15], 0, v[48:49]
	global_store_dword v[48:49], v52, off

; DEVI unsigned pk_bf16(float lo, float hi) { unsigned r; asm("v_cvt_pk_bf16_f32 %0, %1, %2" : "=v"(r) : "v"(lo), "v"(hi)); return r; }
;     DEVI void operator()(const f32x4 (&acc)[2][2][4][2], const Unit& u, int wr, int wc, int fr, int fq, const LAS float*) const {
;     ...
;             const int ai = idx >> 2, m = idx & 3;
;             const size_t ro = (size_t)(row0 + ai * HALF + m * 16) * ldc + col0;
;             if (idx + 1 < 8) { const int ai2 = (idx + 1) >> 2, m2 = (idx + 1) & 3; const size_t ro2 = (size_t)(row0 + ai2 * HALF + m2 * 16) * ldc + col0;
; #pragma unroll
;                 for (int bj = 0; bj < 2; ++bj)
; #pragma unroll
;                     for (int n = 0; n < 2; ++n) nxt[bj][n] = *(const f32x4*)(R + ro2 + bj * HALF + n * 16); }
;             float ss = 0.f;
; #pragma unroll
;             for (int bj = 0; bj < 2; ++bj)
; #pragma unroll
;                 for (int n = 0; n < 2; ++n) {
;                     const f32x4 hn = cur[bj][n] + acc[ai][bj][m][n] * scale;
;                     *(f32x4*)(C + ro + bj * HALF + n * 16) = hn;
;                     if (HB) { u32x2 w; w.x = pk_bf16(hn[0], hn[1]); w.y = pk_bf16(hn[2], hn[3]); *(u32x2*)(HB + ro + bj * HALF + n * 16) = w;
;                         ss += hn[0] * hn[0] + hn[1] * hn[1] + hn[2] * hn[2] + hn[3] * hn[3]; } }
;             if (HB) { ss += __shfl_xor(ss, 16); ss += __shfl_xor(ss, 32); if (fq == 0) RS[(size_t)(row0 + ai * HALF + m * 16) * 32 + u.pn * 4 + wc] = ss; }
.LBB0_2392:
	v_readlane_b32 s60, v241, 14
	v_or_b32_e32 v86, 32, v118
	v_readlane_b32 s62, v241, 16
	v_readlane_b32 s61, v241, 15
	v_readlane_b32 s63, v241, 17
	v_mad_i64_i32 v[88:89], s[16:17], v86, s62, 0
	s_waitcnt lgkmcnt(0)
	v_lshl_add_u64 v[48:49], v[88:89], 2, v[186:187]
	global_load_dwordx4 v[60:63], v[48:49], off nt
	global_load_dwordx4 v[56:59], v[48:49], off offset:64 nt
	global_load_dwordx4 v[52:55], v[48:49], off offset:512 nt
	s_nop 0
	global_load_dwordx4 v[48:51], v[48:49], off offset:576 nt
	v_readlane_b32 s60, v238, 37
	v_lshl_add_u64 v[92:93], v[104:105], 0, v[182:183]
	v_readlane_b32 s64, v238, 41
	v_readlane_b32 s65, v238, 42
	v_mov_b32_e32 v181, v180
	s_waitcnt vmcnt(8)
	v_pk_fma_f32 v[84:85], v[46:47], v[180:181], v[78:79]
	v_lshl_add_u64 v[90:91], v[92:93], 2, s[64:65]
	v_pk_fma_f32 v[82:83], v[44:45], v[184:185], v[76:77]
	s_and_b64 vcc, exec, s[38:39]
	s_waitcnt vmcnt(7)
	v_pk_fma_f32 v[80:81], v[40:41], v[184:185], v[72:73]
	s_waitcnt vmcnt(6)
	v_pk_fma_f32 v[76:77], v[36:37], v[184:185], v[68:69]
	s_waitcnt vmcnt(5)
	v_pk_fma_f32 v[44:45], v[32:33], v[184:185], v[64:65]
	v_readlane_b32 s61, v238, 38
	v_readlane_b32 s62, v238, 39
	v_readlane_b32 s63, v238, 40
	v_readlane_b32 s66, v238, 43
	v_readlane_b32 s67, v238, 44
	global_store_dwordx4 v[90:91], v[82:85], off nt
	s_cbranch_vccnz .LBB0_2411
	v_readlane_b32 s60, v238, 45
	v_readlane_b32 s62, v238, 47
	v_readlane_b32 s63, v238, 48
	v_cvt_pk_bf16_f32 v36, v82, v83
	v_mul_f32_e32 v40, v83, v83
	v_cvt_pk_bf16_f32 v37, v84, v85
	v_fmac_f32_e32 v40, v82, v82
	v_lshl_add_u64 v[32:33], v[92:93], 1, s[62:63]
	global_store_dwordx2 v[32:33], v[36:37], off
	v_pk_fma_f32 v[82:83], v[42:43], v[180:181], v[74:75]
	v_cvt_pk_bf16_f32 v36, v80, v81
	global_store_dwordx4 v[90:91], v[80:83], off offset:64 nt
	v_cvt_pk_bf16_f32 v37, v82, v83
	global_store_dwordx2 v[32:33], v[36:37], off offset:32
	v_mul_f32_e32 v36, v81, v81
	v_fmac_f32_e32 v36, v80, v80
	v_fmac_f32_e32 v40, v84, v84
	v_fmac_f32_e32 v36, v82, v82
	v_fmac_f32_e32 v40, v85, v85
	v_fmac_f32_e32 v36, v83, v83
	v_add_f32_e32 v40, v40, v36
	v_pk_fma_f32 v[78:79], v[38:39], v[180:181], v[70:71]
	v_cvt_pk_bf16_f32 v36, v76, v77
	global_store_dwordx4 v[90:91], v[76:79], off offset:512 nt
	v_cvt_pk_bf16_f32 v37, v78, v79
	global_store_dwordx2 v[32:33], v[36:37], off offset:256
	v_mul_f32_e32 v36, v77, v77
	v_fmac_f32_e32 v36, v76, v76
	v_fmac_f32_e32 v36, v78, v78
	v_fmac_f32_e32 v36, v79, v79
	v_add_f32_e32 v40, v40, v36
	v_pk_fma_f32 v[46:47], v[34:35], v[180:181], v[66:67]
	v_cvt_pk_bf16_f32 v36, v44, v45
	global_store_dwordx4 v[90:91], v[44:47], off offset:576 nt
	v_cvt_pk_bf16_f32 v37, v46, v47
	global_store_dwordx2 v[32:33], v[36:37], off offset:288
	v_mul_f32_e32 v32, v45, v45
	v_and_b32_e32 v36, 64, v197
	v_fmac_f32_e32 v32, v44, v44
	v_xor_b32_e32 v33, 16, v197
	v_add_u32_e32 v36, 64, v36
	v_fmac_f32_e32 v32, v46, v46
	v_cmp_lt_i32_e32 vcc, v33, v36
	v_fmac_f32_e32 v32, v47, v47
	v_add_f32_e32 v32, v40, v32
	v_cndmask_b32_e32 v33, v197, v33, vcc
	v_lshlrev_b32_e32 v33, 2, v33
	ds_bpermute_b32 v33, v33, v32
	v_readlane_b32 s61, v238, 46
	s_waitcnt lgkmcnt(0)
	v_add_f32_e32 v32, v32, v33
	v_xor_b32_e32 v33, 32, v197
	v_cmp_lt_i32_e32 vcc, v33, v36
	s_nop 1
	v_cndmask_b32_e32 v33, v197, v33, vcc
	v_lshlrev_b32_e32 v33, 2, v33
	ds_bpermute_b32 v33, v33, v32
	s_and_saveexec_b64 s[16:17], s[34:35]
	s_cbranch_execz .LBB0_2395
	v_ashrrev_i32_e32 v103, 31, v102
	s_waitcnt lgkmcnt(0)
	v_add_f32_e32 v36, v32, v33
	v_lshlrev_b64 v[32:33], 7, v[102:103]
	v_lshl_add_u64 v[32:33], s[14:15], 0, v[32:33]
	global_store_dword v[32:33], v36, off

; DEVI unsigned pk_bf16(float lo, float hi) { unsigned r; asm("v_cvt_pk_bf16_f32 %0, %1, %2" : "=v"(r) : "v"(lo), "v"(hi)); return r; }
;     DEVI void operator()(const f32x4 (&acc)[2][2][4][2], const Unit& u, int wr, int wc, int fr, int fq, const LAS float*) const {
;     ...
;             const int ai = idx >> 2, m = idx & 3;
;             const size_t ro = (size_t)(row0 + ai * HALF + m * 16) * ldc + col0;
;             if (idx + 1 < 8) { const int ai2 = (idx + 1) >> 2, m2 = (idx + 1) & 3; const size_t ro2 = (size_t)(row0 + ai2 * HALF + m2 * 16) * ldc + col0;
; #pragma unroll
;                 for (int bj = 0; bj < 2; ++bj)
; #pragma unroll
;                     for (int n = 0; n < 2; ++n) nxt[bj][n] = *(const f32x4*)(R + ro2 + bj * HALF + n * 16); }
;             float ss = 0.f;
; #pragma unroll
;             for (int bj = 0; bj < 2; ++bj)
; #pragma unroll
;                 for (int n = 0; n < 2; ++n) {
;                     const f32x4 hn = cur[bj][n] + acc[ai][bj][m][n] * scale;
;                     *(f32x4*)(C + ro + bj * HALF + n * 16) = hn;
;                     if (HB) { u32x2 w; w.x = pk_bf16(hn[0], hn[1]); w.y = pk_bf16(hn[2], hn[3]); *(u32x2*)(HB + ro + bj * HALF + n * 16) = w;
;                         ss += hn[0] * hn[0] + hn[1] * hn[1] + hn[2] * hn[2] + hn[3] * hn[3]; } }
;             if (HB) { ss += __shfl_xor(ss, 16); ss += __shfl_xor(ss, 32); if (fq == 0) RS[(size_t)(row0 + ai * HALF + m * 16) * 32 + u.pn * 4 + wc] = ss; }
.LBB0_2397:
	v_readlane_b32 s60, v241, 14
	v_or_b32_e32 v70, 48, v118
	v_readlane_b32 s62, v241, 16
	v_readlane_b32 s61, v241, 15
	v_readlane_b32 s63, v241, 17
	v_mad_i64_i32 v[72:73], s[16:17], v70, s62, 0
	s_waitcnt lgkmcnt(0)
	v_lshl_add_u64 v[32:33], v[72:73], 2, v[186:187]
	global_load_dwordx4 v[44:47], v[32:33], off nt
	global_load_dwordx4 v[40:43], v[32:33], off offset:64 nt
	global_load_dwordx4 v[36:39], v[32:33], off offset:512 nt
	s_nop 0
	global_load_dwordx4 v[32:35], v[32:33], off offset:576 nt
	v_readlane_b32 s60, v238, 37
	v_lshl_add_u64 v[76:77], v[88:89], 0, v[182:183]
	v_readlane_b32 s64, v238, 41
	v_readlane_b32 s65, v238, 42
	v_mov_b32_e32 v181, v180
	s_waitcnt vmcnt(8)
	v_pk_fma_f32 v[68:69], v[30:31], v[180:181], v[62:63]
	v_lshl_add_u64 v[74:75], v[76:77], 2, s[64:65]
	v_pk_fma_f32 v[66:67], v[28:29], v[184:185], v[60:61]
	s_and_b64 vcc, exec, s[38:39]
	s_waitcnt vmcnt(7)
	v_pk_fma_f32 v[64:65], v[24:25], v[184:185], v[56:57]
	s_waitcnt vmcnt(6)
	v_pk_fma_f32 v[60:61], v[20:21], v[184:185], v[52:53]
	s_waitcnt vmcnt(5)
	v_pk_fma_f32 v[28:29], v[16:17], v[184:185], v[48:49]
	v_readlane_b32 s61, v238, 38
	v_readlane_b32 s62, v238, 39
	v_readlane_b32 s63, v238, 40
	v_readlane_b32 s66, v238, 43
	v_readlane_b32 s67, v238, 44
	global_store_dwordx4 v[74:75], v[66:69], off nt
	s_cbranch_vccnz .LBB0_2412
	v_readlane_b32 s60, v238, 45
	v_readlane_b32 s62, v238, 47
	v_readlane_b32 s63, v238, 48
	v_cvt_pk_bf16_f32 v20, v66, v67
	v_mul_f32_e32 v24, v67, v67
	v_cvt_pk_bf16_f32 v21, v68, v69
	v_fmac_f32_e32 v24, v66, v66
	v_lshl_add_u64 v[16:17], v[76:77], 1, s[62:63]
	global_store_dwordx2 v[16:17], v[20:21], off
	v_pk_fma_f32 v[66:67], v[26:27], v[180:181], v[58:59]
	v_cvt_pk_bf16_f32 v20, v64, v65
	global_store_dwordx4 v[74:75], v[64:67], off offset:64 nt
	v_cvt_pk_bf16_f32 v21, v66, v67
	global_store_dwordx2 v[16:17], v[20:21], off offset:32
	v_mul_f32_e32 v20, v65, v65
	v_fmac_f32_e32 v20, v64, v64
	v_fmac_f32_e32 v24, v68, v68
	v_fmac_f32_e32 v20, v66, v66
	v_fmac_f32_e32 v24, v69, v69
	v_fmac_f32_e32 v20, v67, v67
	v_add_f32_e32 v24, v24, v20
	v_pk_fma_f32 v[62:63], v[22:23], v[180:181], v[54:55]
	v_cvt_pk_bf16_f32 v20, v60, v61
	global_store_dwordx4 v[74:75], v[60:63], off offset:512 nt
	v_cvt_pk_bf16_f32 v21, v62, v63
	global_store_dwordx2 v[16:17], v[20:21], off offset:256
	v_mul_f32_e32 v20, v61, v61
	v_fmac_f32_e32 v20, v60, v60
	v_fmac_f32_e32 v20, v62, v62
	v_fmac_f32_e32 v20, v63, v63
	v_add_f32_e32 v24, v24, v20
	v_pk_fma_f32 v[30:31], v[18:19], v[180:181], v[50:51]
	v_cvt_pk_bf16_f32 v20, v28, v29
	global_store_dwordx4 v[74:75], v[28:31], off offset:576 nt
	v_cvt_pk_bf16_f32 v21, v30, v31
	global_store_dwordx2 v[16:17], v[20:21], off offset:288
	v_mul_f32_e32 v16, v29, v29
	v_and_b32_e32 v20, 64, v197
	v_fmac_f32_e32 v16, v28, v28
	v_xor_b32_e32 v17, 16, v197
	v_add_u32_e32 v20, 64, v20
	v_fmac_f32_e32 v16, v30, v30
	v_cmp_lt_i32_e32 vcc, v17, v20
	v_fmac_f32_e32 v16, v31, v31
	v_add_f32_e32 v16, v24, v16
	v_cndmask_b32_e32 v17, v197, v17, vcc
	v_lshlrev_b32_e32 v17, 2, v17
	ds_bpermute_b32 v17, v17, v16
	v_readlane_b32 s61, v238, 46
	s_waitcnt lgkmcnt(0)
	v_add_f32_e32 v16, v16, v17
	v_xor_b32_e32 v17, 32, v197
	v_cmp_lt_i32_e32 vcc, v17, v20
	s_nop 1
	v_cndmask_b32_e32 v17, v197, v17, vcc
	v_lshlrev_b32_e32 v17, 2, v17
	ds_bpermute_b32 v17, v17, v16
	s_and_saveexec_b64 s[16:17], s[34:35]
	s_cbranch_execz .LBB0_2400
	v_ashrrev_i32_e32 v87, 31, v86
	s_waitcnt lgkmcnt(0)
	v_add_f32_e32 v20, v16, v17
	v_lshlrev_b64 v[16:17], 7, v[86:87]
	v_lshl_add_u64 v[16:17], s[14:15], 0, v[16:17]
	global_store_dword v[16:17], v20, off

; DEVI unsigned pk_bf16(float lo, float hi) { unsigned r; asm("v_cvt_pk_bf16_f32 %0, %1, %2" : "=v"(r) : "v"(lo), "v"(hi)); return r; }
;     DEVI void operator()(const f32x4 (&acc)[2][2][4][2], const Unit& u, int wr, int wc, int fr, int fq, const LAS float*) const {
;     ...
;         const int row0 = u.pm * BM + wr * 64 + fr, col0 = u.pn * BM + wc * 32 + 4 * fq;
;         f32x4 cur[2][2], nxt[2][2];
;         { const size_t ro = (size_t)row0 * ldc + col0;
; #pragma unroll
;           for (int bj = 0; bj < 2; ++bj)
; #pragma unroll
;               for (int n = 0; n < 2; ++n) cur[bj][n] = *(const f32x4*)(R + ro + bj * HALF + n * 16); }
; #pragma unroll
;         for (int idx = 0; idx < 8; ++idx) {
;             const int ai = idx >> 2, m = idx & 3;
;             const size_t ro = (size_t)(row0 + ai * HALF + m * 16) * ldc + col0;
;             if (idx + 1 < 8) { const int ai2 = (idx + 1) >> 2, m2 = (idx + 1) & 3; const size_t ro2 = (size_t)(row0 + ai2 * HALF + m2 * 16) * ldc + col0;
; #pragma unroll
;                 for (int bj = 0; bj < 2; ++bj)
; #pragma unroll
;                     for (int n = 0; n < 2; ++n) nxt[bj][n] = *(const f32x4*)(R + ro2 + bj * HALF + n * 16); }
;             float ss = 0.f;
; #pragma unroll
;             for (int bj = 0; bj < 2; ++bj)
; #pragma unroll
;                 for (int n = 0; n < 2; ++n) {
;                     const f32x4 hn = cur[bj][n] + acc[ai][bj][m][n] * scale;
;                     *(f32x4*)(C + ro + bj * HALF + n * 16) = hn;
;                     if (HB) { u32x2 w; w.x = pk_bf16(hn[0], hn[1]); w.y = pk_bf16(hn[2], hn[3]); *(u32x2*)(HB + ro + bj * HALF + n * 16) = w;
;                         ss += hn[0] * hn[0] + hn[1] * hn[1] + hn[2] * hn[2] + hn[3] * hn[3]; } }
;             if (HB) { ss += __shfl_xor(ss, 16); ss += __shfl_xor(ss, 32); if (fq == 0) RS[(size_t)(row0 + ai * HALF + m * 16) * 32 + u.pn * 4 + wc] = ss; }
.LBB0_2591:
	v_lshl_add_u32 v188, s53, 8, v198
	v_lshl_or_b32 v182, s31, 8, v199
	v_mad_i64_i32 v[128:129], s[4:5], v188, s58, 0
	v_ashrrev_i32_e32 v183, 31, v182
	v_lshl_add_u64 v[128:129], v[128:129], 2, s[82:83]
	v_lshlrev_b64 v[130:131], 2, v[182:183]
	v_or_b32_e32 v190, 16, v188
	v_mov_b32_e32 v180, v203
	v_lshl_add_u64 v[128:129], v[128:129], 0, v[130:131]
	v_lshl_add_u64 v[186:187], s[82:83], 0, v[130:131]
	v_mad_i64_i32 v[192:193], s[4:5], v190, s58, 0
	global_load_dwordx4 v[160:163], v[128:129], off nt
	global_load_dwordx4 v[152:155], v[128:129], off offset:64 nt
	global_load_dwordx4 v[148:151], v[128:129], off offset:512 nt
	global_load_dwordx4 v[144:147], v[128:129], off offset:576 nt
	v_lshl_add_u64 v[128:129], v[192:193], 2, v[186:187]
	global_load_dwordx4 v[140:143], v[128:129], off nt
	global_load_dwordx4 v[136:139], v[128:129], off offset:64 nt
	global_load_dwordx4 v[132:135], v[128:129], off offset:512 nt
	s_nop 0
	global_load_dwordx4 v[128:131], v[128:129], off offset:576 nt
	s_lshl_b32 s24, s31, 2
	s_ashr_i32 s25, s24, 31
	s_lshl_b64 s[24:25], s[24:25], 2
	v_cndmask_b32_e64 v156, 0, 1, s[20:21]
	v_mov_b32_e32 v184, v180
	v_mov_b32_e32 v185, v180
	v_mad_i64_i32 v[158:159], s[26:27], v188, s58, v[182:183]
	s_add_u32 s24, s44, s24
	v_ashrrev_i32_e32 v189, 31, v188
	v_cmp_ne_u32_e64 s[4:5], 1, v156
	v_lshl_add_u64 v[194:195], v[158:159], 2, s[80:81]
	s_addc_u32 s25, s45, s25
	s_andn2_b64 vcc, exec, s[20:21]
	s_waitcnt vmcnt(0)
	v_pk_fma_f32 v[164:165], v[126:127], v[180:181], v[162:163] op_sel_hi:[1,0,1]
	v_pk_fma_f32 v[162:163], v[124:125], v[180:181], v[160:161] op_sel_hi:[1,0,1]
	v_pk_fma_f32 v[160:161], v[120:121], v[184:185], v[152:153]
	v_pk_fma_f32 v[156:157], v[116:117], v[184:185], v[148:149]
	v_pk_fma_f32 v[124:125], v[112:113], v[184:185], v[144:145]
	global_store_dwordx4 v[194:195], v[162:165], off nt
	s_cbranch_vccnz .LBB0_2630
	v_lshl_add_u64 v[116:117], v[158:159], 1, s[74:75]
	v_cvt_pk_bf16_f32 v112, v162, v163
	v_mul_f32_e32 v120, v163, v163
	v_mov_b32_e32 v181, v180
	v_cvt_pk_bf16_f32 v113, v164, v165
	global_store_dwordx2 v[116:117], v[112:113], off
	v_fmac_f32_e32 v120, v162, v162
	v_pk_fma_f32 v[162:163], v[122:123], v[180:181], v[154:155]
	v_cvt_pk_bf16_f32 v112, v160, v161
	global_store_dwordx4 v[194:195], v[160:163], off offset:64 nt
	v_cvt_pk_bf16_f32 v113, v162, v163
	global_store_dwordx2 v[116:117], v[112:113], off offset:32
	v_mul_f32_e32 v112, v161, v161
	v_fmac_f32_e32 v112, v160, v160
	v_mul_f32_e32 v113, v157, v157
	v_fmac_f32_e32 v120, v164, v164
	v_fmac_f32_e32 v112, v162, v162
	v_pk_fma_f32 v[158:159], v[118:119], v[180:181], v[150:151]
	v_fmac_f32_e32 v113, v156, v156
	v_fmac_f32_e32 v120, v165, v165
	v_fmac_f32_e32 v112, v163, v163
	v_fmac_f32_e32 v113, v158, v158
	v_add_f32_e32 v112, v120, v112
	v_fmac_f32_e32 v113, v159, v159
	v_add_f32_e32 v112, v113, v112
	v_mul_f32_e32 v113, v125, v125
	v_pk_fma_f32 v[126:127], v[114:115], v[180:181], v[146:147]
	v_fmac_f32_e32 v113, v124, v124
	v_fmac_f32_e32 v113, v126, v126
	v_fmac_f32_e32 v113, v127, v127
	v_add_f32_e32 v120, v113, v112
	v_and_b32_e32 v113, 64, v197
	v_xor_b32_e32 v112, 16, v197
	v_add_u32_e32 v121, 64, v113
	v_cmp_lt_i32_e32 vcc, v112, v121
	v_cvt_pk_bf16_f32 v113, v158, v159
	global_store_dwordx4 v[194:195], v[156:159], off offset:512 nt
	s_nop 0
	v_cndmask_b32_e32 v112, v197, v112, vcc
	v_lshlrev_b32_e32 v112, 2, v112
	ds_bpermute_b32 v144, v112, v120
	v_cvt_pk_bf16_f32 v112, v156, v157
	global_store_dwordx2 v[116:117], v[112:113], off offset:256
	v_xor_b32_e32 v113, 32, v197
	v_cmp_lt_i32_e32 vcc, v113, v121
	s_waitcnt lgkmcnt(0)
	v_add_f32_e32 v112, v120, v144
	global_store_dwordx4 v[194:195], v[124:127], off offset:576 nt
	v_cndmask_b32_e32 v113, v197, v113, vcc
	v_lshlrev_b32_e32 v113, 2, v113
	ds_bpermute_b32 v113, v113, v112
	v_cvt_pk_bf16_f32 v120, v124, v125
	v_cvt_pk_bf16_f32 v121, v126, v127
	global_store_dwordx2 v[116:117], v[120:121], off offset:288
	s_and_saveexec_b64 s[26:27], s[0:1]
	s_cbranch_execz .LBB0_2594
	s_waitcnt lgkmcnt(0)
	v_add_f32_e32 v116, v112, v113
	v_lshlrev_b64 v[112:113], 7, v[188:189]
	v_lshl_add_u64 v[112:113], s[24:25], 0, v[112:113]
	global_store_dword v[112:113], v116, off

; DEVI unsigned pk_bf16(float lo, float hi) { unsigned r; asm("v_cvt_pk_bf16_f32 %0, %1, %2" : "=v"(r) : "v"(lo), "v"(hi)); return r; }
;     DEVI void operator()(const f32x4 (&acc)[2][2][4][2], const Unit& u, int wr, int wc, int fr, int fq, const LAS float*) const {
;     ...
;         for (int idx = 0; idx < 8; ++idx) {
;             const int ai = idx >> 2, m = idx & 3;
;             const size_t ro = (size_t)(row0 + ai * HALF + m * 16) * ldc + col0;
;             if (idx + 1 < 8) { const int ai2 = (idx + 1) >> 2, m2 = (idx + 1) & 3; const size_t ro2 = (size_t)(row0 + ai2 * HALF + m2 * 16) * ldc + col0;
; #pragma unroll
;                 for (int bj = 0; bj < 2; ++bj)
; #pragma unroll
;                     for (int n = 0; n < 2; ++n) nxt[bj][n] = *(const f32x4*)(R + ro2 + bj * HALF + n * 16); }
;             float ss = 0.f;
; #pragma unroll
;             for (int bj = 0; bj < 2; ++bj)
; #pragma unroll
;                 for (int n = 0; n < 2; ++n) {
;                     const f32x4 hn = cur[bj][n] + acc[ai][bj][m][n] * scale;
;                     *(f32x4*)(C + ro + bj * HALF + n * 16) = hn;
;                     if (HB) { u32x2 w; w.x = pk_bf16(hn[0], hn[1]); w.y = pk_bf16(hn[2], hn[3]); *(u32x2*)(HB + ro + bj * HALF + n * 16) = w;
;                         ss += hn[0] * hn[0] + hn[1] * hn[1] + hn[2] * hn[2] + hn[3] * hn[3]; } }
;             if (HB) { ss += __shfl_xor(ss, 16); ss += __shfl_xor(ss, 32); if (fq == 0) RS[(size_t)(row0 + ai * HALF + m * 16) * 32 + u.pn * 4 + wc] = ss; }
; #pragma unroll
;             for (int bj = 0; bj < 2; ++bj)
; #pragma unroll
;                 for (int n = 0; n < 2; ++n) cur[bj][n] = nxt[bj][n];
.LBB0_2596:
	v_or_b32_e32 v150, 32, v188
	v_mad_i64_i32 v[152:153], s[26:27], v150, s58, 0
	s_waitcnt lgkmcnt(0)
	v_lshl_add_u64 v[112:113], v[152:153], 2, v[186:187]
	global_load_dwordx4 v[124:127], v[112:113], off nt
	global_load_dwordx4 v[120:123], v[112:113], off offset:64 nt
	global_load_dwordx4 v[116:119], v[112:113], off offset:512 nt
	s_nop 0
	global_load_dwordx4 v[112:115], v[112:113], off offset:576 nt
	v_lshl_add_u64 v[156:157], v[192:193], 0, v[182:183]
	v_mov_b32_e32 v181, v180
	v_lshl_add_u64 v[154:155], v[156:157], 2, s[80:81]
	v_pk_fma_f32 v[148:149], v[110:111], v[180:181], v[142:143]
	v_pk_fma_f32 v[146:147], v[108:109], v[184:185], v[140:141]
	s_and_b64 vcc, exec, s[4:5]
	v_pk_fma_f32 v[144:145], v[104:105], v[184:185], v[136:137]
	v_pk_fma_f32 v[140:141], v[100:101], v[184:185], v[132:133]
	v_pk_fma_f32 v[108:109], v[96:97], v[184:185], v[128:129]
	global_store_dwordx4 v[154:155], v[146:149], off nt
	s_cbranch_vccnz .LBB0_2631
	v_lshl_add_u64 v[100:101], v[156:157], 1, s[74:75]
	v_cvt_pk_bf16_f32 v96, v146, v147
	v_mul_f32_e32 v104, v147, v147
	v_cvt_pk_bf16_f32 v97, v148, v149
	global_store_dwordx2 v[100:101], v[96:97], off
	v_fmac_f32_e32 v104, v146, v146
	v_pk_fma_f32 v[146:147], v[106:107], v[180:181], v[138:139]
	v_cvt_pk_bf16_f32 v96, v144, v145
	global_store_dwordx4 v[154:155], v[144:147], off offset:64 nt
	v_cvt_pk_bf16_f32 v97, v146, v147
	global_store_dwordx2 v[100:101], v[96:97], off offset:32
	v_mul_f32_e32 v96, v145, v145
	v_fmac_f32_e32 v96, v144, v144
	v_mul_f32_e32 v97, v141, v141
	v_fmac_f32_e32 v104, v148, v148
	v_fmac_f32_e32 v96, v146, v146
	v_pk_fma_f32 v[142:143], v[102:103], v[180:181], v[134:135]
	v_fmac_f32_e32 v97, v140, v140
	v_fmac_f32_e32 v104, v149, v149
	v_fmac_f32_e32 v96, v147, v147
	v_fmac_f32_e32 v97, v142, v142
	v_add_f32_e32 v96, v104, v96
	v_fmac_f32_e32 v97, v143, v143
	v_add_f32_e32 v96, v96, v97
	v_mul_f32_e32 v97, v109, v109
	v_pk_fma_f32 v[110:111], v[98:99], v[180:181], v[130:131]
	v_fmac_f32_e32 v97, v108, v108
	v_fmac_f32_e32 v97, v110, v110
	v_fmac_f32_e32 v97, v111, v111
	v_add_f32_e32 v104, v96, v97
	v_and_b32_e32 v97, 64, v197
	v_xor_b32_e32 v96, 16, v197
	v_add_u32_e32 v105, 64, v97
	v_cmp_lt_i32_e32 vcc, v96, v105
	v_cvt_pk_bf16_f32 v97, v142, v143
	global_store_dwordx4 v[154:155], v[140:143], off offset:512 nt
	s_nop 0
	v_cndmask_b32_e32 v96, v197, v96, vcc
	v_lshlrev_b32_e32 v96, 2, v96
	ds_bpermute_b32 v128, v96, v104
	v_cvt_pk_bf16_f32 v96, v140, v141
	global_store_dwordx2 v[100:101], v[96:97], off offset:256
	v_xor_b32_e32 v97, 32, v197
	v_cmp_lt_i32_e32 vcc, v97, v105
	s_waitcnt lgkmcnt(0)
	v_add_f32_e32 v96, v104, v128
	global_store_dwordx4 v[154:155], v[108:111], off offset:576 nt
	v_cndmask_b32_e32 v97, v197, v97, vcc
	v_lshlrev_b32_e32 v97, 2, v97
	ds_bpermute_b32 v97, v97, v96
	v_cvt_pk_bf16_f32 v104, v108, v109
	v_cvt_pk_bf16_f32 v105, v110, v111
	global_store_dwordx2 v[100:101], v[104:105], off offset:288
	s_and_saveexec_b64 s[26:27], s[0:1]
	s_cbranch_execz .LBB0_2599
	v_ashrrev_i32_e32 v191, 31, v190
	s_waitcnt lgkmcnt(0)
	v_add_f32_e32 v100, v96, v97
	v_lshlrev_b64 v[96:97], 7, v[190:191]
	v_lshl_add_u64 v[96:97], s[24:25], 0, v[96:97]
	global_store_dword v[96:97], v100, off

; DEVI unsigned pk_bf16(float lo, float hi) { unsigned r; asm("v_cvt_pk_bf16_f32 %0, %1, %2" : "=v"(r) : "v"(lo), "v"(hi)); return r; }
;     DEVI void operator()(const f32x4 (&acc)[2][2][4][2], const Unit& u, int wr, int wc, int fr, int fq, const LAS float*) const {
;     ...
;         for (int idx = 0; idx < 8; ++idx) {
;             const int ai = idx >> 2, m = idx & 3;
;             const size_t ro = (size_t)(row0 + ai * HALF + m * 16) * ldc + col0;
;             if (idx + 1 < 8) { const int ai2 = (idx + 1) >> 2, m2 = (idx + 1) & 3; const size_t ro2 = (size_t)(row0 + ai2 * HALF + m2 * 16) * ldc + col0;
; #pragma unroll
;                 for (int bj = 0; bj < 2; ++bj)
; #pragma unroll
;                     for (int n = 0; n < 2; ++n) nxt[bj][n] = *(const f32x4*)(R + ro2 + bj * HALF + n * 16); }
;             float ss = 0.f;
; #pragma unroll
;             for (int bj = 0; bj < 2; ++bj)
; #pragma unroll
;                 for (int n = 0; n < 2; ++n) {
;                     const f32x4 hn = cur[bj][n] + acc[ai][bj][m][n] * scale;
;                     *(f32x4*)(C + ro + bj * HALF + n * 16) = hn;
;                     if (HB) { u32x2 w; w.x = pk_bf16(hn[0], hn[1]); w.y = pk_bf16(hn[2], hn[3]); *(u32x2*)(HB + ro + bj * HALF + n * 16) = w;
;                         ss += hn[0] * hn[0] + hn[1] * hn[1] + hn[2] * hn[2] + hn[3] * hn[3]; } }
;             if (HB) { ss += __shfl_xor(ss, 16); ss += __shfl_xor(ss, 32); if (fq == 0) RS[(size_t)(row0 + ai * HALF + m * 16) * 32 + u.pn * 4 + wc] = ss; }
; #pragma unroll
;             for (int bj = 0; bj < 2; ++bj)
; #pragma unroll
;                 for (int n = 0; n < 2; ++n) cur[bj][n] = nxt[bj][n];
.LBB0_2601:
	v_or_b32_e32 v134, 48, v188
	v_mad_i64_i32 v[136:137], s[26:27], v134, s58, 0
	s_waitcnt lgkmcnt(0)
	v_lshl_add_u64 v[96:97], v[136:137], 2, v[186:187]
	global_load_dwordx4 v[108:111], v[96:97], off nt
	global_load_dwordx4 v[104:107], v[96:97], off offset:64 nt
	global_load_dwordx4 v[100:103], v[96:97], off offset:512 nt
	s_nop 0
	global_load_dwordx4 v[96:99], v[96:97], off offset:576 nt
	v_lshl_add_u64 v[140:141], v[152:153], 0, v[182:183]
	v_mov_b32_e32 v181, v180
	v_lshl_add_u64 v[138:139], v[140:141], 2, s[80:81]
	s_waitcnt vmcnt(8)
	v_pk_fma_f32 v[132:133], v[94:95], v[180:181], v[126:127]
	v_pk_fma_f32 v[130:131], v[92:93], v[184:185], v[124:125]
	s_and_b64 vcc, exec, s[4:5]
	s_waitcnt vmcnt(7)
	v_pk_fma_f32 v[128:129], v[88:89], v[184:185], v[120:121]
	s_waitcnt vmcnt(6)
	v_pk_fma_f32 v[124:125], v[84:85], v[184:185], v[116:117]
	s_waitcnt vmcnt(5)
	v_pk_fma_f32 v[92:93], v[80:81], v[184:185], v[112:113]
	global_store_dwordx4 v[138:139], v[130:133], off nt
	s_cbranch_vccnz .LBB0_2632
	v_lshl_add_u64 v[84:85], v[140:141], 1, s[74:75]
	v_cvt_pk_bf16_f32 v80, v130, v131
	v_mul_f32_e32 v88, v131, v131
	v_cvt_pk_bf16_f32 v81, v132, v133
	global_store_dwordx2 v[84:85], v[80:81], off
	v_fmac_f32_e32 v88, v130, v130
	v_pk_fma_f32 v[130:131], v[90:91], v[180:181], v[122:123]
	v_cvt_pk_bf16_f32 v80, v128, v129
	global_store_dwordx4 v[138:139], v[128:131], off offset:64 nt
	v_cvt_pk_bf16_f32 v81, v130, v131
	global_store_dwordx2 v[84:85], v[80:81], off offset:32
	v_mul_f32_e32 v80, v129, v129
	v_fmac_f32_e32 v80, v128, v128
	v_mul_f32_e32 v81, v125, v125
	v_fmac_f32_e32 v88, v132, v132
	v_fmac_f32_e32 v80, v130, v130
	v_pk_fma_f32 v[126:127], v[86:87], v[180:181], v[118:119]
	v_fmac_f32_e32 v81, v124, v124
	v_fmac_f32_e32 v88, v133, v133
	v_fmac_f32_e32 v80, v131, v131
	v_fmac_f32_e32 v81, v126, v126
	v_add_f32_e32 v80, v88, v80
	v_fmac_f32_e32 v81, v127, v127
	v_add_f32_e32 v80, v80, v81
	v_mul_f32_e32 v81, v93, v93
	v_pk_fma_f32 v[94:95], v[82:83], v[180:181], v[114:115]
	v_fmac_f32_e32 v81, v92, v92
	v_fmac_f32_e32 v81, v94, v94
	v_fmac_f32_e32 v81, v95, v95
	v_add_f32_e32 v88, v80, v81
	v_and_b32_e32 v81, 64, v197
	v_xor_b32_e32 v80, 16, v197
	v_add_u32_e32 v89, 64, v81
	v_cmp_lt_i32_e32 vcc, v80, v89
	v_cvt_pk_bf16_f32 v81, v126, v127
	global_store_dwordx4 v[138:139], v[124:127], off offset:512 nt
	s_nop 0
	v_cndmask_b32_e32 v80, v197, v80, vcc
	v_lshlrev_b32_e32 v80, 2, v80
	ds_bpermute_b32 v112, v80, v88
	v_cvt_pk_bf16_f32 v80, v124, v125
	global_store_dwordx2 v[84:85], v[80:81], off offset:256
	v_xor_b32_e32 v81, 32, v197
	v_cmp_lt_i32_e32 vcc, v81, v89
	s_waitcnt lgkmcnt(0)
	v_add_f32_e32 v80, v88, v112
	global_store_dwordx4 v[138:139], v[92:95], off offset:576 nt
	v_cndmask_b32_e32 v81, v197, v81, vcc
	v_lshlrev_b32_e32 v81, 2, v81
	ds_bpermute_b32 v81, v81, v80
	v_cvt_pk_bf16_f32 v88, v92, v93
	v_cvt_pk_bf16_f32 v89, v94, v95
	global_store_dwordx2 v[84:85], v[88:89], off offset:288
	s_and_saveexec_b64 s[26:27], s[0:1]
	s_cbranch_execz .LBB0_2604
	v_ashrrev_i32_e32 v151, 31, v150
	s_waitcnt lgkmcnt(0)
	v_add_f32_e32 v84, v80, v81
	v_lshlrev_b64 v[80:81], 7, v[150:151]
	v_lshl_add_u64 v[80:81], s[24:25], 0, v[80:81]
	global_store_dword v[80:81], v84, off

; DEVI unsigned pk_bf16(float lo, float hi) { unsigned r; asm("v_cvt_pk_bf16_f32 %0, %1, %2" : "=v"(r) : "v"(lo), "v"(hi)); return r; }
;     DEVI void operator()(const f32x4 (&acc)[2][2][4][2], const Unit& u, int wr, int wc, int fr, int fq, const LAS float*) const {
;     ...
;         for (int idx = 0; idx < 8; ++idx) {
;             const int ai = idx >> 2, m = idx & 3;
;             const size_t ro = (size_t)(row0 + ai * HALF + m * 16) * ldc + col0;
;             if (idx + 1 < 8) { const int ai2 = (idx + 1) >> 2, m2 = (idx + 1) & 3; const size_t ro2 = (size_t)(row0 + ai2 * HALF + m2 * 16) * ldc + col0;
; #pragma unroll
;                 for (int bj = 0; bj < 2; ++bj)
; #pragma unroll
;                     for (int n = 0; n < 2; ++n) nxt[bj][n] = *(const f32x4*)(R + ro2 + bj * HALF + n * 16); }
;             float ss = 0.f;
; #pragma unroll
;             for (int bj = 0; bj < 2; ++bj)
; #pragma unroll
;                 for (int n = 0; n < 2; ++n) {
;                     const f32x4 hn = cur[bj][n] + acc[ai][bj][m][n] * scale;
;                     *(f32x4*)(C + ro + bj * HALF + n * 16) = hn;
;                     if (HB) { u32x2 w; w.x = pk_bf16(hn[0], hn[1]); w.y = pk_bf16(hn[2], hn[3]); *(u32x2*)(HB + ro + bj * HALF + n * 16) = w;
;                         ss += hn[0] * hn[0] + hn[1] * hn[1] + hn[2] * hn[2] + hn[3] * hn[3]; } }
;             if (HB) { ss += __shfl_xor(ss, 16); ss += __shfl_xor(ss, 32); if (fq == 0) RS[(size_t)(row0 + ai * HALF + m * 16) * 32 + u.pn * 4 + wc] = ss; }
; #pragma unroll
;             for (int bj = 0; bj < 2; ++bj)
; #pragma unroll
;                 for (int n = 0; n < 2; ++n) cur[bj][n] = nxt[bj][n];
.LBB0_2606:
	v_add_u32_e32 v118, 0x80, v188
	v_mad_i64_i32 v[120:121], s[26:27], v118, s58, 0
	s_waitcnt lgkmcnt(0)
	v_lshl_add_u64 v[80:81], v[120:121], 2, v[186:187]
	global_load_dwordx4 v[92:95], v[80:81], off nt
	global_load_dwordx4 v[88:91], v[80:81], off offset:64 nt
	global_load_dwordx4 v[84:87], v[80:81], off offset:512 nt
	s_nop 0
	global_load_dwordx4 v[80:83], v[80:81], off offset:576 nt
	v_lshl_add_u64 v[124:125], v[136:137], 0, v[182:183]
	v_mov_b32_e32 v181, v180
	v_lshl_add_u64 v[122:123], v[124:125], 2, s[80:81]
	s_waitcnt vmcnt(8)
	v_pk_fma_f32 v[116:117], v[78:79], v[180:181], v[110:111]
	v_pk_fma_f32 v[114:115], v[76:77], v[184:185], v[108:109]
	s_and_b64 vcc, exec, s[4:5]
	s_waitcnt vmcnt(7)
	v_pk_fma_f32 v[112:113], v[72:73], v[184:185], v[104:105]
	s_waitcnt vmcnt(6)
	v_pk_fma_f32 v[108:109], v[68:69], v[184:185], v[100:101]
	s_waitcnt vmcnt(5)
	v_pk_fma_f32 v[76:77], v[64:65], v[184:185], v[96:97]
	global_store_dwordx4 v[122:123], v[114:117], off nt
	s_cbranch_vccnz .LBB0_2633
	v_lshl_add_u64 v[68:69], v[124:125], 1, s[74:75]
	v_cvt_pk_bf16_f32 v64, v114, v115
	v_mul_f32_e32 v72, v115, v115
	v_cvt_pk_bf16_f32 v65, v116, v117
	global_store_dwordx2 v[68:69], v[64:65], off
	v_fmac_f32_e32 v72, v114, v114
	v_pk_fma_f32 v[114:115], v[74:75], v[180:181], v[106:107]
	v_cvt_pk_bf16_f32 v64, v112, v113
	global_store_dwordx4 v[122:123], v[112:115], off offset:64 nt
	v_cvt_pk_bf16_f32 v65, v114, v115
	global_store_dwordx2 v[68:69], v[64:65], off offset:32
	v_mul_f32_e32 v64, v113, v113
	v_fmac_f32_e32 v64, v112, v112
	v_mul_f32_e32 v65, v109, v109
	v_fmac_f32_e32 v72, v116, v116
	v_fmac_f32_e32 v64, v114, v114
	v_pk_fma_f32 v[110:111], v[70:71], v[180:181], v[102:103]
	v_fmac_f32_e32 v65, v108, v108
	v_fmac_f32_e32 v72, v117, v117
	v_fmac_f32_e32 v64, v115, v115
	v_fmac_f32_e32 v65, v110, v110
	v_add_f32_e32 v64, v72, v64
	v_fmac_f32_e32 v65, v111, v111
	v_add_f32_e32 v64, v64, v65
	v_mul_f32_e32 v65, v77, v77
	v_pk_fma_f32 v[78:79], v[66:67], v[180:181], v[98:99]
	v_fmac_f32_e32 v65, v76, v76
	v_fmac_f32_e32 v65, v78, v78
	v_fmac_f32_e32 v65, v79, v79
	v_add_f32_e32 v72, v64, v65
	v_and_b32_e32 v65, 64, v197
	v_xor_b32_e32 v64, 16, v197
	v_add_u32_e32 v73, 64, v65
	v_cmp_lt_i32_e32 vcc, v64, v73
	v_cvt_pk_bf16_f32 v65, v110, v111
	global_store_dwordx4 v[122:123], v[108:111], off offset:512 nt
	s_nop 0
	v_cndmask_b32_e32 v64, v197, v64, vcc
	v_lshlrev_b32_e32 v64, 2, v64
	ds_bpermute_b32 v96, v64, v72
	v_cvt_pk_bf16_f32 v64, v108, v109
	global_store_dwordx2 v[68:69], v[64:65], off offset:256
	v_xor_b32_e32 v65, 32, v197
	v_cmp_lt_i32_e32 vcc, v65, v73
	s_waitcnt lgkmcnt(0)
	v_add_f32_e32 v64, v72, v96
	global_store_dwordx4 v[122:123], v[76:79], off offset:576 nt
	v_cndmask_b32_e32 v65, v197, v65, vcc
	v_lshlrev_b32_e32 v65, 2, v65
	ds_bpermute_b32 v65, v65, v64
	v_cvt_pk_bf16_f32 v72, v76, v77
	v_cvt_pk_bf16_f32 v73, v78, v79
	global_store_dwordx2 v[68:69], v[72:73], off offset:288
	s_and_saveexec_b64 s[26:27], s[0:1]
	s_cbranch_execz .LBB0_2609
	v_ashrrev_i32_e32 v135, 31, v134
	s_waitcnt lgkmcnt(0)
	v_add_f32_e32 v68, v64, v65
	v_lshlrev_b64 v[64:65], 7, v[134:135]
	v_lshl_add_u64 v[64:65], s[24:25], 0, v[64:65]
	global_store_dword v[64:65], v68, off

; DEVI unsigned pk_bf16(float lo, float hi) { unsigned r; asm("v_cvt_pk_bf16_f32 %0, %1, %2" : "=v"(r) : "v"(lo), "v"(hi)); return r; }
;     DEVI void operator()(const f32x4 (&acc)[2][2][4][2], const Unit& u, int wr, int wc, int fr, int fq, const LAS float*) const {
;     ...
;         for (int idx = 0; idx < 8; ++idx) {
;             const int ai = idx >> 2, m = idx & 3;
;             const size_t ro = (size_t)(row0 + ai * HALF + m * 16) * ldc + col0;
;             if (idx + 1 < 8) { const int ai2 = (idx + 1) >> 2, m2 = (idx + 1) & 3; const size_t ro2 = (size_t)(row0 + ai2 * HALF + m2 * 16) * ldc + col0;
; #pragma unroll
;                 for (int bj = 0; bj < 2; ++bj)
; #pragma unroll
;                     for (int n = 0; n < 2; ++n) nxt[bj][n] = *(const f32x4*)(R + ro2 + bj * HALF + n * 16); }
;             float ss = 0.f;
; #pragma unroll
;             for (int bj = 0; bj < 2; ++bj)
; #pragma unroll
;                 for (int n = 0; n < 2; ++n) {
;                     const f32x4 hn = cur[bj][n] + acc[ai][bj][m][n] * scale;
;                     *(f32x4*)(C + ro + bj * HALF + n * 16) = hn;
;                     if (HB) { u32x2 w; w.x = pk_bf16(hn[0], hn[1]); w.y = pk_bf16(hn[2], hn[3]); *(u32x2*)(HB + ro + bj * HALF + n * 16) = w;
;                         ss += hn[0] * hn[0] + hn[1] * hn[1] + hn[2] * hn[2] + hn[3] * hn[3]; } }
;             if (HB) { ss += __shfl_xor(ss, 16); ss += __shfl_xor(ss, 32); if (fq == 0) RS[(size_t)(row0 + ai * HALF + m * 16) * 32 + u.pn * 4 + wc] = ss; }
; #pragma unroll
;             for (int bj = 0; bj < 2; ++bj)
; #pragma unroll
;                 for (int n = 0; n < 2; ++n) cur[bj][n] = nxt[bj][n];
.LBB0_2611:
	v_or_b32_e32 v102, 16, v118
	v_mad_i64_i32 v[104:105], s[26:27], v102, s58, 0
	s_waitcnt lgkmcnt(0)
	v_lshl_add_u64 v[64:65], v[104:105], 2, v[186:187]
	global_load_dwordx4 v[76:79], v[64:65], off nt
	global_load_dwordx4 v[72:75], v[64:65], off offset:64 nt
	global_load_dwordx4 v[68:71], v[64:65], off offset:512 nt
	s_nop 0
	global_load_dwordx4 v[64:67], v[64:65], off offset:576 nt
	v_lshl_add_u64 v[108:109], v[120:121], 0, v[182:183]
	v_mov_b32_e32 v181, v180
	v_ashrrev_i32_e32 v119, 31, v118
	v_lshl_add_u64 v[106:107], v[108:109], 2, s[80:81]
	s_waitcnt vmcnt(8)
	v_pk_fma_f32 v[100:101], v[62:63], v[180:181], v[94:95]
	v_pk_fma_f32 v[98:99], v[60:61], v[184:185], v[92:93]
	s_and_b64 vcc, exec, s[4:5]
	s_waitcnt vmcnt(7)
	v_pk_fma_f32 v[96:97], v[56:57], v[184:185], v[88:89]
	s_waitcnt vmcnt(6)
	v_pk_fma_f32 v[92:93], v[52:53], v[184:185], v[84:85]
	s_waitcnt vmcnt(5)
	v_pk_fma_f32 v[60:61], v[48:49], v[184:185], v[80:81]
	global_store_dwordx4 v[106:107], v[98:101], off nt
	s_cbranch_vccnz .LBB0_2634
	v_lshl_add_u64 v[52:53], v[108:109], 1, s[74:75]
	v_cvt_pk_bf16_f32 v48, v98, v99
	v_mul_f32_e32 v56, v99, v99
	v_cvt_pk_bf16_f32 v49, v100, v101
	global_store_dwordx2 v[52:53], v[48:49], off
	v_fmac_f32_e32 v56, v98, v98
	v_pk_fma_f32 v[98:99], v[58:59], v[180:181], v[90:91]
	v_cvt_pk_bf16_f32 v48, v96, v97
	global_store_dwordx4 v[106:107], v[96:99], off offset:64 nt
	v_cvt_pk_bf16_f32 v49, v98, v99
	global_store_dwordx2 v[52:53], v[48:49], off offset:32
	v_mul_f32_e32 v48, v97, v97
	v_fmac_f32_e32 v48, v96, v96
	v_mul_f32_e32 v49, v93, v93
	v_fmac_f32_e32 v56, v100, v100
	v_fmac_f32_e32 v48, v98, v98
	v_pk_fma_f32 v[94:95], v[54:55], v[180:181], v[86:87]
	v_fmac_f32_e32 v49, v92, v92
	v_fmac_f32_e32 v56, v101, v101
	v_fmac_f32_e32 v48, v99, v99
	v_fmac_f32_e32 v49, v94, v94
	v_add_f32_e32 v48, v56, v48
	v_fmac_f32_e32 v49, v95, v95
	v_add_f32_e32 v48, v48, v49
	v_mul_f32_e32 v49, v61, v61
	v_pk_fma_f32 v[62:63], v[50:51], v[180:181], v[82:83]
	v_fmac_f32_e32 v49, v60, v60
	v_fmac_f32_e32 v49, v62, v62
	v_fmac_f32_e32 v49, v63, v63
	v_add_f32_e32 v56, v48, v49
	v_and_b32_e32 v49, 64, v197
	v_xor_b32_e32 v48, 16, v197
	v_add_u32_e32 v57, 64, v49
	v_cmp_lt_i32_e32 vcc, v48, v57
	v_cvt_pk_bf16_f32 v49, v94, v95
	global_store_dwordx4 v[106:107], v[92:95], off offset:512 nt
	s_nop 0
	v_cndmask_b32_e32 v48, v197, v48, vcc
	v_lshlrev_b32_e32 v48, 2, v48
	ds_bpermute_b32 v80, v48, v56
	v_cvt_pk_bf16_f32 v48, v92, v93
	global_store_dwordx2 v[52:53], v[48:49], off offset:256
	v_xor_b32_e32 v49, 32, v197
	v_cmp_lt_i32_e32 vcc, v49, v57
	s_waitcnt lgkmcnt(0)
	v_add_f32_e32 v48, v56, v80
	global_store_dwordx4 v[106:107], v[60:63], off offset:576 nt
	v_cndmask_b32_e32 v49, v197, v49, vcc
	v_lshlrev_b32_e32 v49, 2, v49
	ds_bpermute_b32 v49, v49, v48
	v_cvt_pk_bf16_f32 v56, v60, v61
	v_cvt_pk_bf16_f32 v57, v62, v63
	global_store_dwordx2 v[52:53], v[56:57], off offset:288
	s_and_saveexec_b64 s[26:27], s[0:1]
	s_cbranch_execz .LBB0_2614
	s_waitcnt lgkmcnt(0)
	v_add_f32_e32 v52, v48, v49
	v_lshlrev_b64 v[48:49], 7, v[118:119]
	v_lshl_add_u64 v[48:49], s[24:25], 0, v[48:49]
	global_store_dword v[48:49], v52, off

; DEVI unsigned pk_bf16(float lo, float hi) { unsigned r; asm("v_cvt_pk_bf16_f32 %0, %1, %2" : "=v"(r) : "v"(lo), "v"(hi)); return r; }
;     DEVI void operator()(const f32x4 (&acc)[2][2][4][2], const Unit& u, int wr, int wc, int fr, int fq, const LAS float*) const {
;     ...
;         for (int idx = 0; idx < 8; ++idx) {
;             const int ai = idx >> 2, m = idx & 3;
;             const size_t ro = (size_t)(row0 + ai * HALF + m * 16) * ldc + col0;
;             if (idx + 1 < 8) { const int ai2 = (idx + 1) >> 2, m2 = (idx + 1) & 3; const size_t ro2 = (size_t)(row0 + ai2 * HALF + m2 * 16) * ldc + col0;
; #pragma unroll
;                 for (int bj = 0; bj < 2; ++bj)
; #pragma unroll
;                     for (int n = 0; n < 2; ++n) nxt[bj][n] = *(const f32x4*)(R + ro2 + bj * HALF + n * 16); }
;             float ss = 0.f;
; #pragma unroll
;             for (int bj = 0; bj < 2; ++bj)
; #pragma unroll
;                 for (int n = 0; n < 2; ++n) {
;                     const f32x4 hn = cur[bj][n] + acc[ai][bj][m][n] * scale;
;                     *(f32x4*)(C + ro + bj * HALF + n * 16) = hn;
;                     if (HB) { u32x2 w; w.x = pk_bf16(hn[0], hn[1]); w.y = pk_bf16(hn[2], hn[3]); *(u32x2*)(HB + ro + bj * HALF + n * 16) = w;
;                         ss += hn[0] * hn[0] + hn[1] * hn[1] + hn[2] * hn[2] + hn[3] * hn[3]; } }
;             if (HB) { ss += __shfl_xor(ss, 16); ss += __shfl_xor(ss, 32); if (fq == 0) RS[(size_t)(row0 + ai * HALF + m * 16) * 32 + u.pn * 4 + wc] = ss; }
; #pragma unroll
;             for (int bj = 0; bj < 2; ++bj)
; #pragma unroll
;                 for (int n = 0; n < 2; ++n) cur[bj][n] = nxt[bj][n];
.LBB0_2616:
	v_or_b32_e32 v86, 32, v118
	v_mad_i64_i32 v[88:89], s[26:27], v86, s58, 0
	s_waitcnt lgkmcnt(0)
	v_lshl_add_u64 v[48:49], v[88:89], 2, v[186:187]
	global_load_dwordx4 v[60:63], v[48:49], off nt
	global_load_dwordx4 v[56:59], v[48:49], off offset:64 nt
	global_load_dwordx4 v[52:55], v[48:49], off offset:512 nt
	s_nop 0
	global_load_dwordx4 v[48:51], v[48:49], off offset:576 nt
	v_lshl_add_u64 v[92:93], v[104:105], 0, v[182:183]
	v_mov_b32_e32 v181, v180
	v_lshl_add_u64 v[90:91], v[92:93], 2, s[80:81]
	s_waitcnt vmcnt(8)
	v_pk_fma_f32 v[84:85], v[46:47], v[180:181], v[78:79]
	v_pk_fma_f32 v[82:83], v[44:45], v[184:185], v[76:77]
	s_and_b64 vcc, exec, s[4:5]
	s_waitcnt vmcnt(7)
	v_pk_fma_f32 v[80:81], v[40:41], v[184:185], v[72:73]
	s_waitcnt vmcnt(6)
	v_pk_fma_f32 v[76:77], v[36:37], v[184:185], v[68:69]
	s_waitcnt vmcnt(5)
	v_pk_fma_f32 v[44:45], v[32:33], v[184:185], v[64:65]
	global_store_dwordx4 v[90:91], v[82:85], off nt
	s_cbranch_vccnz .LBB0_2635
	v_lshl_add_u64 v[36:37], v[92:93], 1, s[74:75]
	v_cvt_pk_bf16_f32 v32, v82, v83
	v_mul_f32_e32 v40, v83, v83
	v_cvt_pk_bf16_f32 v33, v84, v85
	global_store_dwordx2 v[36:37], v[32:33], off
	v_fmac_f32_e32 v40, v82, v82
	v_pk_fma_f32 v[82:83], v[42:43], v[180:181], v[74:75]
	v_cvt_pk_bf16_f32 v32, v80, v81
	global_store_dwordx4 v[90:91], v[80:83], off offset:64 nt
	v_cvt_pk_bf16_f32 v33, v82, v83
	global_store_dwordx2 v[36:37], v[32:33], off offset:32
	v_mul_f32_e32 v32, v81, v81
	v_fmac_f32_e32 v32, v80, v80
	v_mul_f32_e32 v33, v77, v77
	v_fmac_f32_e32 v40, v84, v84
	v_fmac_f32_e32 v32, v82, v82
	v_pk_fma_f32 v[78:79], v[38:39], v[180:181], v[70:71]
	v_fmac_f32_e32 v33, v76, v76
	v_fmac_f32_e32 v40, v85, v85
	v_fmac_f32_e32 v32, v83, v83
	v_fmac_f32_e32 v33, v78, v78
	v_add_f32_e32 v32, v40, v32
	v_fmac_f32_e32 v33, v79, v79
	v_add_f32_e32 v32, v32, v33
	v_mul_f32_e32 v33, v45, v45
	v_pk_fma_f32 v[46:47], v[34:35], v[180:181], v[66:67]
	v_fmac_f32_e32 v33, v44, v44
	v_fmac_f32_e32 v33, v46, v46
	v_fmac_f32_e32 v33, v47, v47
	v_add_f32_e32 v40, v32, v33
	v_and_b32_e32 v33, 64, v197
	v_xor_b32_e32 v32, 16, v197
	v_add_u32_e32 v41, 64, v33
	v_cmp_lt_i32_e32 vcc, v32, v41
	v_cvt_pk_bf16_f32 v33, v78, v79
	global_store_dwordx4 v[90:91], v[76:79], off offset:512 nt
	s_nop 0
	v_cndmask_b32_e32 v32, v197, v32, vcc
	v_lshlrev_b32_e32 v32, 2, v32
	ds_bpermute_b32 v64, v32, v40
	v_cvt_pk_bf16_f32 v32, v76, v77
	global_store_dwordx2 v[36:37], v[32:33], off offset:256
	v_xor_b32_e32 v33, 32, v197
	v_cmp_lt_i32_e32 vcc, v33, v41
	s_waitcnt lgkmcnt(0)
	v_add_f32_e32 v32, v40, v64
	global_store_dwordx4 v[90:91], v[44:47], off offset:576 nt
	v_cndmask_b32_e32 v33, v197, v33, vcc
	v_lshlrev_b32_e32 v33, 2, v33
	ds_bpermute_b32 v33, v33, v32
	v_cvt_pk_bf16_f32 v40, v44, v45
	v_cvt_pk_bf16_f32 v41, v46, v47
	global_store_dwordx2 v[36:37], v[40:41], off offset:288
	s_and_saveexec_b64 s[26:27], s[0:1]
	s_cbranch_execz .LBB0_2619
	v_ashrrev_i32_e32 v103, 31, v102
	s_waitcnt lgkmcnt(0)
	v_add_f32_e32 v36, v32, v33
	v_lshlrev_b64 v[32:33], 7, v[102:103]
	v_lshl_add_u64 v[32:33], s[24:25], 0, v[32:33]
	global_store_dword v[32:33], v36, off

; DEVI unsigned pk_bf16(float lo, float hi) { unsigned r; asm("v_cvt_pk_bf16_f32 %0, %1, %2" : "=v"(r) : "v"(lo), "v"(hi)); return r; }
;     DEVI void operator()(const f32x4 (&acc)[2][2][4][2], const Unit& u, int wr, int wc, int fr, int fq, const LAS float*) const {
;     ...
;         for (int idx = 0; idx < 8; ++idx) {
;             const int ai = idx >> 2, m = idx & 3;
;             const size_t ro = (size_t)(row0 + ai * HALF + m * 16) * ldc + col0;
;             if (idx + 1 < 8) { const int ai2 = (idx + 1) >> 2, m2 = (idx + 1) & 3; const size_t ro2 = (size_t)(row0 + ai2 * HALF + m2 * 16) * ldc + col0;
; #pragma unroll
;                 for (int bj = 0; bj < 2; ++bj)
; #pragma unroll
;                     for (int n = 0; n < 2; ++n) nxt[bj][n] = *(const f32x4*)(R + ro2 + bj * HALF + n * 16); }
;             float ss = 0.f;
; #pragma unroll
;             for (int bj = 0; bj < 2; ++bj)
; #pragma unroll
;                 for (int n = 0; n < 2; ++n) {
;                     const f32x4 hn = cur[bj][n] + acc[ai][bj][m][n] * scale;
;                     *(f32x4*)(C + ro + bj * HALF + n * 16) = hn;
;                     if (HB) { u32x2 w; w.x = pk_bf16(hn[0], hn[1]); w.y = pk_bf16(hn[2], hn[3]); *(u32x2*)(HB + ro + bj * HALF + n * 16) = w;
;                         ss += hn[0] * hn[0] + hn[1] * hn[1] + hn[2] * hn[2] + hn[3] * hn[3]; } }
;             if (HB) { ss += __shfl_xor(ss, 16); ss += __shfl_xor(ss, 32); if (fq == 0) RS[(size_t)(row0 + ai * HALF + m * 16) * 32 + u.pn * 4 + wc] = ss; }
; #pragma unroll
;             for (int bj = 0; bj < 2; ++bj)
; #pragma unroll
;                 for (int n = 0; n < 2; ++n) cur[bj][n] = nxt[bj][n];
.LBB0_2621:
	v_or_b32_e32 v70, 48, v118
	v_mad_i64_i32 v[72:73], s[26:27], v70, s58, 0
	s_waitcnt lgkmcnt(0)
	v_lshl_add_u64 v[32:33], v[72:73], 2, v[186:187]
	global_load_dwordx4 v[44:47], v[32:33], off nt
	global_load_dwordx4 v[40:43], v[32:33], off offset:64 nt
	global_load_dwordx4 v[36:39], v[32:33], off offset:512 nt
	s_nop 0
	global_load_dwordx4 v[32:35], v[32:33], off offset:576 nt
	v_lshl_add_u64 v[76:77], v[88:89], 0, v[182:183]
	v_mov_b32_e32 v181, v180
	v_lshl_add_u64 v[74:75], v[76:77], 2, s[80:81]
	s_waitcnt vmcnt(8)
	v_pk_fma_f32 v[68:69], v[30:31], v[180:181], v[62:63]
	v_pk_fma_f32 v[66:67], v[28:29], v[184:185], v[60:61]
	s_and_b64 vcc, exec, s[4:5]
	s_waitcnt vmcnt(7)
	v_pk_fma_f32 v[64:65], v[24:25], v[184:185], v[56:57]
	s_waitcnt vmcnt(6)
	v_pk_fma_f32 v[60:61], v[20:21], v[184:185], v[52:53]
	s_waitcnt vmcnt(5)
	v_pk_fma_f32 v[28:29], v[16:17], v[184:185], v[48:49]
	global_store_dwordx4 v[74:75], v[66:69], off nt
	s_cbranch_vccnz .LBB0_2636
	v_lshl_add_u64 v[20:21], v[76:77], 1, s[74:75]
	v_cvt_pk_bf16_f32 v16, v66, v67
	v_mul_f32_e32 v24, v67, v67
	v_cvt_pk_bf16_f32 v17, v68, v69
	global_store_dwordx2 v[20:21], v[16:17], off
	v_fmac_f32_e32 v24, v66, v66
	v_pk_fma_f32 v[66:67], v[26:27], v[180:181], v[58:59]
	v_cvt_pk_bf16_f32 v16, v64, v65
	global_store_dwordx4 v[74:75], v[64:67], off offset:64 nt
	v_cvt_pk_bf16_f32 v17, v66, v67
	global_store_dwordx2 v[20:21], v[16:17], off offset:32
	v_mul_f32_e32 v16, v65, v65
	v_fmac_f32_e32 v16, v64, v64
	v_mul_f32_e32 v17, v61, v61
	v_fmac_f32_e32 v24, v68, v68
	v_fmac_f32_e32 v16, v66, v66
	v_pk_fma_f32 v[62:63], v[22:23], v[180:181], v[54:55]
	v_fmac_f32_e32 v17, v60, v60
	v_fmac_f32_e32 v24, v69, v69
	v_fmac_f32_e32 v16, v67, v67
	v_fmac_f32_e32 v17, v62, v62
	v_add_f32_e32 v16, v24, v16
	v_fmac_f32_e32 v17, v63, v63
	v_add_f32_e32 v16, v16, v17
	v_mul_f32_e32 v17, v29, v29
	v_pk_fma_f32 v[30:31], v[18:19], v[180:181], v[50:51]
	v_fmac_f32_e32 v17, v28, v28
	v_fmac_f32_e32 v17, v30, v30
	v_fmac_f32_e32 v17, v31, v31
	v_add_f32_e32 v24, v16, v17
	v_and_b32_e32 v17, 64, v197
	v_xor_b32_e32 v16, 16, v197
	v_add_u32_e32 v25, 64, v17
	v_cmp_lt_i32_e32 vcc, v16, v25
	v_cvt_pk_bf16_f32 v17, v62, v63
	global_store_dwordx4 v[74:75], v[60:63], off offset:512 nt
	s_nop 0
	v_cndmask_b32_e32 v16, v197, v16, vcc
	v_lshlrev_b32_e32 v16, 2, v16
	ds_bpermute_b32 v48, v16, v24
	v_cvt_pk_bf16_f32 v16, v60, v61
	global_store_dwordx2 v[20:21], v[16:17], off offset:256
	v_xor_b32_e32 v17, 32, v197
	v_cmp_lt_i32_e32 vcc, v17, v25
	s_waitcnt lgkmcnt(0)
	v_add_f32_e32 v16, v24, v48
	global_store_dwordx4 v[74:75], v[28:31], off offset:576 nt
	v_cndmask_b32_e32 v17, v197, v17, vcc
	v_lshlrev_b32_e32 v17, 2, v17
	ds_bpermute_b32 v17, v17, v16
	v_cvt_pk_bf16_f32 v24, v28, v29
	v_cvt_pk_bf16_f32 v25, v30, v31
	global_store_dwordx2 v[20:21], v[24:25], off offset:288
	s_and_saveexec_b64 s[26:27], s[0:1]
	s_cbranch_execz .LBB0_2624
	v_ashrrev_i32_e32 v87, 31, v86
	s_waitcnt lgkmcnt(0)
	v_add_f32_e32 v20, v16, v17
	v_lshlrev_b64 v[16:17], 7, v[86:87]
	v_lshl_add_u64 v[16:17], s[24:25], 0, v[16:17]
	global_store_dword v[16:17], v20, off
